# v79 + HGRN pass-C backward-direction hg_out: the eight forward-output read-back loads hoisted above the MFMA blocks into unused VGPRs (no serialized round trips), counted waits
# baseline (speedup 1.0000x reference)
.LBB0_372:
	s_andn2_b64 vcc, exec, s[2:3]
	s_cbranch_vccnz .LBB0_339
	s_mul_i32 s3, s4, 9
	s_ashr_i32 s2, s3, 1
	s_add_i32 s3, s3, 9
	s_ashr_i32 s3, s3, 1
	v_ashrrev_i32_e32 v0, 6, v205
	s_sub_i32 s3, s3, s2
	v_cmp_gt_i32_e32 vcc, s3, v0
	s_and_saveexec_b64 s[38:39], vcc
	s_cbranch_execz .LBB0_338
	v_add_u32_e32 v0, s2, v0
	s_mov_b32 s2, 0x38e38e39
	v_mul_hi_i32 v2, v0, s2
	v_lshrrev_b32_e32 v3, 31, v2
	v_ashrrev_i32_e32 v2, 3, v2
	v_add_u32_e32 v2, v2, v3
	v_mul_lo_u32 v3, v2, 36
	v_sub_u32_e32 v96, v0, v3
	v_cmp_gt_i32_e64 s[40:41], 4, v96
	s_and_b64 s[2:3], s[18:19], s[40:41]
	v_mov_b32_e32 v1, v236
	s_xor_b64 s[2:3], s[2:3], -1
	s_and_b64 exec, exec, s[2:3]
	s_cbranch_execz .LBB0_338
	v_lshrrev_b32_e32 v0, 6, v1
	s_movk_i32 s2, 0x4d00
	v_mul_lo_u32 v0, v0, s2
	v_add_u32_e32 v92, 16, v0
	v_lshlrev_b32_e32 v0, 6, v2
	v_and_b32_e32 v94, 63, v1
	v_and_b32_e32 v0, 0xc0, v0
	v_or_b32_e32 v3, v94, v0
	v_readlane_b32 s0, v255, 20
	v_lshlrev_b32_e32 v160, 2, v3
	v_readlane_b32 s1, v255, 21
	s_nop 4
	global_load_dword v3, v160, s[0:1]
	global_load_dword v6, v160, s[0:1] offset:2048
	v_lshl_add_u64 v[4:5], s[0:1], 0, v[160:161]
	v_add_co_u32_e32 v4, vcc, 0x1000, v4
	s_mov_b32 s0, 0xf149f2ca
	s_nop 0
	v_addc_co_u32_e32 v5, vcc, 0, v5, vcc
	global_load_dword v8, v[4:5], off
	s_nop 0
	global_load_dword v4, v[4:5], off offset:2048
	v_lshlrev_b32_e32 v148, 1, v2
	v_ashrrev_i32_e32 v97, 31, v96
	v_mov_b32_e32 v99, v161
	v_mov_b32_e32 v101, v161
	v_readlane_b32 s44, v254, 28
	v_readlane_b32 s45, v254, 29
	v_mov_b32_e32 v16, v94
	s_waitcnt vmcnt(2)
	v_max3_f32 v7, v3, s0, v6
	v_readlane_b32 s0, v255, 1
	v_readlane_b32 s1, v255, 2
	s_waitcnt vmcnt(0)
	v_max3_f32 v5, v7, v8, v4
	v_sub_f32_e32 v6, v6, v5
	v_mul_f32_e32 v6, 0x3fb8aa3b, v6
	v_sub_f32_e32 v3, v3, v5
	v_exp_f32_e32 v6, v6
	v_sub_f32_e32 v7, v8, v5
	v_mul_f32_e32 v3, 0x3fb8aa3b, v3
	v_mul_f32_e32 v7, 0x3fb8aa3b, v7
	v_exp_f32_e32 v3, v3
	v_exp_f32_e32 v7, v7
	v_sub_f32_e32 v4, v4, v5
	v_mul_f32_e32 v4, 0x3fb8aa3b, v4
	v_exp_f32_e32 v4, v4
	v_add_f32_e32 v5, 0, v6
	v_cndmask_b32_e64 v5, v5, 0, s[0:1]
	v_readlane_b32 s0, v255, 3
	v_add_f32_e32 v8, v7, v5
	v_readlane_b32 s1, v255, 4
	v_add_f32_e32 v3, 0, v3
	v_add_f32_e32 v3, v6, v3
	v_cndmask_b32_e64 v5, v8, v5, s[0:1]
	v_readlane_b32 s0, v255, 5
	v_add_f32_e32 v8, v4, v5
	v_readlane_b32 s1, v255, 6
	v_add_f32_e32 v3, v7, v3
	v_add_f32_e32 v3, v4, v3
	v_cndmask_b32_e64 v5, v8, v5, s[0:1]
	v_div_scale_f32 v4, s[2:3], v3, v3, v5
	v_rcp_f32_e32 v6, v4
	v_readlane_b32 s0, v255, 22
	v_readlane_b32 s1, v255, 23
	v_fma_f32 v7, -v4, v6, 1.0
	v_fmac_f32_e32 v6, v7, v6
	v_div_scale_f32 v7, vcc, v5, v3, v5
	v_mul_f32_e32 v8, v7, v6
	v_fma_f32 v9, -v4, v8, v7
	v_fmac_f32_e32 v8, v9, v6
	v_fma_f32 v4, -v4, v8, v7
	v_div_fmas_f32 v4, v4, v6, v8
	v_div_fixup_f32 v149, v4, v3, v5
	v_ashrrev_i32_e32 v6, 2, v2
	v_mad_i64_i32 v[2:3], s[2:3], v148, 36, v[96:97]
	v_lshlrev_b64 v[2:3], 13, v[2:3]
	v_lshlrev_b32_e32 v4, 7, v1
	v_lshl_add_u64 v[2:3], s[0:1], 0, v[2:3]
	v_and_b32_e32 v98, 0xf80, v4
	v_lshrrev_b32_e32 v1, 2, v1
	v_lshl_add_u64 v[2:3], v[2:3], 0, v[98:99]
	v_and_b32_e32 v100, 8, v1
	v_lshl_add_u64 v[2:3], v[2:3], 0, v[100:101]
	global_load_dwordx2 v[42:43], v[2:3], off
	global_load_dwordx2 v[36:37], v[2:3], off offset:16
	global_load_dwordx2 v[34:35], v[2:3], off offset:32
	global_load_dwordx2 v[4:5], v[2:3], off offset:48
	s_movk_i32 s0, 0x1000
	v_mov_b32_e32 v1, 0xffffff00
	v_lshl_add_u32 v1, v6, 11, v1
	s_mov_b64 s[2:3], s[44:45]
	v_sub_f32_e32 v80, 1.0, v149
	s_waitcnt vmcnt(1)
	v_lshlrev_b32_e32 v40, 16, v35
	s_waitcnt vmcnt(0)
	v_lshlrev_b32_e32 v44, 16, v4
	v_and_b32_e32 v45, 0xffff0000, v4
	v_add_co_u32_e32 v4, vcc, s0, v2
	v_lshlrev_b32_e32 v46, 16, v5
	v_and_b32_e32 v47, 0xffff0000, v5
	v_addc_co_u32_e32 v5, vcc, 0, v3, vcc
	global_load_dwordx2 v[52:53], v[4:5], off
	global_load_dwordx2 v[50:51], v[4:5], off offset:16
	global_load_dwordx2 v[48:49], v[4:5], off offset:32
	global_load_dwordx2 v[38:39], v[4:5], off offset:48
	global_load_dwordx2 v[60:61], v[2:3], off offset:64
	global_load_dwordx2 v[58:59], v[2:3], off offset:80
	global_load_dwordx2 v[56:57], v[2:3], off offset:96
	global_load_dwordx2 v[54:55], v[2:3], off offset:112
	global_load_dwordx2 v[26:27], v[4:5], off offset:64
	global_load_dwordx2 v[28:29], v[4:5], off offset:80
	global_load_dwordx2 v[30:31], v[4:5], off offset:96
	global_load_dwordx2 v[32:33], v[4:5], off offset:112
	v_mov_b32_e32 v2, 0x4000
	v_lshl_add_u32 v2, v6, 8, v2
	v_cndmask_b32_e64 v1, v1, v2, s[40:41]
	v_lshl_add_u32 v93, v96, 6, v1
	v_and_b32_e32 v41, 0xffff0000, v35
	v_ashrrev_i32_e32 v89, 31, v93
	v_and_b32_e32 v35, 31, v16
	v_ashrrev_i32_e32 v81, 5, v16
	v_mov_b64_e32 v[2:3], s[2:3]
	s_movk_i32 s0, 0x1200
	v_mad_i64_i32 v[2:3], s[4:5], v93, s0, v[2:3]
	v_lshlrev_b32_e32 v90, 1, v0
	v_mov_b32_e32 v91, v161
	v_ashrrev_i32_e32 v17, 31, v16
	v_lshl_add_u64 v[0:1], v[2:3], 0, v[90:91]
	v_lshl_add_u64 v[18:19], v[16:17], 1, v[0:1]
	s_mov_b64 s[0:1], 0xb200000
	v_lshl_add_u64 v[0:1], v[18:19], 0, s[0:1]
	global_load_ushort v15, v[0:1], off offset:3072
	global_load_ushort v66, v[0:1], off offset:2048
	s_mov_b32 s7, 0xb202000
	v_add_co_u32_e32 v2, vcc, s7, v18
	s_mov_b32 s11, 0xb205000
	s_nop 0
	v_addc_co_u32_e32 v3, vcc, 0, v19, vcc
	v_add_co_u32_e32 v4, vcc, s11, v18
	s_mov_b32 s12, 0xb207000
	s_nop 0
	v_addc_co_u32_e32 v5, vcc, 0, v19, vcc
	v_add_co_u32_e32 v6, vcc, s12, v18
	s_mov_b32 s13, 0xb209000
	s_nop 0
	v_addc_co_u32_e32 v7, vcc, 0, v19, vcc
	v_add_co_u32_e32 v8, vcc, s13, v18
	s_mov_b32 s14, 0xb20b000
	s_nop 0
	v_addc_co_u32_e32 v9, vcc, 0, v19, vcc
	v_add_co_u32_e32 v10, vcc, s14, v18
	s_mov_b32 s15, 0xb20e000
	s_nop 0
	v_addc_co_u32_e32 v11, vcc, 0, v19, vcc
	v_add_co_u32_e32 v62, vcc, s15, v18
	s_mov_b32 s18, 0xb210000
	s_nop 0
	v_addc_co_u32_e32 v63, vcc, 0, v19, vcc
	v_add_co_u32_e32 v64, vcc, s18, v18
	s_mov_b32 s19, 0xb212000
	s_nop 0
	v_addc_co_u32_e32 v65, vcc, 0, v19, vcc
	v_add_co_u32_e32 v76, vcc, s19, v18
	s_mov_b32 s21, 0xb214000
	s_nop 0
	v_addc_co_u32_e32 v77, vcc, 0, v19, vcc
	v_add_co_u32_e32 v102, vcc, s21, v18
	s_mov_b32 s30, 0xb217000
	s_nop 0
	v_addc_co_u32_e32 v103, vcc, 0, v19, vcc
	global_load_ushort v88, v[4:5], off offset:1024
	global_load_ushort v95, v[4:5], off
	global_load_ushort v104, v[2:3], off offset:3072
	global_load_ushort v14, v[4:5], off offset:512
	global_load_ushort v13, v[2:3], off offset:3584
	global_load_ushort v12, v[0:1], off offset:2560
	v_add_co_u32_e32 v78, vcc, s30, v18
	s_mov_b32 s9, 0xc1f00000
	s_nop 0
	v_addc_co_u32_e32 v79, vcc, 0, v19, vcc
	s_mov_b32 s31, 0xb219000
	v_add_co_u32_e32 v82, vcc, s31, v18
	s_mov_b32 s34, 0xb21b000
	s_nop 0
	v_addc_co_u32_e32 v83, vcc, 0, v19, vcc
	v_add_co_u32_e32 v20, vcc, s34, v18
	s_mov_b32 s35, 0xb21d000
	s_nop 0
	v_addc_co_u32_e32 v21, vcc, 0, v19, vcc
	v_add_co_u32_e32 v68, vcc, s35, v18
	s_mov_b32 s36, 0xb220000
	s_nop 0
	v_addc_co_u32_e32 v69, vcc, 0, v19, vcc
	v_add_co_u32_e32 v22, vcc, s36, v18
	s_mov_b32 s37, 0xb222000
	s_nop 0
	v_addc_co_u32_e32 v23, vcc, 0, v19, vcc
	v_add_co_u32_e32 v24, vcc, s37, v18
	s_mov_b32 s40, 0xb201000
	s_nop 0
	v_addc_co_u32_e32 v25, vcc, 0, v19, vcc
	s_waitcnt vmcnt(7)
	v_lshlrev_b32_e32 v0, 16, v15
	v_max_f32_e32 v0, v0, v0
	v_med3_f32 v0, v0, s9, v244
	v_mul_f32_e32 v0, 0xbfb8aa3b, v0
	v_exp_f32_e32 v86, v0
	v_add_co_u32_e32 v0, vcc, s40, v18
	s_mov_b32 s41, 0xb203000
	v_add_f32_e32 v2, 1.0, v86
	v_rcp_f32_e32 v118, v2
	v_addc_co_u32_e32 v1, vcc, 0, v19, vcc
	s_waitcnt vmcnt(6)
	v_lshlrev_b32_e32 v4, 16, v66
	v_fma_f32 v5, v80, v118, v149
	v_max_f32_e32 v15, 0xda24260, v5
	v_add_co_u32_e32 v2, vcc, s41, v18
	v_mul_f32_e32 v4, v15, v4
	s_nop 0
	v_addc_co_u32_e32 v3, vcc, 0, v19, vcc
	v_bfe_u32 v5, v4, 16, 1
	s_movk_i32 s10, 0x7fff
	s_mov_b32 s46, 0xb204000
	v_add3_u32 v105, v4, v5, s10
	v_add_co_u32_e32 v4, vcc, s46, v18
	s_mov_b32 s28, 0xb206000
	s_nop 0
	v_addc_co_u32_e32 v5, vcc, 0, v19, vcc
	global_load_ushort v106, v[4:5], off offset:-4096
	global_load_ushort v107, v[4:5], off offset:512
	global_load_ushort v87, v[0:1], off offset:3584
	global_load_ushort v110, v[0:1], off offset:2560
	global_load_ushort v111, v[2:3], off offset:3584
	v_add_co_u32_e32 v2, vcc, s28, v18
	s_mov_b32 s29, 0xb208000
	s_nop 0
	v_addc_co_u32_e32 v3, vcc, 0, v19, vcc
	global_load_ushort v156, v[6:7], off offset:1536
	global_load_ushort v157, v[8:9], off offset:2560
	global_load_ushort v158, v[10:11], off offset:3584
	global_load_ushort v116, v[6:7], off offset:2048
	global_load_ushort v117, v[8:9], off offset:3072
	global_load_ushort v121, v[10:11], off offset:3072
	global_load_ushort v120, v[8:9], off offset:2048
	global_load_ushort v126, v[6:7], off offset:1024
	v_add_co_u32_e32 v6, vcc, s29, v18
	s_mov_b32 s42, 0xb20a000
	s_nop 0
	v_addc_co_u32_e32 v7, vcc, 0, v19, vcc
	v_add_co_u32_e32 v8, vcc, s42, v18
	s_mov_b32 s6, 0xb20c000
	s_nop 0
	v_addc_co_u32_e32 v9, vcc, 0, v19, vcc
	v_add_co_u32_e32 v10, vcc, s6, v18
	s_mov_b32 s49, 0xb20d000
	s_nop 0
	v_addc_co_u32_e32 v11, vcc, 0, v19, vcc
	v_add_co_u32_e32 v66, vcc, s49, v18
	s_mov_b32 s4, 0xb20f000
	s_nop 0
	v_addc_co_u32_e32 v67, vcc, 0, v19, vcc
	v_add_co_u32_e32 v74, vcc, s4, v18
	s_mov_b32 s4, 0xb211000
	s_nop 0
	v_addc_co_u32_e32 v75, vcc, 0, v19, vcc
	v_add_co_u32_e32 v84, vcc, s4, v18
	s_mov_b32 s4, 0xb223000
	s_nop 0
	v_addc_co_u32_e32 v85, vcc, 0, v19, vcc
	global_load_ushort v159, v[62:63], off offset:512
	global_load_ushort v162, v[64:65], off offset:1536
	global_load_ushort v163, v[76:77], off offset:2560
	global_load_ushort v164, v[102:103], off offset:3584
	global_load_ushort v127, v[62:63], off offset:1024
	global_load_ushort v137, v[64:65], off offset:2048
	global_load_ushort v141, v[64:65], off offset:1024
	global_load_ushort v131, v[62:63], off
	v_add_co_u32_e32 v62, vcc, s4, v18
	s_mov_b32 s4, 0xb221000
	s_nop 0
	v_addc_co_u32_e32 v63, vcc, 0, v19, vcc
	v_add_co_u32_e32 v64, vcc, s4, v18
	s_mov_b32 s4, 0xb21f000
	s_nop 0
	v_addc_co_u32_e32 v65, vcc, 0, v19, vcc
	v_add_co_u32_e32 v70, vcc, s4, v18
	s_mov_b32 s97, 0xb21c000
	s_nop 0
	v_addc_co_u32_e32 v71, vcc, 0, v19, vcc
	v_add_co_u32_e32 v72, vcc, s97, v18
	s_mov_b32 s4, 0xb21a000
	s_nop 0
	v_addc_co_u32_e32 v73, vcc, 0, v19, vcc
	v_add_co_u32_e32 v108, vcc, s4, v18
	s_mov_b32 s48, 0xb218000
	s_nop 0
	v_addc_co_u32_e32 v109, vcc, 0, v19, vcc
	v_add_co_u32_e32 v112, vcc, s48, v18
	s_mov_b32 s47, 0xb216000
	s_nop 0
	v_addc_co_u32_e32 v113, vcc, 0, v19, vcc
	v_add_co_u32_e32 v114, vcc, s47, v18
	s_mov_b32 s43, 0xb213000
	s_nop 0
	v_addc_co_u32_e32 v115, vcc, 0, v19, vcc
	v_add_co_u32_e32 v124, vcc, s43, v18
	global_load_ushort v165, v[78:79], off offset:512
	global_load_ushort v166, v[82:83], off offset:1536
	global_load_ushort v167, v[20:21], off offset:2560
	global_load_ushort v168, v[68:69], off offset:3584
	global_load_ushort v169, v[22:23], off offset:512
	global_load_ushort v170, v[24:25], off offset:1536
	global_load_ushort v171, v[22:23], off offset:-4096
	global_load_ushort v172, v[78:79], off offset:-4096
	v_addc_co_u32_e32 v125, vcc, 0, v19, vcc
	global_load_ushort v128, v[66:67], off offset:-4096
	global_load_ushort v129, v[66:67], off offset:512
	global_load_ushort v173, v[112:113], off offset:1024
	s_nop 0
	global_load_ushort v66, v[66:67], off
	s_nop 0
	global_load_ushort v67, v[4:5], off
	s_nop 0
	global_load_ushort v4, v[124:125], off offset:3072
	global_load_ushort v5, v[2:3], off offset:1536
	global_load_ushort v130, v[2:3], off offset:512
	global_load_ushort v136, v[6:7], off offset:1536
	global_load_ushort v174, v[2:3], off offset:1024
	global_load_ushort v175, v[0:1], off offset:3072
	s_waitcnt vmcnt(37)
	v_lshlrev_b32_e32 v0, 16, v87
	v_max_f32_e32 v0, v0, v0
	v_med3_f32 v0, v0, s9, v244
	v_mul_f32_e32 v0, 0xbfb8aa3b, v0
	v_exp_f32_e32 v87, v0
	global_load_ushort v0, v[74:75], off offset:1536
	global_load_ushort v1, v[84:85], off offset:2560
	global_load_ushort v2, v[84:85], off offset:1536
	global_load_ushort v3, v[62:63], off offset:2048
	global_load_ushort v176, v[64:65], off offset:1024
	global_load_ushort v177, v[72:73], off offset:3072
	global_load_ushort v178, v[108:109], off offset:2048
	global_load_ushort v179, v[84:85], off offset:2048
	global_load_ushort v138, v[6:7], off offset:2560
	global_load_ushort v139, v[8:9], off offset:3584
	global_load_ushort v140, v[8:9], off offset:2560
	s_nop 0
	global_load_ushort v10, v[10:11], off offset:3584
	s_nop 0
	global_load_ushort v11, v[74:75], off offset:512
	global_load_ushort v180, v[74:75], off offset:1024
	s_nop 0
	global_load_ushort v8, v[8:9], off offset:3072
	s_nop 0
	global_load_ushort v181, v[6:7], off offset:2048
	v_lshlrev_b32_e32 v7, 16, v106
	v_max_f32_e32 v7, v7, v7
	v_add_f32_e32 v84, 1.0, v87
	v_med3_f32 v7, v7, s9, v244
	v_rcp_f32_e32 v119, v84
	v_mul_f32_e32 v7, 0xbfb8aa3b, v7
	v_exp_f32_e32 v84, v7
	s_waitcnt vmcnt(52)
	v_lshlrev_b32_e32 v7, 16, v110
	v_fma_f32 v6, v80, v119, v149
	v_mul_f32_e32 v6, v15, v6
	v_add_f32_e32 v9, 1.0, v84
	v_max_f32_e32 v6, 0xda24260, v6
	v_rcp_f32_e32 v132, v9
	v_mul_f32_e32 v7, v6, v7
	v_bfe_u32 v9, v7, 16, 1
	v_lshl_add_u32 v17, v16, 1, v92
	v_add3_u32 v7, v7, v9, s10
	ds_write_b16_d16_hi v17, v7 offset:144
	v_fma_f32 v7, v80, v132, v149
	v_rcp_f32_e32 v123, v6
	v_mul_f32_e32 v6, v6, v7
	v_lshlrev_b32_e32 v7, 16, v107
	v_max_f32_e32 v7, v7, v7
	v_med3_f32 v7, v7, s9, v244
	v_mul_f32_e32 v7, 0xbfb8aa3b, v7
	v_exp_f32_e32 v85, v7
	v_max_f32_e32 v6, 0xda24260, v6
	v_lshlrev_b32_e32 v7, 16, v104
	v_mul_f32_e32 v7, v6, v7
	v_add_f32_e32 v9, 1.0, v85
	v_rcp_f32_e32 v133, v9
	v_bfe_u32 v9, v7, 16, 1
	v_add3_u32 v7, v7, v9, s10
	ds_write_b16_d16_hi v17, v7 offset:288
	v_fma_f32 v7, v80, v133, v149
	v_rcp_f32_e32 v134, v6
	v_mul_f32_e32 v6, v6, v7
	v_lshlrev_b32_e32 v7, 16, v88
	v_max_f32_e32 v7, v7, v7
	v_med3_f32 v7, v7, s9, v244
	v_mul_f32_e32 v7, 0xbfb8aa3b, v7
	v_exp_f32_e32 v74, v7
	v_max_f32_e32 v6, 0xda24260, v6
	s_waitcnt vmcnt(51)
	v_lshlrev_b32_e32 v7, 16, v111
	v_mul_f32_e32 v7, v6, v7
	v_add_f32_e32 v9, 1.0, v74
	v_rcp_f32_e32 v144, v9
	v_bfe_u32 v9, v7, 16, 1
	v_add3_u32 v7, v7, v9, s10
	ds_write_b16_d16_hi v17, v7 offset:432
	v_fma_f32 v7, v80, v144, v149
	v_rcp_f32_e32 v135, v6
	v_mul_f32_e32 v6, v6, v7
	v_max_f32_e32 v6, 0xda24260, v6
	v_rcp_f32_e32 v146, v6
	ds_write_b16_d16_hi v17, v105
	v_rcp_f32_e32 v122, v15
	v_pk_mul_f32 v[84:85], v[84:85], v[132:133]
	v_pk_mul_f32 v[86:87], v[86:87], v[118:119]
	v_pk_mul_f32 v[84:85], v[80:81], v[84:85] op_sel_hi:[0,1]
	v_pk_mul_f32 v[86:87], v[80:81], v[86:87] op_sel_hi:[0,1]
	s_movk_i32 s4, 0x50
	v_pk_mul_f32 v[84:85], v[84:85], v[134:135]
	v_pk_mul_f32 v[86:87], v[86:87], v[122:123]
	v_and_b32_sdwa v132, v85, v239 dst_sel:DWORD dst_unused:UNUSED_PAD src0_sel:WORD_1 src1_sel:DWORD
	s_waitcnt vmcnt(23)
	v_lshl_or_b32 v9, v66, 16, v158
	s_waitcnt vmcnt(22)
	v_lshl_or_b32 v13, v67, 16, v13
	v_mad_u64_u32 v[66:67], s[4:5], v16, s4, v[92:93]
	s_waitcnt vmcnt(20)
	v_lshlrev_b32_e32 v5, 16, v5
	v_max_f32_e32 v5, v5, v5
	v_med3_f32 v5, v5, s9, v244
	v_mul_f32_e32 v5, 0xbfb8aa3b, v5
	v_exp_f32_e32 v75, v5
	v_lshlrev_b32_e32 v5, 16, v95
	v_mul_f32_e32 v5, v6, v5
	s_waitcnt vmcnt(15)
	v_lshlrev_b32_e32 v0, 16, v0
	v_add_f32_e32 v7, 1.0, v75
	v_rcp_f32_e32 v145, v7
	v_bfe_u32 v7, v5, 16, 1
	v_add3_u32 v5, v5, v7, s10
	ds_write_b16_d16_hi v17, v5 offset:576
	v_fma_f32 v5, v80, v145, v149
	v_mul_f32_e32 v5, v6, v5
	v_lshlrev_b32_e32 v6, 16, v116
	v_max_f32_e32 v6, v6, v6
	v_med3_f32 v6, v6, s9, v244
	v_mul_f32_e32 v6, 0xbfb8aa3b, v6
	v_exp_f32_e32 v150, v6
	v_max_f32_e32 v5, 0xda24260, v5
	v_lshlrev_b32_e32 v6, 16, v130
	v_mul_f32_e32 v6, v5, v6
	v_add_f32_e32 v7, 1.0, v150
	v_rcp_f32_e32 v152, v7
	v_bfe_u32 v7, v6, 16, 1
	v_add3_u32 v6, v6, v7, s10
	ds_write_b16_d16_hi v17, v6 offset:720
	v_fma_f32 v6, v80, v152, v149
	v_rcp_f32_e32 v147, v5
	v_mul_f32_e32 v5, v5, v6
	s_waitcnt vmcnt(7)
	v_lshlrev_b32_e32 v6, 16, v138
	v_max_f32_e32 v6, v6, v6
	v_med3_f32 v6, v6, s9, v244
	v_mul_f32_e32 v6, 0xbfb8aa3b, v6
	v_exp_f32_e32 v151, v6
	v_max_f32_e32 v5, 0xda24260, v5
	v_lshlrev_b32_e32 v6, 16, v126
	v_mul_f32_e32 v6, v5, v6
	v_add_f32_e32 v7, 1.0, v151
	v_rcp_f32_e32 v153, v7
	v_bfe_u32 v7, v6, 16, 1
	v_add3_u32 v6, v6, v7, s10
	ds_write_b16_d16_hi v17, v6 offset:864
	v_fma_f32 v6, v80, v153, v149
	v_rcp_f32_e32 v154, v5
	v_mul_f32_e32 v5, v5, v6
	v_lshlrev_b32_e32 v6, 16, v117
	v_max_f32_e32 v6, v6, v6
	v_med3_f32 v6, v6, s9, v244
	v_mul_f32_e32 v6, 0xbfb8aa3b, v6
	v_exp_f32_e32 v104, v6
	v_max_f32_e32 v5, 0xda24260, v5
	v_lshlrev_b32_e32 v6, 16, v136
	v_mul_f32_e32 v6, v5, v6
	v_add_f32_e32 v7, 1.0, v104
	v_rcp_f32_e32 v106, v7
	v_bfe_u32 v7, v6, 16, 1
	v_add3_u32 v6, v6, v7, s10
	ds_write_b16_d16_hi v17, v6 offset:1008
	v_fma_f32 v6, v80, v106, v149
	v_rcp_f32_e32 v155, v5
	v_mul_f32_e32 v5, v5, v6
	s_waitcnt vmcnt(6)
	v_lshlrev_b32_e32 v6, 16, v139
	v_max_f32_e32 v6, v6, v6
	v_med3_f32 v6, v6, s9, v244
	v_mul_f32_e32 v6, 0xbfb8aa3b, v6
	v_exp_f32_e32 v105, v6
	v_max_f32_e32 v5, 0xda24260, v5
	v_lshlrev_b32_e32 v6, 16, v120
	v_mul_f32_e32 v6, v5, v6
	v_add_f32_e32 v7, 1.0, v105
	v_rcp_f32_e32 v107, v7
	v_bfe_u32 v7, v6, 16, 1
	v_add3_u32 v88, v6, v7, s10
	v_rcp_f32_e32 v110, v5
	v_fma_f32 v6, v80, v107, v149
	v_mul_f32_e32 v5, v5, v6
	v_lshlrev_b32_e32 v6, 16, v128
	v_max_f32_e32 v6, v6, v6
	v_med3_f32 v6, v6, s9, v244
	v_mul_f32_e32 v6, 0xbfb8aa3b, v6
	v_exp_f32_e32 v116, v6
	v_max_f32_e32 v5, 0xda24260, v5
	s_waitcnt vmcnt(5)
	v_lshlrev_b32_e32 v6, 16, v140
	v_mul_f32_e32 v6, v5, v6
	v_add_f32_e32 v7, 1.0, v116
	v_rcp_f32_e32 v120, v7
	v_bfe_u32 v7, v6, 16, 1
	v_add3_u32 v95, v6, v7, s10
	v_rcp_f32_e32 v111, v5
	v_fma_f32 v6, v80, v120, v149
	v_mul_f32_e32 v5, v5, v6
	v_lshlrev_b32_e32 v6, 16, v129
	v_max_f32_e32 v6, v6, v6
	v_med3_f32 v6, v6, s9, v244
	v_mul_f32_e32 v6, 0xbfb8aa3b, v6
	v_exp_f32_e32 v117, v6
	v_lshlrev_b32_e32 v6, 16, v121
	v_max_f32_e32 v5, 0xda24260, v5
	v_mul_f32_e32 v6, v5, v6
	v_add_f32_e32 v7, 1.0, v117
	v_rcp_f32_e32 v121, v7
	v_bfe_u32 v7, v6, 16, 1
	v_add3_u32 v182, v6, v7, s10
	v_rcp_f32_e32 v126, v5
	v_fma_f32 v6, v80, v121, v149
	v_mul_f32_e32 v5, v5, v6
	v_lshlrev_b32_e32 v6, 16, v127
	v_max_f32_e32 v6, v6, v6
	v_med3_f32 v6, v6, s9, v244
	v_mul_f32_e32 v6, 0xbfb8aa3b, v6
	v_exp_f32_e32 v128, v6
	v_max_f32_e32 v0, v0, v0
	v_med3_f32 v0, v0, s9, v244
	v_mul_f32_e32 v0, 0xbfb8aa3b, v0
	v_add_f32_e32 v7, 1.0, v128
	v_rcp_f32_e32 v130, v7
	v_max_f32_e32 v5, 0xda24260, v5
	s_waitcnt vmcnt(4)
	v_lshlrev_b32_e32 v6, 16, v10
	v_exp_f32_e32 v129, v0
	v_mul_f32_e32 v6, v5, v6
	v_bfe_u32 v7, v6, 16, 1
	v_add3_u32 v183, v6, v7, s10
	v_fma_f32 v6, v80, v130, v149
	v_rcp_f32_e32 v127, v5
	v_mul_f32_e32 v5, v5, v6
	v_add_f32_e32 v6, 1.0, v129
	v_max_f32_e32 v0, 0xda24260, v5
	v_lshlrev_b32_e32 v5, 16, v131
	v_rcp_f32_e32 v131, v6
	v_mul_f32_e32 v5, v0, v5
	v_bfe_u32 v6, v5, 16, 1
	v_add3_u32 v184, v5, v6, s10
	v_fma_f32 v5, v80, v131, v149
	v_rcp_f32_e32 v136, v0
	v_mul_f32_e32 v0, v0, v5
	v_lshlrev_b32_e32 v5, 16, v137
	v_max_f32_e32 v5, v5, v5
	v_med3_f32 v5, v5, s9, v244
	v_mul_f32_e32 v5, 0xbfb8aa3b, v5
	v_exp_f32_e32 v138, v5
	v_lshlrev_b32_e32 v1, 16, v1
	v_max_f32_e32 v1, v1, v1
	v_med3_f32 v1, v1, s9, v244
	v_add_f32_e32 v6, 1.0, v138
	v_rcp_f32_e32 v140, v6
	v_mul_f32_e32 v1, 0xbfb8aa3b, v1
	v_max_f32_e32 v0, 0xda24260, v0
	s_waitcnt vmcnt(3)
	v_lshlrev_b32_e32 v5, 16, v11
	v_exp_f32_e32 v139, v1
	v_mul_f32_e32 v5, v0, v5
	v_bfe_u32 v6, v5, 16, 1
	v_add3_u32 v185, v5, v6, s10
	v_fma_f32 v5, v80, v140, v149
	v_rcp_f32_e32 v137, v0
	v_mul_f32_e32 v0, v0, v5
	v_add_f32_e32 v5, 1.0, v139
	v_lshlrev_b32_e32 v1, 16, v141
	v_rcp_f32_e32 v141, v5
	v_max_f32_e32 v0, 0xda24260, v0
	v_mul_f32_e32 v1, v0, v1
	v_bfe_u32 v5, v1, 16, 1
	v_add3_u32 v186, v1, v5, s10
	v_fma_f32 v1, v80, v141, v149
	v_pk_mul_f32 v[150:151], v[150:151], v[152:153]
	v_pk_mul_f32 v[74:75], v[74:75], v[144:145]
	v_rcp_f32_e32 v142, v0
	v_mul_f32_e32 v0, v0, v1
	v_pk_mul_f32 v[150:151], v[80:81], v[150:151] op_sel_hi:[0,1]
	v_pk_mul_f32 v[74:75], v[80:81], v[74:75] op_sel_hi:[0,1]
	v_max_f32_e32 v187, 0xda24260, v0
	v_lshlrev_b32_e32 v0, 16, v2
	v_pk_mul_f32 v[150:151], v[150:151], v[154:155]
	v_pk_mul_f32 v[74:75], v[74:75], v[146:147]
	v_mul_f32_e32 v0, v187, v0
	v_and_b32_sdwa v152, v150, v239 dst_sel:DWORD dst_unused:UNUSED_PAD src0_sel:WORD_1 src1_sel:DWORD
	v_and_b32_sdwa v144, v75, v239 dst_sel:DWORD dst_unused:UNUSED_PAD src0_sel:WORD_1 src1_sel:DWORD
	v_and_b32_sdwa v145, v74, v239 dst_sel:DWORD dst_unused:UNUSED_PAD src0_sel:WORD_1 src1_sel:DWORD
	v_and_b32_sdwa v133, v84, v239 dst_sel:DWORD dst_unused:UNUSED_PAD src0_sel:WORD_1 src1_sel:DWORD
	v_and_b32_sdwa v118, v87, v239 dst_sel:DWORD dst_unused:UNUSED_PAD src0_sel:WORD_1 src1_sel:DWORD
	v_and_b32_sdwa v119, v86, v239 dst_sel:DWORD dst_unused:UNUSED_PAD src0_sel:WORD_1 src1_sel:DWORD
	v_bfe_u32 v1, v0, 16, 1
	v_and_b32_sdwa v67, v151, v239 dst_sel:DWORD dst_unused:UNUSED_PAD src0_sel:WORD_1 src1_sel:DWORD
	v_add3_u32 v150, v150, v152, s10
	v_add3_u32 v75, v75, v144, s10
	v_add3_u32 v74, v74, v145, s10
	v_add3_u32 v85, v85, v132, s10
	v_add3_u32 v84, v84, v133, s10
	v_add3_u32 v87, v87, v118, s10
	v_add3_u32 v86, v86, v119, s10
	v_rcp_f32_e32 v143, v187
	v_add3_u32 v188, v0, v1, s10
	v_lshl_or_b32 v3, v3, 16, v170
	v_lshl_or_b32 v2, v176, 16, v169
	v_lshl_or_b32 v1, v171, 16, v168
	v_lshl_or_b32 v0, v177, 16, v167
	v_lshl_or_b32 v7, v178, 16, v166
	v_lshl_or_b32 v6, v173, 16, v165
	v_lshl_or_b32 v5, v172, 16, v164
	v_lshl_or_b32 v4, v4, 16, v163
	v_lshl_or_b32 v11, v179, 16, v162
	s_waitcnt vmcnt(2)
	v_lshl_or_b32 v10, v180, 16, v159
	s_waitcnt vmcnt(1)
	v_lshl_or_b32 v8, v8, 16, v157
	s_waitcnt vmcnt(0)
	v_lshl_or_b32 v15, v181, 16, v156
	v_lshl_or_b32 v14, v174, 16, v14
	v_lshl_or_b32 v12, v175, 16, v12
	s_movk_i32 s16, 0x50
	v_add3_u32 v67, v151, v67, s10
	ds_write_b16_d16_hi v17, v150 offset:5472
	ds_write_b16_d16_hi v17, v67 offset:5616
	ds_write_b16_d16_hi v17, v74 offset:5184
	ds_write_b16_d16_hi v17, v75 offset:5328
	v_and_b32_e32 v75, 0xffff0000, v75
	v_and_b32_e32 v74, 0xffff0000, v74
	ds_write_b16_d16_hi v17, v84 offset:4896
	ds_write_b16_d16_hi v17, v85 offset:5040
	v_and_b32_e32 v85, 0xffff0000, v85
	v_and_b32_e32 v84, 0xffff0000, v84
	ds_write_b16_d16_hi v17, v86 offset:4608
	ds_write_b16_d16_hi v17, v87 offset:4752
	v_and_b32_e32 v87, 0xffff0000, v87
	v_and_b32_e32 v86, 0xffff0000, v86
	global_load_ushort v118, v[76:77], off offset:3072
	s_nop 0
	global_load_ushort v102, v[102:103], off offset:3072
	s_nop 0
	global_load_ushort v103, v[78:79], off offset:1024
	global_load_ushort v119, v[82:83], off offset:1024
	global_load_ushort v123, v[82:83], off offset:2048
	s_nop 0
	global_load_ushort v78, v[78:79], off
	s_nop 0
	global_load_ushort v79, v[76:77], off offset:2048
	global_load_ushort v82, v[124:125], off offset:3584
	s_mov_b32 s5, 0xb215000
	v_add_co_u32_e32 v76, vcc, s5, v18
	v_pk_mul_f32 v[138:139], v[138:139], v[140:141]
	s_nop 0
	v_addc_co_u32_e32 v77, vcc, 0, v19, vcc
	global_load_ushort v83, v[76:77], off
	s_nop 0
	global_load_ushort v76, v[76:77], off offset:3584
	s_nop 0
	global_load_ushort v77, v[124:125], off offset:2560
	s_nop 0
	global_load_ushort v114, v[114:115], off offset:512
	s_nop 0
	global_load_ushort v115, v[112:113], off offset:1536
	global_load_ushort v144, v[108:109], off offset:1536
	ds_write_b16_d16_hi v17, v88 offset:1152
	ds_write_b16_d16_hi v17, v95 offset:1296
	ds_write_b16_d16_hi v17, v182 offset:1440
	ds_write_b16_d16_hi v17, v183 offset:1584
	ds_write_b16_d16_hi v17, v184 offset:1728
	ds_write_b16_d16_hi v17, v185 offset:1872
	ds_write_b16_d16_hi v17, v186 offset:2016
	ds_write_b16_d16_hi v17, v188 offset:2160
	global_load_ushort v88, v[112:113], off offset:512
	global_load_ushort v95, v[108:109], off offset:2560
	v_pk_mul_f32 v[128:129], v[128:129], v[130:131]
	v_pk_mul_f32 v[116:117], v[116:117], v[120:121]
	v_pk_mul_f32 v[104:105], v[104:105], v[106:107]
	v_pk_mul_f32 v[138:139], v[80:81], v[138:139] op_sel_hi:[0,1]
	v_pk_mul_f32 v[128:129], v[80:81], v[128:129] op_sel_hi:[0,1]
	v_pk_mul_f32 v[116:117], v[80:81], v[116:117] op_sel_hi:[0,1]
	v_pk_mul_f32 v[104:105], v[80:81], v[104:105] op_sel_hi:[0,1]
	v_pk_mul_f32 v[138:139], v[138:139], v[142:143]
	v_pk_mul_f32 v[128:129], v[128:129], v[136:137]
	v_pk_mul_f32 v[116:117], v[116:117], v[126:127]
	v_pk_mul_f32 v[104:105], v[104:105], v[110:111]
	v_and_b32_sdwa v140, v138, v239 dst_sel:DWORD dst_unused:UNUSED_PAD src0_sel:WORD_1 src1_sel:DWORD
	v_and_b32_sdwa v130, v129, v239 dst_sel:DWORD dst_unused:UNUSED_PAD src0_sel:WORD_1 src1_sel:DWORD
	v_and_b32_sdwa v131, v128, v239 dst_sel:DWORD dst_unused:UNUSED_PAD src0_sel:WORD_1 src1_sel:DWORD
	v_and_b32_sdwa v120, v117, v239 dst_sel:DWORD dst_unused:UNUSED_PAD src0_sel:WORD_1 src1_sel:DWORD
	v_and_b32_sdwa v121, v116, v239 dst_sel:DWORD dst_unused:UNUSED_PAD src0_sel:WORD_1 src1_sel:DWORD
	v_and_b32_sdwa v106, v105, v239 dst_sel:DWORD dst_unused:UNUSED_PAD src0_sel:WORD_1 src1_sel:DWORD
	v_and_b32_sdwa v107, v104, v239 dst_sel:DWORD dst_unused:UNUSED_PAD src0_sel:WORD_1 src1_sel:DWORD
	v_add3_u32 v142, v138, v140, s10
	v_add3_u32 v129, v129, v130, s10
	v_add3_u32 v128, v128, v131, s10
	v_add3_u32 v117, v117, v120, s10
	v_add3_u32 v116, v116, v121, s10
	v_add3_u32 v105, v105, v106, s10
	v_add3_u32 v104, v104, v107, s10
	s_waitcnt vmcnt(15)
	v_lshlrev_b32_e32 v108, 16, v118
	s_waitcnt vmcnt(14)
	v_lshlrev_b32_e32 v113, 16, v102
	s_waitcnt vmcnt(10)
	v_lshlrev_b32_e32 v118, 16, v78
	v_max_f32_e32 v78, v108, v108
	s_waitcnt vmcnt(9)
	v_lshlrev_b32_e32 v112, 16, v79
	s_waitcnt vmcnt(8)
	v_lshlrev_b32_e32 v79, 16, v82
	v_med3_f32 v78, v78, s9, v244
	v_lshlrev_b32_e32 v82, 16, v103
	v_max_f32_e32 v79, v79, v79
	v_mul_f32_e32 v78, 0xbfb8aa3b, v78
	s_waitcnt vmcnt(5)
	v_lshlrev_b32_e32 v122, 16, v77
	v_lshlrev_b32_e32 v77, 16, v83
	v_lshlrev_b32_e32 v124, 16, v76
	v_max_f32_e32 v76, v82, v82
	s_waitcnt vmcnt(3)
	v_lshlrev_b32_e32 v82, 16, v115
	v_med3_f32 v79, v79, s9, v244
	v_exp_f32_e32 v102, v78
	v_max_f32_e32 v77, v77, v77
	v_max_f32_e32 v82, v82, v82
	v_mul_f32_e32 v79, 0xbfb8aa3b, v79
	v_lshlrev_b32_e32 v83, 16, v114
	v_med3_f32 v76, v76, s9, v244
	v_med3_f32 v77, v77, s9, v244
	v_med3_f32 v82, v82, s9, v244
	v_exp_f32_e32 v103, v79
	v_max_f32_e32 v83, v83, v83
	v_mul_f32_e32 v76, 0xbfb8aa3b, v76
	v_mul_f32_e32 v77, 0xbfb8aa3b, v77
	v_mul_f32_e32 v82, 0xbfb8aa3b, v82
	v_med3_f32 v83, v83, s9, v244
	v_exp_f32_e32 v76, v76
	v_exp_f32_e32 v78, v77
	v_exp_f32_e32 v77, v82
	v_add_f32_e32 v82, 1.0, v102
	v_mul_f32_e32 v79, 0xbfb8aa3b, v83
	v_rcp_f32_e32 v114, v82
	v_exp_f32_e32 v79, v79
	v_add_f32_e32 v83, 1.0, v103
	v_rcp_f32_e32 v115, v83
	v_add_f32_e32 v108, 1.0, v76
	v_add_f32_e32 v83, 1.0, v78
	v_rcp_f32_e32 v82, v108
	v_rcp_f32_e32 v108, v83
	v_fma_f32 v83, v80, v114, v149
	v_add_f32_e32 v109, 1.0, v79
	v_mul_f32_e32 v83, v187, v83
	v_rcp_f32_e32 v109, v109
	v_fma_f32 v125, v80, v115, v149
	v_max_f32_e32 v83, 0xda24260, v83
	v_rcp_f32_e32 v134, v83
	v_mul_f32_e32 v112, v83, v112
	v_mul_f32_e32 v83, v83, v125
	v_fma_f32 v132, v80, v108, v149
	v_bfe_u32 v125, v112, 16, 1
	v_max_f32_e32 v83, 0xda24260, v83
	v_add3_u32 v146, v112, v125, s10
	v_rcp_f32_e32 v135, v83
	v_mul_f32_e32 v112, v83, v122
	v_mul_f32_e32 v83, v83, v132
	v_fma_f32 v133, v80, v109, v149
	v_bfe_u32 v122, v112, 16, 1
	v_max_f32_e32 v83, 0xda24260, v83
	v_add3_u32 v147, v112, v122, s10
	v_rcp_f32_e32 v132, v83
	v_mul_f32_e32 v112, v83, v113
	v_mul_f32_e32 v83, v83, v133
	v_fma_f32 v145, v80, v82, v149
	v_bfe_u32 v113, v112, 16, 1
	v_max_f32_e32 v83, 0xda24260, v83
	v_add3_u32 v151, v112, v113, s10
	v_rcp_f32_e32 v133, v83
	v_mul_f32_e32 v112, v83, v124
	v_mul_f32_e32 v83, v83, v145
	v_max_f32_e32 v124, 0xda24260, v83
	v_add_f32_e32 v83, 1.0, v77
	v_rcp_f32_e32 v83, v83
	v_bfe_u32 v113, v112, 16, 1
	v_add3_u32 v152, v112, v113, s10
	v_mul_f32_e32 v112, v124, v118
	v_bfe_u32 v113, v112, 16, 1
	v_add3_u32 v153, v112, v113, s10
	v_fma_f32 v112, v80, v83, v149
	v_mul_f32_e32 v113, v124, v112
	v_lshlrev_b32_e32 v112, 16, v123
	v_max_f32_e32 v112, v112, v112
	v_med3_f32 v112, v112, s9, v244
	v_mul_f32_e32 v112, 0xbfb8aa3b, v112
	v_exp_f32_e32 v112, v112
	v_max_f32_e32 v113, 0xda24260, v113
	s_waitcnt vmcnt(1)
	v_lshlrev_b32_e32 v88, 16, v88
	s_waitcnt vmcnt(0)
	v_lshlrev_b32_e32 v95, 16, v95
	v_add_f32_e32 v118, 1.0, v112
	v_rcp_f32_e32 v118, v118
	v_mul_f32_e32 v88, v113, v88
	v_max_f32_e32 v95, v95, v95
	v_rcp_f32_e32 v122, v124
	v_bfe_u32 v124, v88, 16, 1
	v_med3_f32 v95, v95, s9, v244
	v_add3_u32 v88, v88, v124, s10
	v_fma_f32 v124, v80, v118, v149
	v_mul_f32_e32 v95, 0xbfb8aa3b, v95
	v_rcp_f32_e32 v123, v113
	v_mul_f32_e32 v124, v113, v124
	v_exp_f32_e32 v113, v95
	v_lshlrev_b32_e32 v125, 16, v119
	v_max_f32_e32 v95, 0xda24260, v124
	v_mul_f32_e32 v125, v95, v125
	v_add_f32_e32 v119, 1.0, v113
	v_rcp_f32_e32 v119, v119
	v_bfe_u32 v145, v125, 16, 1
	v_add3_u32 v154, v125, v145, s10
	v_rcp_f32_e32 v124, v95
	v_fma_f32 v125, v80, v119, v149
	v_mul_f32_e32 v95, v95, v125
	v_max_f32_e32 v95, 0xda24260, v95
	v_lshlrev_b32_e32 v144, 16, v144
	v_mul_f32_e32 v144, v95, v144
	v_bfe_u32 v145, v144, 16, 1
	v_add3_u32 v155, v144, v145, s10
	v_and_b32_e32 v145, 0xffff0000, v67
	v_and_b32_sdwa v67, v139, v239 dst_sel:DWORD dst_unused:UNUSED_PAD src0_sel:WORD_1 src1_sel:DWORD
	v_rcp_f32_e32 v125, v95
	v_and_b32_e32 v144, 0xffff0000, v150
	v_add3_u32 v67, v139, v67, s10
	ds_write_b16_d16_hi v17, v142 offset:6624
	ds_write_b16_d16_hi v17, v67 offset:6768
	ds_write_b16_d16_hi v17, v128 offset:6336
	ds_write_b16_d16_hi v17, v129 offset:6480
	v_and_b32_e32 v129, 0xffff0000, v129
	v_and_b32_e32 v128, 0xffff0000, v128
	ds_write_b16_d16_hi v17, v116 offset:6048
	ds_write_b16_d16_hi v17, v117 offset:6192
	v_and_b32_e32 v117, 0xffff0000, v117
	v_and_b32_e32 v116, 0xffff0000, v116
	ds_write_b16_d16_hi v17, v104 offset:5760
	ds_write_b16_d16_hi v17, v105 offset:5904
	v_and_b32_e32 v105, 0xffff0000, v105
	v_and_b32_e32 v104, 0xffff0000, v104
	global_load_ushort v106, v[20:21], off offset:3072
	s_nop 0
	global_load_ushort v68, v[68:69], off offset:3072
	s_nop 0
	global_load_ushort v69, v[22:23], off offset:1024
	global_load_ushort v139, v[24:25], off offset:1024
	global_load_ushort v131, v[24:25], off offset:2048
	s_nop 0
	global_load_ushort v22, v[22:23], off
	s_nop 0
	global_load_ushort v20, v[20:21], off offset:2048
	s_nop 0
	global_load_ushort v21, v[72:73], off offset:3584
	s_mov_b32 s4, 0xb21e000
	v_add_co_u32_e32 v18, vcc, s4, v18
	s_waitcnt vmcnt(6)
	v_lshlrev_b32_e32 v68, 16, v68
	v_addc_co_u32_e32 v19, vcc, 0, v19, vcc
	global_load_ushort v23, v[18:19], off
	s_nop 0
	global_load_ushort v18, v[18:19], off offset:3584
	s_nop 0
	global_load_ushort v19, v[72:73], off offset:2560
	global_load_ushort v24, v[70:71], off offset:512
	global_load_ushort v25, v[64:65], off offset:1536
	s_nop 0
	global_load_ushort v70, v[62:63], off offset:1536
	ds_write_b16_d16_hi v17, v146 offset:2304
	ds_write_b16_d16_hi v17, v147 offset:2448
	ds_write_b16_d16_hi v17, v151 offset:2592
	ds_write_b16_d16_hi v17, v152 offset:2736
	ds_write_b16_d16_hi v17, v153 offset:2880
	ds_write_b16_d16_hi v17, v88 offset:3024
	ds_write_b16_d16_hi v17, v154 offset:3168
	ds_write_b16_d16_hi v17, v155 offset:3312
	global_load_ushort v64, v[64:65], off offset:512
	s_nop 0
	global_load_ushort v62, v[62:63], off offset:2560
	v_lshlrev_b32_e32 v63, 16, v106
	s_waitcnt vmcnt(9)
	v_lshlrev_b32_e32 v65, 16, v20
	s_waitcnt vmcnt(8)
	v_lshlrev_b32_e32 v20, 16, v21
	v_lshlrev_b32_e32 v21, 16, v69
	v_lshlrev_b32_e32 v69, 16, v22
	v_max_f32_e32 v22, v63, v63
	v_med3_f32 v22, v22, s9, v244
	v_max_f32_e32 v20, v20, v20
	v_mul_f32_e32 v22, 0xbfb8aa3b, v22
	v_med3_f32 v20, v20, s9, v244
	v_mul_f32_e32 v20, 0xbfb8aa3b, v20
	s_waitcnt vmcnt(6)
	v_lshlrev_b32_e32 v71, 16, v18
	s_waitcnt vmcnt(5)
	v_lshlrev_b32_e32 v63, 16, v19
	v_lshlrev_b32_e32 v19, 16, v23
	s_waitcnt vmcnt(4)
	v_lshlrev_b32_e32 v23, 16, v24
	v_exp_f32_e32 v24, v22
	v_max_f32_e32 v18, v21, v21
	s_waitcnt vmcnt(3)
	v_lshlrev_b32_e32 v21, 16, v25
	v_max_f32_e32 v19, v19, v19
	v_max_f32_e32 v23, v23, v23
	v_max_f32_e32 v21, v21, v21
	v_med3_f32 v19, v19, s9, v244
	v_med3_f32 v23, v23, s9, v244
	v_exp_f32_e32 v25, v20
	v_med3_f32 v21, v21, s9, v244
	v_mul_f32_e32 v19, 0xbfb8aa3b, v19
	v_mul_f32_e32 v22, 0xbfb8aa3b, v23
	v_med3_f32 v18, v18, s9, v244
	v_mul_f32_e32 v23, 0xbfb8aa3b, v21
	v_exp_f32_e32 v20, v19
	v_exp_f32_e32 v21, v22
	v_add_f32_e32 v22, 1.0, v24
	v_mul_f32_e32 v18, 0xbfb8aa3b, v18
	v_rcp_f32_e32 v106, v22
	v_exp_f32_e32 v18, v18
	v_exp_f32_e32 v19, v23
	v_add_f32_e32 v23, 1.0, v25
	v_rcp_f32_e32 v107, v23
	v_add_f32_e32 v23, 1.0, v20
	v_rcp_f32_e32 v110, v23
	v_fma_f32 v23, v80, v106, v149
	v_add_f32_e32 v72, 1.0, v18
	v_add_f32_e32 v73, 1.0, v21
	v_mul_f32_e32 v23, v95, v23
	v_rcp_f32_e32 v22, v72
	v_rcp_f32_e32 v111, v73
	v_fma_f32 v72, v80, v107, v149
	v_max_f32_e32 v23, 0xda24260, v23
	v_rcp_f32_e32 v120, v23
	v_mul_f32_e32 v65, v23, v65
	v_mul_f32_e32 v23, v23, v72
	v_fma_f32 v88, v80, v110, v149
	v_max_f32_e32 v23, 0xda24260, v23
	v_bfe_u32 v72, v65, 16, 1
	v_rcp_f32_e32 v121, v23
	v_mul_f32_e32 v63, v23, v63
	v_mul_f32_e32 v23, v23, v88
	v_fma_f32 v95, v80, v111, v149
	v_add3_u32 v143, v65, v72, s10
	v_bfe_u32 v65, v63, 16, 1
	v_max_f32_e32 v23, 0xda24260, v23
	v_add3_u32 v146, v63, v65, s10
	v_rcp_f32_e32 v126, v23
	v_mul_f32_e32 v63, v23, v68
	v_mul_f32_e32 v23, v23, v95
	v_fma_f32 v73, v80, v22, v149
	v_bfe_u32 v65, v63, 16, 1
	v_max_f32_e32 v23, 0xda24260, v23
	v_add3_u32 v95, v63, v65, s10
	v_rcp_f32_e32 v127, v23
	v_mul_f32_e32 v63, v23, v71
	v_mul_f32_e32 v23, v23, v73
	v_bfe_u32 v65, v63, 16, 1
	v_max_f32_e32 v68, 0xda24260, v23
	v_add3_u32 v147, v63, v65, s10
	v_mul_f32_e32 v63, v68, v69
	v_bfe_u32 v65, v63, 16, 1
	v_add3_u32 v150, v63, v65, s10
	v_lshlrev_b32_e32 v65, 16, v131
	v_max_f32_e32 v65, v65, v65
	v_med3_f32 v65, v65, s9, v244
	v_add_f32_e32 v23, 1.0, v19
	v_mul_f32_e32 v65, 0xbfb8aa3b, v65
	v_rcp_f32_e32 v23, v23
	v_exp_f32_e32 v136, v65
	s_waitcnt vmcnt(0)
	v_lshlrev_b32_e32 v62, 16, v62
	v_max_f32_e32 v62, v62, v62
	v_fma_f32 v63, v80, v23, v149
	v_add_f32_e32 v65, 1.0, v136
	v_med3_f32 v62, v62, s9, v244
	v_mul_f32_e32 v63, v68, v63
	v_rcp_f32_e32 v138, v65
	v_mul_f32_e32 v62, 0xbfb8aa3b, v62
	v_max_f32_e32 v63, 0xda24260, v63
	v_lshlrev_b32_e32 v64, 16, v64
	v_exp_f32_e32 v137, v62
	v_mul_f32_e32 v64, v63, v64
	v_bfe_u32 v65, v64, 16, 1
	v_add3_u32 v151, v64, v65, s10
	v_fma_f32 v64, v80, v138, v149
	v_rcp_f32_e32 v131, v63
	v_mul_f32_e32 v63, v63, v64
	v_add_f32_e32 v64, 1.0, v137
	v_max_f32_e32 v62, 0xda24260, v63
	v_lshlrev_b32_e32 v63, 16, v139
	v_rcp_f32_e32 v139, v64
	v_mul_f32_e32 v63, v62, v63
	v_bfe_u32 v64, v63, 16, 1
	v_add3_u32 v152, v63, v64, s10
	v_fma_f32 v63, v80, v139, v149
	v_rcp_f32_e32 v140, v62
	v_mul_f32_e32 v62, v62, v63
	v_max_f32_e32 v88, 0xda24260, v62
	v_lshlrev_b32_e32 v62, 16, v70
	v_mul_f32_e32 v62, v88, v62
	v_bfe_u32 v63, v62, 16, 1
	v_add3_u32 v153, v62, v63, s10
	v_pk_mul_f32 v[62:63], v[88:89], v[86:87] op_sel_hi:[0,1]
	v_pk_mul_f32 v[64:65], v[88:89], v[84:85] op_sel_hi:[0,1]
	v_rcp_f32_e32 v130, v68
	v_cvt_pk_bf16_f32 v62, v62, v63
	v_cvt_pk_bf16_f32 v63, v64, v65
	v_pk_mul_f32 v[64:65], v[88:89], v[74:75] op_sel_hi:[0,1]
	v_pk_mul_f32 v[68:69], v[88:89], v[144:145] op_sel_hi:[0,1]
	v_cvt_pk_bf16_f32 v64, v64, v65
	v_cvt_pk_bf16_f32 v65, v68, v69
	v_pk_mul_f32 v[68:69], v[88:89], v[104:105] op_sel_hi:[0,1]
	v_pk_mul_f32 v[70:71], v[88:89], v[116:117] op_sel_hi:[0,1]
	v_and_b32_e32 v73, 0xffff0000, v67
	v_and_b32_e32 v72, 0xffff0000, v142
	v_cvt_pk_bf16_f32 v68, v68, v69
	v_cvt_pk_bf16_f32 v69, v70, v71
	v_pk_mul_f32 v[70:71], v[88:89], v[128:129] op_sel_hi:[0,1]
	v_pk_mul_f32 v[72:73], v[88:89], v[72:73] op_sel_hi:[0,1]
	v_cvt_pk_bf16_f32 v70, v70, v71
	v_cvt_pk_bf16_f32 v71, v72, v73
	v_pk_mul_f32 v[72:73], v[102:103], v[114:115]
	v_rcp_f32_e32 v141, v88
	v_pk_mul_f32 v[72:73], v[80:81], v[72:73] op_sel_hi:[0,1]
	v_pk_mul_f32 v[72:73], v[72:73], v[134:135]
	s_nop 0
	v_and_b32_sdwa v67, v73, v239 dst_sel:DWORD dst_unused:UNUSED_PAD src0_sel:WORD_1 src1_sel:DWORD
	v_and_b32_sdwa v74, v72, v239 dst_sel:DWORD dst_unused:UNUSED_PAD src0_sel:WORD_1 src1_sel:DWORD
	v_add3_u32 v67, v73, v67, s10
	v_add3_u32 v72, v72, v74, s10
	v_pk_mul_f32 v[74:75], v[78:79], v[108:109]
	ds_write_b16_d16_hi v17, v72 offset:6912
	ds_write_b16_d16_hi v17, v67 offset:7056
	v_and_b32_e32 v73, 0xffff0000, v67
	v_and_b32_e32 v72, 0xffff0000, v72
	v_pk_mul_f32 v[74:75], v[80:81], v[74:75] op_sel_hi:[0,1]
	v_pk_mul_f32 v[72:73], v[88:89], v[72:73] op_sel_hi:[0,1]
	v_pk_mul_f32 v[74:75], v[74:75], v[132:133]
	v_cvt_pk_bf16_f32 v72, v72, v73
	v_and_b32_sdwa v67, v75, v239 dst_sel:DWORD dst_unused:UNUSED_PAD src0_sel:WORD_1 src1_sel:DWORD
	v_and_b32_sdwa v73, v74, v239 dst_sel:DWORD dst_unused:UNUSED_PAD src0_sel:WORD_1 src1_sel:DWORD
	v_add3_u32 v67, v75, v67, s10
	v_add3_u32 v73, v74, v73, s10
	v_and_b32_e32 v75, 0xffff0000, v67
	v_and_b32_e32 v74, 0xffff0000, v73
	v_pk_mul_f32 v[74:75], v[88:89], v[74:75] op_sel_hi:[0,1]
	ds_write_b16_d16_hi v17, v73 offset:7200
	ds_write_b16_d16_hi v17, v67 offset:7344
	v_cvt_pk_bf16_f32 v73, v74, v75
	v_pk_mul_f32 v[74:75], v[76:77], v[82:83]
	s_nop 0
	v_pk_mul_f32 v[74:75], v[80:81], v[74:75] op_sel_hi:[0,1]
	v_pk_mul_f32 v[74:75], v[74:75], v[122:123]
	s_nop 0
	v_and_b32_sdwa v67, v75, v239 dst_sel:DWORD dst_unused:UNUSED_PAD src0_sel:WORD_1 src1_sel:DWORD
	v_and_b32_sdwa v76, v74, v239 dst_sel:DWORD dst_unused:UNUSED_PAD src0_sel:WORD_1 src1_sel:DWORD
	v_add3_u32 v67, v75, v67, s10
	v_add3_u32 v74, v74, v76, s10
	v_pk_mul_f32 v[76:77], v[112:113], v[118:119]
	ds_write_b16_d16_hi v17, v74 offset:7488
	ds_write_b16_d16_hi v17, v67 offset:7632
	v_and_b32_e32 v75, 0xffff0000, v67
	v_and_b32_e32 v74, 0xffff0000, v74
	v_pk_mul_f32 v[76:77], v[80:81], v[76:77] op_sel_hi:[0,1]
	v_pk_mul_f32 v[74:75], v[88:89], v[74:75] op_sel_hi:[0,1]
	v_pk_mul_f32 v[76:77], v[76:77], v[124:125]
	v_cvt_pk_bf16_f32 v74, v74, v75
	v_and_b32_sdwa v75, v76, v239 dst_sel:DWORD dst_unused:UNUSED_PAD src0_sel:WORD_1 src1_sel:DWORD
	v_and_b32_sdwa v67, v77, v239 dst_sel:DWORD dst_unused:UNUSED_PAD src0_sel:WORD_1 src1_sel:DWORD
	v_add3_u32 v75, v76, v75, s10
	v_add3_u32 v67, v77, v67, s10
	ds_write_b16_d16_hi v17, v75 offset:7776
	ds_write_b16_d16_hi v17, v67 offset:7920
	v_pk_mul_f32 v[24:25], v[24:25], v[106:107]
	v_and_b32_e32 v77, 0xffff0000, v67
	v_and_b32_e32 v76, 0xffff0000, v75
	v_pk_mul_f32 v[24:25], v[80:81], v[24:25] op_sel_hi:[0,1]
	v_pk_mul_f32 v[76:77], v[88:89], v[76:77] op_sel_hi:[0,1]
	v_pk_mul_f32 v[24:25], v[24:25], v[120:121]
	v_cvt_pk_bf16_f32 v75, v76, v77
	v_and_b32_sdwa v67, v25, v239 dst_sel:DWORD dst_unused:UNUSED_PAD src0_sel:WORD_1 src1_sel:DWORD
	v_and_b32_sdwa v76, v24, v239 dst_sel:DWORD dst_unused:UNUSED_PAD src0_sel:WORD_1 src1_sel:DWORD
	v_add3_u32 v25, v25, v67, s10
	v_add3_u32 v24, v24, v76, s10
	v_pk_mul_f32 v[20:21], v[20:21], v[110:111]
	ds_write_b16_d16_hi v17, v143 offset:3456
	ds_write_b16_d16_hi v17, v146 offset:3600
	ds_write_b16_d16_hi v17, v95 offset:3744
	ds_write_b16_d16_hi v17, v147 offset:3888
	ds_write_b16_d16_hi v17, v150 offset:4032
	ds_write_b16_d16_hi v17, v151 offset:4176
	ds_write_b16_d16_hi v17, v152 offset:4320
	ds_write_b16_d16_hi v17, v153 offset:4464
	ds_write_b16_d16_hi v17, v24 offset:8064
	ds_write_b16_d16_hi v17, v25 offset:8208
	v_and_b32_e32 v25, 0xffff0000, v25
	v_and_b32_e32 v24, 0xffff0000, v24
	v_pk_mul_f32 v[20:21], v[80:81], v[20:21] op_sel_hi:[0,1]
	v_pk_mul_f32 v[24:25], v[88:89], v[24:25] op_sel_hi:[0,1]
	v_pk_mul_f32 v[20:21], v[20:21], v[126:127]
	v_cvt_pk_bf16_f32 v76, v24, v25
	v_and_b32_sdwa v24, v21, v239 dst_sel:DWORD dst_unused:UNUSED_PAD src0_sel:WORD_1 src1_sel:DWORD
	v_and_b32_sdwa v25, v20, v239 dst_sel:DWORD dst_unused:UNUSED_PAD src0_sel:WORD_1 src1_sel:DWORD
	v_add3_u32 v21, v21, v24, s10
	v_add3_u32 v20, v20, v25, s10
	v_pk_mul_f32 v[18:19], v[18:19], v[22:23]
	ds_write_b16_d16_hi v17, v20 offset:8352
	ds_write_b16_d16_hi v17, v21 offset:8496
	v_and_b32_e32 v21, 0xffff0000, v21
	v_and_b32_e32 v20, 0xffff0000, v20
	v_pk_mul_f32 v[18:19], v[80:81], v[18:19] op_sel_hi:[0,1]
	v_pk_mul_f32 v[20:21], v[88:89], v[20:21] op_sel_hi:[0,1]
	v_pk_mul_f32 v[18:19], v[18:19], v[130:131]
	v_cvt_pk_bf16_f32 v77, v20, v21
	v_and_b32_sdwa v20, v19, v239 dst_sel:DWORD dst_unused:UNUSED_PAD src0_sel:WORD_1 src1_sel:DWORD
	v_and_b32_sdwa v21, v18, v239 dst_sel:DWORD dst_unused:UNUSED_PAD src0_sel:WORD_1 src1_sel:DWORD
	v_add3_u32 v19, v19, v20, s10
	v_add3_u32 v18, v18, v21, s10
	ds_write_b16_d16_hi v17, v18 offset:8640
	ds_write_b16_d16_hi v17, v19 offset:8784
	v_and_b32_e32 v19, 0xffff0000, v19
	v_and_b32_e32 v18, 0xffff0000, v18
	v_pk_mul_f32 v[18:19], v[88:89], v[18:19] op_sel_hi:[0,1]
	v_cvt_pk_bf16_f32 v78, v18, v19
	v_pk_mul_f32 v[18:19], v[136:137], v[138:139]
	s_nop 0
	v_pk_mul_f32 v[18:19], v[80:81], v[18:19] op_sel_hi:[0,1]
	v_pk_mul_f32 v[18:19], v[18:19], v[140:141]
	s_nop 0
	v_and_b32_sdwa v21, v18, v239 dst_sel:DWORD dst_unused:UNUSED_PAD src0_sel:WORD_1 src1_sel:DWORD
	v_and_b32_sdwa v20, v19, v239 dst_sel:DWORD dst_unused:UNUSED_PAD src0_sel:WORD_1 src1_sel:DWORD
	v_add3_u32 v18, v18, v21, s10
	v_add3_u32 v19, v19, v20, s10
	ds_write_b16_d16_hi v17, v18 offset:8928
	ds_write_b16_d16_hi v17, v19 offset:9072
	v_and_b32_e32 v19, 0xffff0000, v19
	v_and_b32_e32 v18, 0xffff0000, v18
	v_pk_mul_f32 v[18:19], v[88:89], v[18:19] op_sel_hi:[0,1]
	v_cvt_pk_bf16_f32 v79, v18, v19
	v_lshl_add_u32 v16, v16, 2, v92
	ds_write_b128 v66, v[62:65] offset:9216
	ds_write_b128 v66, v[68:71] offset:9232
	ds_write_b128 v66, v[72:75] offset:9248
	ds_write_b128 v66, v[76:79] offset:9264
	ds_write_b32 v16, v88 offset:19456
	ds_write_b128 v66, v[12:15] offset:14336
	ds_write_b128 v66, v[8:11] offset:14352
	ds_write_b128 v66, v[4:7] offset:14368
	ds_write_b128 v66, v[0:3] offset:14384
	s_waitcnt lgkmcnt(0)
	s_movk_i32 s17, 0x90
	v_mad_u32_u24 v72, v35, s17, v92
	v_lshlrev_b32_e32 v73, 4, v81
	v_add_u32_e32 v66, v72, v73
	ds_read_b128 v[0:3], v66 offset:4608
	ds_read_b128 v[4:7], v66
	ds_read_b128 v[18:21], v66 offset:32
	ds_read_b128 v[22:25], v66 offset:4640
	ds_read_b128 v[62:65], v66 offset:4672
	s_waitcnt lgkmcnt(3)
	v_mfma_f32_32x32x16_bf16 v[2:17], v[0:3], v[4:7], 0
	v_lshlrev_b32_e32 v70, 2, v81
	v_cmp_le_i32_e32 vcc, v70, v35
	v_or_b32_e32 v74, 2, v70
	v_or_b32_e32 v75, 3, v70
	v_or_b32_e32 v88, v93, v35
	v_add_u32_e32 v76, 8, v70
	v_lshlrev_b64 v[0:1], 11, v[88:89]
	s_waitcnt lgkmcnt(1)
	v_mfma_f32_32x32x16_bf16 v[2:17], v[22:25], v[18:21], v[2:17]
	ds_read_b128 v[18:21], v66 offset:64
	ds_read_b128 v[22:25], v66 offset:4704
	ds_read_b128 v[66:69], v66 offset:96
	v_lshl_add_u64 v[0:1], s[2:3], 0, v[0:1]
	v_ashrrev_i32_e32 v71, 31, v70
	v_lshl_add_u64 v[0:1], v[0:1], 0, v[90:91]
	v_lshl_add_u64 v[84:85], v[70:71], 1, v[0:1]
	v_add_u32_e32 v0, 16, v70
	s_waitcnt lgkmcnt(2)
	v_mfma_f32_32x32x16_bf16 v[2:17], v[62:65], v[18:21], v[2:17]
	v_add_u32_e32 v18, 9, v70
	v_add_u32_e32 v19, 10, v70
	v_add_u32_e32 v20, 11, v70
	v_lshlrev_b32_e32 v138, 16, v42
	v_and_b32_e32 v139, 0xffff0000, v42
	v_lshlrev_b32_e32 v42, 16, v43
	v_and_b32_e32 v43, 0xffff0000, v43
	s_waitcnt lgkmcnt(0)
	v_mfma_f32_32x32x16_bf16 v[2:17], v[22:25], v[66:69], v[2:17]
	v_lshlrev_b32_e32 v140, 16, v36
	v_and_b32_e32 v141, 0xffff0000, v36
	v_lshlrev_b32_e32 v142, 16, v37
	v_and_b32_e32 v143, 0xffff0000, v37
	v_cvt_pk_bf16_f32 v130, v138, v139
	v_cvt_pk_bf16_f32 v131, v42, v43
	v_cvt_pk_bf16_f32 v132, v140, v141
	s_nop 4
	v_cndmask_b32_e32 v21, 0, v2, vcc
	v_cmp_lt_i32_e32 vcc, v70, v35
	v_cvt_pk_bf16_f32 v133, v142, v143
	v_add_u32_e32 v95, v92, v73
	v_cndmask_b32_e32 v22, 0, v3, vcc
	v_cmp_le_i32_e32 vcc, v74, v35
	v_lshlrev_b32_e32 v74, 3, v81
	v_add_u32_e32 v88, v72, v74
	v_cndmask_b32_e32 v4, 0, v4, vcc
	v_cmp_le_i32_e32 vcc, v75, v35
	v_mad_u32_u24 v144, v35, s16, v95
	v_cvt_pk_bf16_f32 v36, v44, v45
	v_cndmask_b32_e32 v5, 0, v5, vcc
	v_cmp_le_i32_e32 vcc, v76, v35
	v_cvt_pk_bf16_f32 v37, v46, v47
	v_lshlrev_b32_e32 v78, 16, v60
	v_cndmask_b32_e32 v6, 0, v6, vcc
	v_cmp_le_i32_e32 vcc, v18, v35
	v_cvt_pk_bf16_f32 v18, v21, v22
	v_and_b32_e32 v79, 0xffff0000, v60
	v_cndmask_b32_e32 v7, 0, v7, vcc
	v_cmp_le_i32_e32 vcc, v19, v35
	v_cvt_pk_bf16_f32 v19, v4, v5
	v_lshlrev_b32_e32 v82, 16, v61
	v_cndmask_b32_e32 v8, 0, v8, vcc
	v_cmp_le_i32_e32 vcc, v20, v35
	v_cvt_pk_bf16_f32 v20, v6, v7
	v_and_b32_e32 v83, 0xffff0000, v61
	v_cndmask_b32_e32 v9, 0, v9, vcc
	v_cmp_le_i32_e32 vcc, v0, v35
	v_add_u32_e32 v0, 17, v70
	v_cvt_pk_bf16_f32 v21, v8, v9
	v_cndmask_b32_e32 v23, 0, v10, vcc
	v_cmp_le_i32_e32 vcc, v0, v35
	v_add_u32_e32 v0, 18, v70
	v_add_u32_e32 v10, 26, v70
	v_cndmask_b32_e32 v24, 0, v11, vcc
	v_cmp_le_i32_e32 vcc, v0, v35
	v_add_u32_e32 v0, 19, v70
	v_cvt_pk_bf16_f32 v22, v23, v24
	v_cndmask_b32_e32 v25, 0, v12, vcc
	v_cmp_le_i32_e32 vcc, v0, v35
	v_add_u32_e32 v0, 24, v70
	v_lshlrev_b32_e32 v60, 16, v58
	v_cndmask_b32_e32 v68, 0, v13, vcc
	v_cmp_le_i32_e32 vcc, v0, v35
	v_add_u32_e32 v0, 25, v70
	v_add_u32_e32 v70, 27, v70
	v_cndmask_b32_e32 v69, 0, v14, vcc
	v_cmp_le_i32_e32 vcc, v0, v35
	v_mul_u32_u24_e32 v0, 0x50, v35
	v_add3_u32 v81, v92, v74, v0
	v_add_u32_e32 v11, 0x3800, v81
	ds_read2_b64 v[0:3], v11 offset1:2
	ds_read2_b64 v[64:67], v11 offset0:4 offset1:6
	v_cndmask_b32_e32 v71, 0, v15, vcc
	v_cmp_le_i32_e32 vcc, v10, v35
	s_waitcnt lgkmcnt(1)
	v_mfma_f32_32x32x16_bf16 v[0:15], v[0:3], v[18:21], 0
	v_cndmask_b32_e32 v16, 0, v16, vcc
	v_cmp_le_i32_e32 vcc, v70, v35
	v_cvt_pk_bf16_f32 v23, v25, v68
	v_cvt_pk_bf16_f32 v24, v69, v71
	v_cndmask_b32_e32 v17, 0, v17, vcc
	v_cvt_pk_bf16_f32 v25, v16, v17
	ds_read2_b64 v[106:109], v88 offset1:2
	ds_read2_b64 v[110:113], v88 offset0:4 offset1:6
	ds_read2_b64 v[114:117], v88 offset0:8 offset1:10
	ds_read2_b64 v[118:121], v88 offset0:12 offset1:14
	s_waitcnt lgkmcnt(4)
	v_mfma_f32_32x32x16_bf16 v[0:15], v[64:67], v[22:25], v[0:15]
	v_cvt_pk_bf16_f32 v35, v40, v41
	v_and_b32_e32 v61, 0xffff0000, v58
	v_lshlrev_b32_e32 v58, 16, v59
	v_and_b32_e32 v59, 0xffff0000, v59
	v_cvt_pk_bf16_f32 v122, v78, v79
	v_cvt_pk_bf16_f32 v123, v82, v83
	v_cvt_pk_bf16_f32 v124, v60, v61
	s_waitcnt lgkmcnt(3)
	v_mfma_f32_32x32x16_bf16 v[0:15], v[130:133], v[106:109], v[0:15]
	v_lshlrev_b32_e32 v106, 16, v34
	v_and_b32_e32 v107, 0xffff0000, v34
	v_cvt_pk_bf16_f32 v34, v106, v107
	v_cvt_pk_bf16_f32 v125, v58, v59
	v_lshlrev_b32_e32 v86, 16, v56
	v_and_b32_e32 v87, 0xffff0000, v56
	v_lshlrev_b32_e32 v56, 16, v57
	s_waitcnt lgkmcnt(2)
	v_mfma_f32_32x32x16_bf16 v[0:15], v[34:37], v[110:113], v[0:15]
	v_and_b32_e32 v57, 0xffff0000, v57
	v_lshlrev_b32_e32 v102, 16, v54
	v_and_b32_e32 v103, 0xffff0000, v54
	v_lshlrev_b32_e32 v104, 16, v55
	v_and_b32_e32 v105, 0xffff0000, v55
	v_cvt_pk_bf16_f32 v126, v86, v87
	v_cvt_pk_bf16_f32 v127, v56, v57
	s_waitcnt lgkmcnt(1)
	v_mfma_f32_32x32x16_bf16 v[0:15], v[122:125], v[114:117], v[0:15]
	v_cvt_pk_bf16_f32 v128, v102, v103
	v_cvt_pk_bf16_f32 v129, v104, v105
	s_mov_b64 s[2:3], 0x16f00600
	v_lshl_add_u64 v[62:63], v[84:85], 0, s[2:3]
	s_mov_b32 s2, 0x16f00000
	v_lshlrev_b32_e32 v16, 16, v26
	v_and_b32_e32 v17, 0xffff0000, v26
	s_waitcnt lgkmcnt(0)
	v_mfma_f32_32x32x16_bf16 v[0:15], v[126:129], v[118:121], v[0:15]
	v_lshlrev_b32_e32 v64, 16, v27
	v_and_b32_e32 v65, 0xffff0000, v27
	v_lshlrev_b32_e32 v66, 16, v28
	v_and_b32_e32 v67, 0xffff0000, v28
	v_lshlrev_b32_e32 v68, 16, v29
	v_and_b32_e32 v69, 0xffff0000, v29
	v_lshlrev_b32_e32 v70, 16, v30
	s_nop 4
	v_cvt_pk_bf16_f32 v0, v0, v1
	v_cvt_pk_bf16_f32 v1, v2, v3
	v_add_co_u32_e32 v2, vcc, s2, v84
	v_and_b32_e32 v71, 0xffff0000, v30
	s_nop 0
	v_addc_co_u32_e32 v3, vcc, 0, v85, vcc
	global_store_dwordx2 v[2:3], v[0:1], off offset:1536
	v_cvt_pk_bf16_f32 v0, v4, v5
	v_cvt_pk_bf16_f32 v1, v6, v7
	global_store_dwordx2 v[62:63], v[0:1], off offset:16
	v_cvt_pk_bf16_f32 v0, v8, v9
	v_cvt_pk_bf16_f32 v1, v10, v11
	v_lshlrev_b32_e32 v72, 16, v31
	v_and_b32_e32 v73, 0xffff0000, v31
	v_lshlrev_b32_e32 v74, 16, v32
	v_and_b32_e32 v75, 0xffff0000, v32
	v_lshlrev_b32_e32 v76, 16, v33
	v_and_b32_e32 v77, 0xffff0000, v33
	v_lshlrev_b32_e32 v54, 16, v52
	v_and_b32_e32 v55, 0xffff0000, v52
	v_lshlrev_b32_e32 v52, 16, v53
	v_and_b32_e32 v53, 0xffff0000, v53
	v_lshlrev_b32_e32 v130, 16, v50
	v_and_b32_e32 v131, 0xffff0000, v50
	v_lshlrev_b32_e32 v50, 16, v51
	v_and_b32_e32 v51, 0xffff0000, v51
	v_lshlrev_b32_e32 v132, 16, v48
	v_and_b32_e32 v133, 0xffff0000, v48
	v_lshlrev_b32_e32 v48, 16, v49
	v_and_b32_e32 v49, 0xffff0000, v49
	v_lshlrev_b32_e32 v114, 16, v38
	v_and_b32_e32 v115, 0xffff0000, v38
	v_lshlrev_b32_e32 v116, 16, v39
	v_and_b32_e32 v117, 0xffff0000, v39
	global_store_dwordx2 v[62:63], v[0:1], off offset:32
	v_cvt_pk_bf16_f32 v0, v12, v13
	v_cvt_pk_bf16_f32 v1, v14, v15
	v_cvt_pk_bf16_f32 v26, v16, v17
	v_cvt_pk_bf16_f32 v27, v64, v65
	v_cvt_pk_bf16_f32 v28, v66, v67
	v_cvt_pk_bf16_f32 v29, v68, v69
	v_cvt_pk_bf16_f32 v30, v70, v71
	v_cvt_pk_bf16_f32 v31, v72, v73
	v_cvt_pk_bf16_f32 v32, v74, v75
	v_cvt_pk_bf16_f32 v33, v76, v77
	v_cvt_pk_bf16_f32 v134, v54, v55
	v_cvt_pk_bf16_f32 v135, v52, v53
	v_cvt_pk_bf16_f32 v136, v130, v131
	v_cvt_pk_bf16_f32 v137, v50, v51
	v_cvt_pk_bf16_f32 v34, v132, v133
	v_cvt_pk_bf16_f32 v35, v48, v49
	v_cvt_pk_bf16_f32 v36, v114, v115
	v_cvt_pk_bf16_f32 v37, v116, v117
	global_store_dwordx2 v[62:63], v[0:1], off offset:48
	v_add_u32_e32 v38, 0x4000, v81
	ds_read2_b64 v[0:3], v38 offset0:64 offset1:66
	s_waitcnt lgkmcnt(0)
	v_mfma_f32_32x32x16_bf16 v[0:15], v[0:3], v[18:21], 0
	ds_read2_b64 v[18:21], v38 offset0:68 offset1:70
	s_waitcnt lgkmcnt(0)
	v_mfma_f32_32x32x16_bf16 v[0:15], v[18:21], v[22:25], v[0:15]
	ds_read2_b64 v[18:21], v88 offset1:2
	s_waitcnt lgkmcnt(0)
	v_mfma_f32_32x32x16_bf16 v[0:15], v[134:137], v[18:21], v[0:15]
	ds_read2_b64 v[18:21], v88 offset0:4 offset1:6
	s_waitcnt lgkmcnt(0)
	v_mfma_f32_32x32x16_bf16 v[0:15], v[34:37], v[18:21], v[0:15]
	ds_read2_b64 v[18:21], v88 offset0:8 offset1:10
	s_waitcnt lgkmcnt(0)
	v_mfma_f32_32x32x16_bf16 v[0:15], v[26:29], v[18:21], v[0:15]
	ds_read2_b64 v[18:21], v88 offset0:12 offset1:14
	s_waitcnt lgkmcnt(0)
	v_mfma_f32_32x32x16_bf16 v[0:15], v[30:33], v[18:21], v[0:15]
	s_nop 11
	v_cvt_pk_bf16_f32 v0, v0, v1
	v_cvt_pk_bf16_f32 v1, v2, v3
	v_cvt_pk_bf16_f32 v2, v4, v5
	v_cvt_pk_bf16_f32 v3, v6, v7
	v_cvt_pk_bf16_f32 v4, v8, v9
	v_cvt_pk_bf16_f32 v5, v10, v11
	v_cvt_pk_bf16_f32 v6, v12, v13
	v_cvt_pk_bf16_f32 v7, v14, v15
	global_store_dwordx2 v[62:63], v[0:1], off offset:64
	global_store_dwordx2 v[62:63], v[2:3], off offset:80
	global_store_dwordx2 v[62:63], v[4:5], off offset:96
	global_store_dwordx2 v[62:63], v[6:7], off offset:112
	ds_read_b128 v[0:3], v95 offset:19456
	ds_read_b128 v[4:7], v95 offset:19488
	ds_read_b128 v[8:11], v95 offset:19520
	ds_read_b128 v[12:15], v95 offset:19552
	ds_read_b128 v[18:21], v144 offset:9216
	s_waitcnt lgkmcnt(4)
	v_pk_mul_f32 v[34:35], v[2:3], v[42:43]
	ds_read_b128 v[22:25], v144 offset:14336
	s_waitcnt lgkmcnt(3)
	v_pk_mul_f32 v[42:43], v[10:11], v[40:41]
	v_pk_mul_f32 v[40:41], v[8:9], v[106:107]
	ds_read_b128 v[26:29], v144 offset:9248
	ds_read_b128 v[106:109], v144 offset:14368
	ds_read_b128 v[110:113], v144 offset:16896
	v_pk_mul_f32 v[32:33], v[0:1], v[138:139]
	v_pk_mul_f32 v[38:39], v[6:7], v[142:143]
	v_pk_mul_f32 v[36:37], v[4:5], v[140:141]
	s_waitcnt lgkmcnt(5)
	v_pk_mul_f32 v[46:47], v[14:15], v[46:47]
	v_pk_mul_f32 v[44:45], v[12:13], v[44:45]
	v_pk_mul_f32 v[0:1], v[0:1], v[54:55]
	v_pk_mul_f32 v[2:3], v[2:3], v[52:53]
	v_pk_mul_f32 v[4:5], v[4:5], v[130:131]
	v_pk_mul_f32 v[6:7], v[6:7], v[50:51]
	v_pk_mul_f32 v[8:9], v[8:9], v[132:133]
	v_pk_mul_f32 v[10:11], v[10:11], v[48:49]
	v_pk_mul_f32 v[12:13], v[12:13], v[114:115]
	v_pk_mul_f32 v[14:15], v[14:15], v[116:117]
	s_waitcnt lgkmcnt(3)
	v_mfma_f32_32x32x16_bf16 v[32:47], v[18:21], v[22:25], v[32:47]
	ds_read_b128 v[114:117], v144 offset:16928
	s_waitcnt lgkmcnt(1)
	v_mfma_f32_32x32x16_bf16 v[0:15], v[18:21], v[110:113], v[0:15]
	v_mfma_f32_32x32x16_bf16 v[32:47], v[26:29], v[106:109], v[32:47]
	s_waitcnt lgkmcnt(0)
	v_mfma_f32_32x32x16_bf16 v[0:15], v[26:29], v[114:117], v[0:15]
	ds_read_b128 v[18:21], v95 offset:19584
	ds_read_b128 v[26:29], v95 offset:19616
	ds_read_b128 v[118:121], v95 offset:19648
	ds_read_b128 v[122:125], v95 offset:19680
	ds_read_b128 v[126:129], v144 offset:11776
	s_waitcnt lgkmcnt(4)
	v_pk_mul_f32 v[50:51], v[20:21], v[82:83]
	v_pk_mul_f32 v[48:49], v[18:19], v[78:79]
	s_waitcnt lgkmcnt(3)
	v_pk_mul_f32 v[54:55], v[28:29], v[58:59]
	v_pk_mul_f32 v[52:53], v[26:27], v[60:61]
	s_waitcnt lgkmcnt(2)
	v_pk_mul_f32 v[58:59], v[120:121], v[56:57]
	v_pk_mul_f32 v[56:57], v[118:119], v[86:87]
	s_waitcnt lgkmcnt(1)
	v_pk_mul_f32 v[62:63], v[124:125], v[104:105]
	v_pk_mul_f32 v[60:61], v[122:123], v[102:103]
	ds_read_b128 v[82:85], v144 offset:11808
	v_pk_mul_f32 v[16:17], v[18:19], v[16:17]
	s_waitcnt lgkmcnt(1)
	v_mfma_f32_32x32x16_bf16 v[48:63], v[126:129], v[22:25], v[48:63]
	v_mul_f32_e64 v18, v20, v64
	v_mul_f32_e64 v19, v21, v65
	v_mul_f32_e64 v20, v26, v66
	v_mul_f32_e64 v21, v27, v67
	v_mul_f32_e64 v22, v28, v68
	v_mul_f32_e64 v23, v29, v69
	v_pk_mul_f32 v[24:25], v[118:119], v[70:71]
	v_pk_mul_f32 v[26:27], v[120:121], v[72:73]
	v_pk_mul_f32 v[28:29], v[122:123], v[74:75]
	v_pk_mul_f32 v[30:31], v[124:125], v[76:77]
	s_waitcnt lgkmcnt(0)
	s_waitcnt lgkmcnt(0)
	v_mfma_f32_32x32x16_bf16 v[48:63], v[82:85], v[106:109], v[48:63]
	v_mfma_f32_32x32x16_bf16 v[16:31], v[126:129], v[110:113], v[16:31]
	v_mfma_f32_32x32x16_bf16 v[16:31], v[82:85], v[114:117], v[16:31]
	v_mov_b32_e32 v82, v94
	s_mov_b64 s[16:17], s[44:45]
	v_or_b32_e32 v95, 32, v93
	v_and_b32_e32 v124, 31, v82
	v_ashrrev_i32_e32 v125, 5, v82
	v_mov_b64_e32 v[64:65], s[16:17]
	s_movk_i32 s2, 0x1200
	v_mad_i64_i32 v[64:65], s[2:3], v95, s2, v[64:65]
	v_ashrrev_i32_e32 v83, 31, v82
	v_lshl_add_u64 v[64:65], v[64:65], 0, v[90:91]
	v_lshl_add_u64 v[64:65], v[82:83], 1, v[64:65]
	v_lshl_add_u64 v[114:115], v[64:65], 0, s[0:1]
	global_load_ushort v88, v[114:115], off offset:2560
	global_load_ushort v81, v[114:115], off offset:3072
	v_add_co_u32_e32 v112, vcc, s7, v64
	s_mov_b32 s0, 0xb20f000
	s_nop 0
	v_addc_co_u32_e32 v113, vcc, 0, v65, vcc
	global_load_ushort v126, v[112:113], off offset:3584
	v_add_co_u32_e32 v110, vcc, s11, v64
	v_lshl_add_u32 v83, v82, 1, v92
	s_nop 0
	v_addc_co_u32_e32 v111, vcc, 0, v65, vcc
	v_add_co_u32_e32 v108, vcc, s12, v64
	s_waitcnt vmcnt(1)
	v_lshlrev_b32_e32 v81, 16, v81
	v_max_f32_e32 v81, v81, v81
	v_med3_f32 v81, v81, s9, v244
	v_mul_f32_e32 v81, 0xbfb8aa3b, v81
	v_exp_f32_e32 v81, v81
	v_addc_co_u32_e32 v109, vcc, 0, v65, vcc
	v_add_co_u32_e32 v106, vcc, s13, v64
	v_add_f32_e32 v116, 1.0, v81
	v_rcp_f32_e32 v116, v116
	v_addc_co_u32_e32 v107, vcc, 0, v65, vcc
	v_add_co_u32_e32 v104, vcc, s14, v64
	v_fma_f32 v117, v80, v116, v149
	v_max_f32_e32 v183, 0xda24260, v117
	v_mul_f32_e32 v81, v81, v116
	v_rcp_f32_e32 v116, v183
	v_mul_f32_e32 v81, v80, v81
	v_addc_co_u32_e32 v105, vcc, 0, v65, vcc
	v_mul_f32_e32 v81, v81, v116
	v_bfe_u32 v116, v81, 16, 1
	v_add3_u32 v133, v81, v116, s10
	global_load_ushort v81, v[114:115], off offset:2048
	global_load_ushort v127, v[110:111], off offset:512
	global_load_ushort v128, v[108:109], off offset:1536
	global_load_ushort v129, v[106:107], off offset:2560
	global_load_ushort v130, v[104:105], off offset:3584
	v_add_co_u32_e32 v102, vcc, s15, v64
	s_waitcnt vmcnt(4)
	v_lshlrev_b32_e32 v81, 16, v81
	v_addc_co_u32_e32 v103, vcc, 0, v65, vcc
	v_add_co_u32_e32 v86, vcc, s18, v64
	global_load_ushort v131, v[102:103], off offset:512
	s_nop 0
	v_addc_co_u32_e32 v87, vcc, 0, v65, vcc
	v_add_co_u32_e32 v74, vcc, s19, v64
	global_load_ushort v132, v[86:87], off offset:1536
	s_nop 0
	v_addc_co_u32_e32 v75, vcc, 0, v65, vcc
	v_add_co_u32_e32 v78, vcc, s21, v64
	global_load_ushort v134, v[74:75], off offset:2560
	s_nop 0
	v_addc_co_u32_e32 v79, vcc, 0, v65, vcc
	v_add_co_u32_e32 v76, vcc, s30, v64
	global_load_ushort v135, v[78:79], off offset:3584
	s_nop 0
	v_addc_co_u32_e32 v77, vcc, 0, v65, vcc
	v_add_co_u32_e32 v84, vcc, s31, v64
	v_mul_f32_e32 v81, v183, v81
	s_nop 0
	v_addc_co_u32_e32 v85, vcc, 0, v65, vcc
	v_add_co_u32_e32 v66, vcc, s34, v64
	global_load_ushort v137, v[84:85], off offset:1536
	global_load_ushort v136, v[76:77], off offset:512
	v_addc_co_u32_e32 v67, vcc, 0, v65, vcc
	v_add_co_u32_e32 v72, vcc, s35, v64
	global_load_ushort v138, v[66:67], off offset:2560
	s_nop 0
	v_addc_co_u32_e32 v73, vcc, 0, v65, vcc
	v_add_co_u32_e32 v68, vcc, s36, v64
	global_load_ushort v139, v[72:73], off offset:3584
	s_nop 0
	v_addc_co_u32_e32 v69, vcc, 0, v65, vcc
	v_add_co_u32_e32 v70, vcc, s37, v64
	global_load_ushort v140, v[68:69], off offset:512
	s_nop 0
	v_addc_co_u32_e32 v71, vcc, 0, v65, vcc
	v_add_co_u32_e32 v116, vcc, s40, v64
	global_load_ushort v141, v[70:71], off offset:1536
	s_nop 0
	v_addc_co_u32_e32 v117, vcc, 0, v65, vcc
	global_load_ushort v187, v[116:117], off offset:3584
	global_load_ushort v182, v[116:117], off offset:2560
	v_bfe_u32 v114, v81, 16, 1
	v_add3_u32 v188, v81, v114, s10
	v_add_co_u32_e32 v114, vcc, s41, v64
	s_nop 1
	v_addc_co_u32_e32 v115, vcc, 0, v65, vcc
	v_add_co_u32_e32 v118, vcc, s46, v64
	s_nop 1
	v_addc_co_u32_e32 v119, vcc, 0, v65, vcc
	global_load_ushort v180, v[118:119], off offset:-4096
	global_load_ushort v176, v[112:113], off offset:3072
	global_load_ushort v175, v[118:119], off offset:512
	global_load_ushort v170, v[114:115], off offset:3584
	global_load_ushort v181, v[110:111], off offset:1024
	global_load_ushort v178, v[110:111], off
	v_add_co_u32_e32 v120, vcc, s28, v64
	s_nop 1
	v_addc_co_u32_e32 v121, vcc, 0, v65, vcc
	v_add_co_u32_e32 v122, vcc, s29, v64
	global_load_ushort v186, v[120:121], off offset:1536
	global_load_ushort v185, v[120:121], off offset:512
	global_load_ushort v184, v[108:109], off offset:2048
	global_load_ushort v179, v[108:109], off offset:1024
	v_addc_co_u32_e32 v123, vcc, 0, v65, vcc
	v_add_co_u32_e32 v190, vcc, s42, v64
	global_load_ushort v177, v[122:123], off offset:2560
	global_load_ushort v173, v[122:123], off offset:1536
	global_load_ushort v174, v[106:107], off offset:3072
	global_load_ushort v172, v[106:107], off offset:2048
	v_addc_co_u32_e32 v191, vcc, 0, v65, vcc
	v_add_co_u32_e32 v106, vcc, s6, v64
	global_load_ushort v171, v[190:191], off offset:3584
	global_load_ushort v169, v[190:191], off offset:2560
	v_addc_co_u32_e32 v107, vcc, 0, v65, vcc
	v_add_co_u32_e32 v154, vcc, s49, v64
	s_waitcnt vmcnt(4)
	v_lshlrev_b32_e32 v173, 16, v173
	v_addc_co_u32_e32 v155, vcc, 0, v65, vcc
	v_add_co_u32_e32 v192, vcc, s0, v64
	s_mov_b32 s0, 0xb211000
	s_nop 0
	v_addc_co_u32_e32 v193, vcc, 0, v65, vcc
	v_add_co_u32_e32 v194, vcc, s0, v64
	s_mov_b32 s0, 0xb21a000
	s_nop 0
	v_addc_co_u32_e32 v195, vcc, 0, v65, vcc
	v_add_co_u32_e32 v108, vcc, s43, v64
	global_load_ushort v166, v[154:155], off offset:-4096
	global_load_ushort v164, v[104:105], off offset:3072
	global_load_ushort v167, v[154:155], off offset:512
	global_load_ushort v158, v[106:107], off offset:3584
	global_load_ushort v168, v[102:103], off offset:1024
	global_load_ushort v163, v[102:103], off
	v_addc_co_u32_e32 v109, vcc, 0, v65, vcc
	v_add_co_u32_e32 v110, vcc, s47, v64
	global_load_ushort v165, v[192:193], off offset:1536
	global_load_ushort v157, v[192:193], off offset:512
	global_load_ushort v162, v[86:87], off offset:2048
	global_load_ushort v156, v[86:87], off offset:1024
	v_addc_co_u32_e32 v111, vcc, 0, v65, vcc
	v_add_co_u32_e32 v112, vcc, s48, v64
	global_load_ushort v159, v[194:195], off offset:2560
	global_load_ushort v81, v[194:195], off offset:1536
	v_addc_co_u32_e32 v113, vcc, 0, v65, vcc
	v_add_co_u32_e32 v114, vcc, s0, v64
	s_mov_b32 s0, 0xb223000
	s_nop 0
	v_addc_co_u32_e32 v115, vcc, 0, v65, vcc
	v_add_co_u32_e32 v86, vcc, s0, v64
	s_mov_b32 s0, 0xb221000
	s_nop 0
	v_addc_co_u32_e32 v87, vcc, 0, v65, vcc
	v_add_co_u32_e32 v102, vcc, s0, v64
	s_mov_b32 s0, 0xb21f000
	s_nop 0
	v_addc_co_u32_e32 v103, vcc, 0, v65, vcc
	v_add_co_u32_e32 v104, vcc, s0, v64
	global_load_ushort v142, v[86:87], off offset:2048
	global_load_ushort v143, v[102:103], off offset:1024
	global_load_ushort v145, v[68:69], off offset:-4096
	v_addc_co_u32_e32 v105, vcc, 0, v65, vcc
	v_add_co_u32_e32 v106, vcc, s97, v64
	s_nop 1
	v_addc_co_u32_e32 v107, vcc, 0, v65, vcc
	global_load_ushort v146, v[106:107], off offset:3072
	global_load_ushort v147, v[114:115], off offset:2048
	global_load_ushort v150, v[112:113], off offset:1024
	global_load_ushort v151, v[76:77], off offset:-4096
	global_load_ushort v152, v[108:109], off offset:3072
	global_load_ushort v153, v[194:195], off offset:2048
	global_load_ushort v144, v[192:193], off offset:1024
	s_nop 0
	global_load_ushort v154, v[154:155], off
	s_nop 0
	global_load_ushort v155, v[190:191], off offset:3072
	s_nop 0
	global_load_ushort v122, v[122:123], off offset:2048
	s_nop 0
	global_load_ushort v120, v[120:121], off offset:1024
	s_nop 0
	global_load_ushort v118, v[118:119], off
	s_nop 0
	global_load_ushort v121, v[116:117], off offset:3072
	v_lshlrev_b32_e32 v116, 16, v187
	v_max_f32_e32 v116, v116, v116
	v_med3_f32 v116, v116, s9, v244
	v_mul_f32_e32 v116, 0xbfb8aa3b, v116
	v_exp_f32_e32 v116, v116
	ds_write_b16_d16_hi v83, v188
	ds_write_b16_d16_hi v83, v133 offset:4608
	v_add_f32_e32 v117, 1.0, v116
	v_rcp_f32_e32 v117, v117
	s_nop 0
	v_fma_f32 v119, v80, v117, v149
	v_mul_f32_e32 v116, v116, v117
	v_mul_f32_e32 v117, v183, v119
	v_max_f32_e32 v117, 0xda24260, v117
	v_rcp_f32_e32 v119, v117
	v_mul_f32_e32 v116, v80, v116
	v_mul_f32_e32 v116, v116, v119
	v_bfe_u32 v119, v116, 16, 1
	v_add3_u32 v119, v116, v119, s10
	v_lshlrev_b32_e32 v116, 16, v182
	v_mul_f32_e32 v116, v117, v116
	v_bfe_u32 v123, v116, 16, 1
	v_add3_u32 v116, v116, v123, s10
	ds_write_b16_d16_hi v83, v116 offset:144
	ds_write_b16_d16_hi v83, v119 offset:4752
	v_lshlrev_b32_e32 v116, 16, v180
	v_max_f32_e32 v116, v116, v116
	v_med3_f32 v116, v116, s9, v244
	v_mul_f32_e32 v116, 0xbfb8aa3b, v116
	v_exp_f32_e32 v116, v116
	s_nop 0
	v_add_f32_e32 v123, 1.0, v116
	v_rcp_f32_e32 v123, v123
	s_nop 0
	v_fma_f32 v180, v80, v123, v149
	v_mul_f32_e32 v117, v117, v180
	v_max_f32_e32 v117, 0xda24260, v117
	v_mul_f32_e32 v116, v116, v123
	v_rcp_f32_e32 v123, v117
	v_mul_f32_e32 v116, v80, v116
	v_mul_f32_e32 v116, v116, v123
	v_bfe_u32 v123, v116, 16, 1
	v_add3_u32 v116, v116, v123, s10
	v_lshlrev_b32_e32 v123, 16, v176
	v_mul_f32_e32 v123, v117, v123
	v_bfe_u32 v176, v123, 16, 1
	v_add3_u32 v123, v123, v176, s10
	ds_write_b16_d16_hi v83, v123 offset:288
	ds_write_b16_d16_hi v83, v116 offset:4896
	v_lshlrev_b32_e32 v123, 16, v175
	v_max_f32_e32 v123, v123, v123
	v_med3_f32 v123, v123, s9, v244
	v_mul_f32_e32 v123, 0xbfb8aa3b, v123
	v_exp_f32_e32 v123, v123
	s_nop 0
	v_add_f32_e32 v175, 1.0, v123
	v_rcp_f32_e32 v175, v175
	s_nop 0
	v_fma_f32 v176, v80, v175, v149
	v_mul_f32_e32 v117, v117, v176
	v_mul_f32_e32 v123, v123, v175
	v_max_f32_e32 v175, 0xda24260, v117
	v_rcp_f32_e32 v117, v175
	v_mul_f32_e32 v123, v80, v123
	v_mul_f32_e32 v117, v123, v117
	v_bfe_u32 v123, v117, 16, 1
	v_add3_u32 v117, v117, v123, s10
	v_lshlrev_b32_e32 v123, 16, v170
	v_mul_f32_e32 v123, v175, v123
	v_bfe_u32 v170, v123, 16, 1
	v_add3_u32 v123, v123, v170, s10
	ds_write_b16_d16_hi v83, v123 offset:432
	ds_write_b16_d16_hi v83, v117 offset:5040
	v_lshlrev_b32_e32 v123, 16, v181
	v_max_f32_e32 v123, v123, v123
	v_med3_f32 v123, v123, s9, v244
	v_mul_f32_e32 v123, 0xbfb8aa3b, v123
	v_exp_f32_e32 v123, v123
	s_nop 0
	v_add_f32_e32 v170, 1.0, v123
	v_rcp_f32_e32 v170, v170
	s_nop 0
	v_fma_f32 v176, v80, v170, v149
	v_mul_f32_e32 v123, v123, v170
	v_mul_f32_e32 v170, v175, v176
	v_max_f32_e32 v170, 0xda24260, v170
	v_rcp_f32_e32 v175, v170
	v_mul_f32_e32 v123, v80, v123
	v_mul_f32_e32 v123, v123, v175
	v_bfe_u32 v175, v123, 16, 1
	v_add3_u32 v123, v123, v175, s10
	v_lshlrev_b32_e32 v175, 16, v178
	v_mul_f32_e32 v175, v170, v175
	v_bfe_u32 v176, v175, 16, 1
	v_add3_u32 v175, v175, v176, s10
	ds_write_b16_d16_hi v83, v175 offset:576
	ds_write_b16_d16_hi v83, v123 offset:5184
	v_lshlrev_b32_e32 v175, 16, v186
	v_max_f32_e32 v175, v175, v175
	v_med3_f32 v175, v175, s9, v244
	v_mul_f32_e32 v175, 0xbfb8aa3b, v175
	v_exp_f32_e32 v175, v175
	s_nop 0
	v_add_f32_e32 v176, 1.0, v175
	v_rcp_f32_e32 v176, v176
	s_nop 0
	v_fma_f32 v178, v80, v176, v149
	v_mul_f32_e32 v170, v170, v178
	v_max_f32_e32 v170, 0xda24260, v170
	v_mul_f32_e32 v175, v175, v176
	v_rcp_f32_e32 v176, v170
	v_mul_f32_e32 v175, v80, v175
	v_mul_f32_e32 v175, v175, v176
	v_bfe_u32 v176, v175, 16, 1
	v_add3_u32 v175, v175, v176, s10
	v_lshlrev_b32_e32 v176, 16, v185
	v_mul_f32_e32 v176, v170, v176
	v_bfe_u32 v178, v176, 16, 1
	v_add3_u32 v176, v176, v178, s10
	ds_write_b16_d16_hi v83, v176 offset:720
	ds_write_b16_d16_hi v83, v175 offset:5328
	v_lshlrev_b32_e32 v176, 16, v184
	v_max_f32_e32 v176, v176, v176
	v_med3_f32 v176, v176, s9, v244
	v_mul_f32_e32 v176, 0xbfb8aa3b, v176
	v_exp_f32_e32 v176, v176
	s_nop 0
	v_add_f32_e32 v178, 1.0, v176
	v_rcp_f32_e32 v178, v178
	s_nop 0
	v_fma_f32 v180, v80, v178, v149
	v_mul_f32_e32 v170, v170, v180
	v_mul_f32_e32 v176, v176, v178
	v_max_f32_e32 v178, 0xda24260, v170
	v_rcp_f32_e32 v170, v178
	v_mul_f32_e32 v176, v80, v176
	v_mul_f32_e32 v170, v176, v170
	v_bfe_u32 v176, v170, 16, 1
	v_add3_u32 v170, v170, v176, s10
	v_lshlrev_b32_e32 v176, 16, v179
	v_mul_f32_e32 v176, v178, v176
	v_bfe_u32 v179, v176, 16, 1
	v_add3_u32 v176, v176, v179, s10
	ds_write_b16_d16_hi v83, v176 offset:864
	ds_write_b16_d16_hi v83, v170 offset:5472
	v_lshlrev_b32_e32 v176, 16, v177
	v_max_f32_e32 v176, v176, v176
	v_med3_f32 v176, v176, s9, v244
	v_mul_f32_e32 v176, 0xbfb8aa3b, v176
	v_exp_f32_e32 v176, v176
	s_nop 0
	v_add_f32_e32 v177, 1.0, v176
	v_rcp_f32_e32 v177, v177
	s_nop 0
	v_fma_f32 v179, v80, v177, v149
	v_mul_f32_e32 v176, v176, v177
	v_mul_f32_e32 v177, v178, v179
	v_max_f32_e32 v177, 0xda24260, v177
	v_rcp_f32_e32 v178, v177
	v_mul_f32_e32 v176, v80, v176
	v_mul_f32_e32 v173, v177, v173
	v_mul_f32_e32 v176, v176, v178
	v_bfe_u32 v178, v176, 16, 1
	v_add3_u32 v176, v176, v178, s10
	v_bfe_u32 v178, v173, 16, 1
	v_add3_u32 v173, v173, v178, s10
	ds_write_b16_d16_hi v83, v173 offset:1008
	ds_write_b16_d16_hi v83, v176 offset:5616
	s_waitcnt vmcnt(31)
	v_lshlrev_b32_e32 v173, 16, v174
	v_max_f32_e32 v173, v173, v173
	v_med3_f32 v173, v173, s9, v244
	v_mul_f32_e32 v173, 0xbfb8aa3b, v173
	v_exp_f32_e32 v173, v173
	s_waitcnt vmcnt(29)
	v_lshlrev_b32_e32 v171, 16, v171
	v_max_f32_e32 v171, v171, v171
	v_med3_f32 v171, v171, s9, v244
	v_add_f32_e32 v174, 1.0, v173
	v_rcp_f32_e32 v174, v174
	v_mul_f32_e32 v171, 0xbfb8aa3b, v171
	v_exp_f32_e32 v178, v171
	v_lshlrev_b32_e32 v172, 16, v172
	v_fma_f32 v171, v80, v174, v149
	v_mul_f32_e32 v171, v177, v171
	v_max_f32_e32 v177, 0xda24260, v171
	v_rcp_f32_e32 v171, v177
	v_mul_f32_e32 v173, v173, v174
	v_mul_f32_e32 v173, v80, v173
	v_mul_f32_e32 v172, v177, v172
	v_mul_f32_e32 v171, v173, v171
	v_bfe_u32 v173, v171, 16, 1
	v_add3_u32 v171, v171, v173, s10
	v_add_f32_e32 v173, 1.0, v178
	v_rcp_f32_e32 v173, v173
	v_bfe_u32 v174, v172, 16, 1
	v_add3_u32 v172, v172, v174, s10
	ds_write_b16_d16_hi v83, v172 offset:1152
	v_fma_f32 v172, v80, v173, v149
	v_mul_f32_e32 v172, v177, v172
	v_max_f32_e32 v174, 0xda24260, v172
	v_rcp_f32_e32 v172, v174
	v_mul_f32_e32 v173, v178, v173
	v_mul_f32_e32 v173, v80, v173
	s_waitcnt vmcnt(28)
	v_lshlrev_b32_e32 v169, 16, v169
	v_mul_f32_e32 v172, v173, v172
	v_bfe_u32 v173, v172, 16, 1
	v_mul_f32_e32 v169, v174, v169
	ds_write_b16_d16_hi v83, v171 offset:5760
	v_add3_u32 v172, v172, v173, s10
	v_bfe_u32 v173, v169, 16, 1
	v_add3_u32 v169, v169, v173, s10
	global_load_ushort v173, v[74:75], off offset:3072
	global_load_ushort v177, v[108:109], off offset:2560
	s_nop 0
	global_load_ushort v78, v[78:79], off offset:3072
	s_nop 0
	global_load_ushort v79, v[76:77], off offset:1024
	global_load_ushort v178, v[84:85], off offset:2048
	s_nop 0
	global_load_ushort v85, v[84:85], off offset:1024
	s_nop 0
	global_load_ushort v76, v[76:77], off
	s_nop 0
	global_load_ushort v77, v[74:75], off offset:2048
	s_waitcnt vmcnt(35)
	v_lshlrev_b32_e32 v74, 16, v166
	v_max_f32_e32 v74, v74, v74
	v_med3_f32 v74, v74, s9, v244
	v_mul_f32_e32 v74, 0xbfb8aa3b, v74
	v_exp_f32_e32 v84, v74
	v_add_co_u32_e32 v74, vcc, s5, v64
	s_waitcnt vmcnt(32)
	v_lshlrev_b32_e32 v158, 16, v158
	v_addc_co_u32_e32 v75, vcc, 0, v65, vcc
	v_add_f32_e32 v166, 1.0, v84
	global_load_ushort v108, v[108:109], off offset:3584
	s_nop 0
	global_load_ushort v109, v[74:75], off
	s_nop 0
	global_load_ushort v110, v[110:111], off offset:512
	s_nop 0
	global_load_ushort v74, v[74:75], off offset:3584
	s_nop 0
	global_load_ushort v75, v[112:113], off offset:1536
	global_load_ushort v111, v[114:115], off offset:2560
	s_nop 0
	global_load_ushort v114, v[114:115], off offset:1536
	s_nop 0
	global_load_ushort v112, v[112:113], off offset:512
	v_rcp_f32_e32 v166, v166
	s_waitcnt vmcnt(37)
	v_lshlrev_b32_e32 v165, 16, v165
	v_max_f32_e32 v165, v165, v165
	v_med3_f32 v165, v165, s9, v244
	v_fma_f32 v113, v80, v166, v149
	v_mul_f32_e32 v113, v174, v113
	v_mul_f32_e32 v84, v84, v166
	v_lshlrev_b32_e32 v166, 16, v167
	v_max_f32_e32 v113, 0xda24260, v113
	v_max_f32_e32 v166, v166, v166
	v_rcp_f32_e32 v115, v113
	v_med3_f32 v166, v166, s9, v244
	v_mul_f32_e32 v166, 0xbfb8aa3b, v166
	v_exp_f32_e32 v166, v166
	v_mul_f32_e32 v84, v80, v84
	v_mul_f32_e32 v84, v84, v115
	v_bfe_u32 v115, v84, 16, 1
	v_add3_u32 v84, v84, v115, s10
	v_lshlrev_b32_e32 v115, 16, v164
	v_add_f32_e32 v164, 1.0, v166
	v_rcp_f32_e32 v164, v164
	v_mul_f32_e32 v115, v113, v115
	v_bfe_u32 v167, v115, 16, 1
	v_add3_u32 v115, v115, v167, s10
	ds_write_b16_d16_hi v83, v115 offset:1440
	v_fma_f32 v115, v80, v164, v149
	v_mul_f32_e32 v113, v113, v115
	v_mul_f32_e32 v164, v166, v164
	v_lshlrev_b32_e32 v166, 16, v168
	v_max_f32_e32 v113, 0xda24260, v113
	v_max_f32_e32 v166, v166, v166
	v_rcp_f32_e32 v115, v113
	v_med3_f32 v166, v166, s9, v244
	v_mul_f32_e32 v166, 0xbfb8aa3b, v166
	v_exp_f32_e32 v166, v166
	v_mul_f32_e32 v164, v80, v164
	v_mul_f32_e32 v115, v164, v115
	v_bfe_u32 v164, v115, 16, 1
	v_add3_u32 v115, v115, v164, s10
	v_add_f32_e32 v164, 1.0, v166
	v_rcp_f32_e32 v164, v164
	v_mul_f32_e32 v158, v113, v158
	v_bfe_u32 v167, v158, 16, 1
	v_add3_u32 v158, v158, v167, s10
	ds_write_b16_d16_hi v83, v158 offset:1584
	v_fma_f32 v158, v80, v164, v149
	v_mul_f32_e32 v113, v113, v158
	v_max_f32_e32 v113, 0xda24260, v113
	v_rcp_f32_e32 v158, v113
	v_mul_f32_e32 v165, 0xbfb8aa3b, v165
	v_mul_f32_e32 v164, v166, v164
	v_exp_f32_e32 v165, v165
	v_mul_f32_e32 v164, v80, v164
	v_mul_f32_e32 v158, v164, v158
	v_bfe_u32 v164, v158, 16, 1
	v_add3_u32 v158, v158, v164, s10
	v_add_f32_e32 v164, 1.0, v165
	v_lshlrev_b32_e32 v163, 16, v163
	v_rcp_f32_e32 v164, v164
	v_mul_f32_e32 v163, v113, v163
	v_bfe_u32 v166, v163, 16, 1
	v_add3_u32 v163, v163, v166, s10
	ds_write_b16_d16_hi v83, v163 offset:1728
	v_fma_f32 v163, v80, v164, v149
	v_mul_f32_e32 v113, v113, v163
	s_waitcnt vmcnt(35)
	v_lshlrev_b32_e32 v162, 16, v162
	v_max_f32_e32 v113, 0xda24260, v113
	v_max_f32_e32 v162, v162, v162
	v_rcp_f32_e32 v163, v113
	v_med3_f32 v162, v162, s9, v244
	v_mul_f32_e32 v162, 0xbfb8aa3b, v162
	v_mul_f32_e32 v164, v165, v164
	v_exp_f32_e32 v162, v162
	v_mul_f32_e32 v164, v80, v164
	v_mul_f32_e32 v163, v164, v163
	v_bfe_u32 v164, v163, 16, 1
	v_add3_u32 v163, v163, v164, s10
	v_add_f32_e32 v164, 1.0, v162
	v_lshlrev_b32_e32 v157, 16, v157
	v_rcp_f32_e32 v164, v164
	v_mul_f32_e32 v157, v113, v157
	v_bfe_u32 v165, v157, 16, 1
	v_add3_u32 v157, v157, v165, s10
	ds_write_b16_d16_hi v83, v157 offset:1872
	v_fma_f32 v157, v80, v164, v149
	v_mul_f32_e32 v113, v113, v157
	s_waitcnt vmcnt(33)
	v_lshlrev_b32_e32 v159, 16, v159
	v_max_f32_e32 v113, 0xda24260, v113
	v_max_f32_e32 v159, v159, v159
	v_rcp_f32_e32 v157, v113
	v_med3_f32 v159, v159, s9, v244
	v_mul_f32_e32 v159, 0xbfb8aa3b, v159
	v_mul_f32_e32 v162, v162, v164
	v_exp_f32_e32 v159, v159
	v_mul_f32_e32 v162, v80, v162
	v_mul_f32_e32 v157, v162, v157
	v_bfe_u32 v162, v157, 16, 1
	v_add3_u32 v157, v157, v162, s10
	v_add_f32_e32 v162, 1.0, v159
	v_lshlrev_b32_e32 v156, 16, v156
	v_rcp_f32_e32 v162, v162
	v_mul_f32_e32 v156, v113, v156
	v_bfe_u32 v164, v156, 16, 1
	v_add3_u32 v156, v156, v164, s10
	ds_write_b16_d16_hi v83, v156 offset:2016
	v_fma_f32 v156, v80, v162, v149
	v_mul_f32_e32 v113, v113, v156
	v_max_f32_e32 v113, 0xda24260, v113
	v_rcp_f32_e32 v156, v113
	v_mul_f32_e32 v159, v159, v162
	v_mul_f32_e32 v159, v80, v159
	s_waitcnt vmcnt(32)
	v_lshlrev_b32_e32 v81, 16, v81
	v_mul_f32_e32 v156, v159, v156
	v_bfe_u32 v159, v156, 16, 1
	v_mul_f32_e32 v81, v113, v81
	v_add3_u32 v159, v156, v159, s10
	v_bfe_u32 v156, v81, 16, 1
	v_add3_u32 v81, v81, v156, s10
	ds_write_b16_d16_hi v83, v169 offset:1296
	ds_write_b16_d16_hi v83, v172 offset:5904
	ds_write_b16_d16_hi v83, v84 offset:6048
	ds_write_b16_d16_hi v83, v115 offset:6192
	ds_write_b16_d16_hi v83, v158 offset:6336
	ds_write_b16_d16_hi v83, v163 offset:6480
	ds_write_b16_d16_hi v83, v157 offset:6624
	ds_write_b16_d16_hi v83, v81 offset:2160
	ds_write_b16_d16_hi v83, v159 offset:6768
	s_waitcnt vmcnt(15)
	v_lshlrev_b32_e32 v81, 16, v173
	v_max_f32_e32 v81, v81, v81
	v_med3_f32 v81, v81, s9, v244
	v_mul_f32_e32 v81, 0xbfb8aa3b, v81
	v_exp_f32_e32 v81, v81
	s_waitcnt vmcnt(7)
	v_lshlrev_b32_e32 v108, 16, v108
	v_max_f32_e32 v108, v108, v108
	v_med3_f32 v108, v108, s9, v244
	v_add_f32_e32 v156, 1.0, v81
	v_rcp_f32_e32 v156, v156
	v_mul_f32_e32 v108, 0xbfb8aa3b, v108
	v_exp_f32_e32 v108, v108
	v_lshlrev_b32_e32 v77, 16, v77
	v_fma_f32 v162, v80, v156, v149
	v_mul_f32_e32 v113, v113, v162
	v_max_f32_e32 v113, 0xda24260, v113
	v_rcp_f32_e32 v162, v113
	v_mul_f32_e32 v81, v81, v156
	v_mul_f32_e32 v81, v80, v81
	v_mul_f32_e32 v77, v113, v77
	v_mul_f32_e32 v81, v81, v162
	v_bfe_u32 v156, v81, 16, 1
	v_add3_u32 v156, v81, v156, s10
	v_add_f32_e32 v81, 1.0, v108
	v_rcp_f32_e32 v81, v81
	v_bfe_u32 v162, v77, 16, 1
	v_add3_u32 v77, v77, v162, s10
	ds_write_b16_d16_hi v83, v77 offset:2304
	v_fma_f32 v77, v80, v81, v149
	ds_write_b16_d16_hi v83, v156 offset:6912
	v_mul_f32_e32 v77, v113, v77
	global_load_ushort v162, v[66:67], off offset:3072
	global_load_ushort v164, v[72:73], off offset:3072
	global_load_ushort v165, v[68:69], off offset:1024
	global_load_ushort v166, v[70:71], off offset:2048
	global_load_ushort v167, v[86:87], off offset:1536
	global_load_ushort v168, v[70:71], off offset:1024
	global_load_ushort v169, v[68:69], off
	global_load_ushort v173, v[66:67], off offset:2048
	s_waitcnt vmcnt(14)
	v_lshlrev_b32_e32 v66, 16, v109
	v_max_f32_e32 v77, 0xda24260, v77
	v_max_f32_e32 v66, v66, v66
	v_rcp_f32_e32 v113, v77
	v_med3_f32 v66, v66, s9, v244
	v_mul_f32_e32 v66, 0xbfb8aa3b, v66
	v_mul_f32_e32 v81, v108, v81
	v_exp_f32_e32 v66, v66
	v_mul_f32_e32 v81, v80, v81
	v_mul_f32_e32 v81, v81, v113
	v_bfe_u32 v108, v81, 16, 1
	v_add_co_u32_e32 v64, vcc, s4, v64
	v_add3_u32 v108, v81, v108, s10
	v_lshlrev_b32_e32 v81, 16, v177
	v_addc_co_u32_e32 v65, vcc, 0, v65, vcc
	v_add_f32_e32 v67, 1.0, v66
	global_load_ushort v174, v[106:107], off offset:3584
	global_load_ushort v177, v[64:65], off
	global_load_ushort v179, v[64:65], off offset:3584
	s_nop 0
	global_load_ushort v106, v[106:107], off offset:2560
	s_nop 0
	global_load_ushort v104, v[104:105], off offset:512
	s_nop 0
	global_load_ushort v180, v[102:103], off offset:1536
	s_nop 0
	global_load_ushort v102, v[102:103], off offset:512
	s_nop 0
	global_load_ushort v86, v[86:87], off offset:2560
	v_rcp_f32_e32 v67, v67
	v_mul_f32_e32 v81, v77, v81
	v_bfe_u32 v113, v81, 16, 1
	v_add3_u32 v81, v81, v113, s10
	v_fma_f32 v64, v80, v67, v149
	v_mul_f32_e32 v64, v77, v64
	v_mul_f32_e32 v66, v66, v67
	s_waitcnt vmcnt(21)
	v_lshlrev_b32_e32 v67, 16, v110
	v_max_f32_e32 v64, 0xda24260, v64
	v_max_f32_e32 v67, v67, v67
	v_rcp_f32_e32 v65, v64
	v_med3_f32 v67, v67, s9, v244
	v_mul_f32_e32 v67, 0xbfb8aa3b, v67
	v_exp_f32_e32 v67, v67
	v_mul_f32_e32 v66, v80, v66
	v_mul_f32_e32 v65, v66, v65
	v_bfe_u32 v66, v65, 16, 1
	v_add3_u32 v181, v65, v66, s10
	v_add_f32_e32 v66, 1.0, v67
	v_lshlrev_b32_e32 v65, 16, v78
	v_rcp_f32_e32 v66, v66
	v_mul_f32_e32 v65, v64, v65
	v_bfe_u32 v68, v65, 16, 1
	v_add3_u32 v65, v65, v68, s10
	ds_write_b16_d16_hi v83, v65 offset:2592
	v_fma_f32 v65, v80, v66, v149
	v_mul_f32_e32 v66, v67, v66
	v_lshlrev_b32_e32 v67, 16, v79
	v_mul_f32_e32 v64, v64, v65
	v_max_f32_e32 v67, v67, v67
	v_max_f32_e32 v64, 0xda24260, v64
	v_med3_f32 v67, v67, s9, v244
	v_rcp_f32_e32 v65, v64
	v_mul_f32_e32 v67, 0xbfb8aa3b, v67
	v_exp_f32_e32 v67, v67
	v_mul_f32_e32 v66, v80, v66
	v_mul_f32_e32 v65, v66, v65
	v_bfe_u32 v66, v65, 16, 1
	v_add_f32_e32 v68, 1.0, v67
	v_add3_u32 v65, v65, v66, s10
	s_waitcnt vmcnt(20)
	v_lshlrev_b32_e32 v66, 16, v74
	v_rcp_f32_e32 v68, v68
	v_mul_f32_e32 v66, v64, v66
	v_bfe_u32 v69, v66, 16, 1
	v_add3_u32 v66, v66, v69, s10
	ds_write_b16_d16_hi v83, v66 offset:2736
	v_fma_f32 v66, v80, v68, v149
	v_mul_f32_e32 v64, v64, v66
	v_mul_f32_e32 v67, v67, v68
	s_waitcnt vmcnt(19)
	v_lshlrev_b32_e32 v68, 16, v75
	v_max_f32_e32 v64, 0xda24260, v64
	v_max_f32_e32 v68, v68, v68
	v_rcp_f32_e32 v66, v64
	v_med3_f32 v68, v68, s9, v244
	v_mul_f32_e32 v68, 0xbfb8aa3b, v68
	v_exp_f32_e32 v68, v68
	v_mul_f32_e32 v67, v80, v67
	v_mul_f32_e32 v66, v67, v66
	v_bfe_u32 v67, v66, 16, 1
	v_add3_u32 v182, v66, v67, s10
	v_add_f32_e32 v67, 1.0, v68
	v_lshlrev_b32_e32 v66, 16, v76
	v_rcp_f32_e32 v67, v67
	v_mul_f32_e32 v66, v64, v66
	v_bfe_u32 v69, v66, 16, 1
	v_add3_u32 v66, v66, v69, s10
	ds_write_b16_d16_hi v83, v66 offset:2880
	v_fma_f32 v66, v80, v67, v149
	v_mul_f32_e32 v67, v68, v67
	v_lshlrev_b32_e32 v68, 16, v178
	v_mul_f32_e32 v64, v64, v66
	v_max_f32_e32 v68, v68, v68
	v_max_f32_e32 v64, 0xda24260, v64
	v_med3_f32 v68, v68, s9, v244
	v_rcp_f32_e32 v66, v64
	v_mul_f32_e32 v68, 0xbfb8aa3b, v68
	v_exp_f32_e32 v68, v68
	v_mul_f32_e32 v67, v80, v67
	v_mul_f32_e32 v66, v67, v66
	v_bfe_u32 v67, v66, 16, 1
	v_add_f32_e32 v69, 1.0, v68
	v_add3_u32 v66, v66, v67, s10
	s_waitcnt vmcnt(16)
	v_lshlrev_b32_e32 v67, 16, v112
	v_rcp_f32_e32 v69, v69
	v_mul_f32_e32 v67, v64, v67
	v_bfe_u32 v70, v67, 16, 1
	v_add3_u32 v67, v67, v70, s10
	ds_write_b16_d16_hi v83, v67 offset:3024
	v_fma_f32 v67, v80, v69, v149
	v_mul_f32_e32 v64, v64, v67
	v_mul_f32_e32 v68, v68, v69
	v_lshlrev_b32_e32 v69, 16, v111
	v_max_f32_e32 v64, 0xda24260, v64
	v_max_f32_e32 v69, v69, v69
	v_rcp_f32_e32 v67, v64
	v_med3_f32 v69, v69, s9, v244
	v_mul_f32_e32 v69, 0xbfb8aa3b, v69
	v_exp_f32_e32 v69, v69
	v_mul_f32_e32 v68, v80, v68
	v_mul_f32_e32 v67, v68, v67
	v_bfe_u32 v68, v67, 16, 1
	v_add3_u32 v178, v67, v68, s10
	v_add_f32_e32 v68, 1.0, v69
	v_lshlrev_b32_e32 v67, 16, v85
	v_rcp_f32_e32 v68, v68
	v_mul_f32_e32 v67, v64, v67
	v_bfe_u32 v70, v67, 16, 1
	v_add3_u32 v67, v67, v70, s10
	ds_write_b16_d16_hi v83, v67 offset:3168
	v_fma_f32 v67, v80, v68, v149
	v_mul_f32_e32 v64, v64, v67
	v_max_f32_e32 v76, 0xda24260, v64
	v_rcp_f32_e32 v64, v76
	v_mul_f32_e32 v67, v69, v68
	v_mul_f32_e32 v67, v80, v67
	ds_write_b16_d16_hi v83, v81 offset:2448
	v_mul_f32_e32 v64, v67, v64
	v_bfe_u32 v67, v64, 16, 1
	v_add3_u32 v64, v64, v67, s10
	v_lshlrev_b32_e32 v67, 16, v114
	v_mul_f32_e32 v67, v76, v67
	v_bfe_u32 v68, v67, 16, 1
	v_add3_u32 v67, v67, v68, s10
	ds_write_b16_d16_hi v83, v108 offset:7056
	ds_write_b16_d16_hi v83, v181 offset:7200
	ds_write_b16_d16_hi v83, v65 offset:7344
	ds_write_b16_d16_hi v83, v182 offset:7488
	ds_write_b16_d16_hi v83, v66 offset:7632
	ds_write_b16_d16_hi v83, v178 offset:7776
	ds_write_b16_d16_hi v83, v67 offset:3312
	ds_write_b16_d16_hi v83, v64 offset:7920
	s_waitcnt vmcnt(15)
	v_lshlrev_b32_e32 v72, 16, v162
	v_max_f32_e32 v72, v72, v72
	v_med3_f32 v72, v72, s9, v244
	v_mul_f32_e32 v72, 0xbfb8aa3b, v72
	v_and_b32_e32 v103, 0xffff0000, v108
	v_exp_f32_e32 v108, v72
	v_lshl_or_b32 v78, v120, 16, v127
	s_waitcnt vmcnt(4)
	v_lshlrev_b32_e32 v106, 16, v106
	s_waitcnt vmcnt(3)
	v_lshlrev_b32_e32 v104, 16, v104
	v_add_f32_e32 v77, 1.0, v108
	v_rcp_f32_e32 v110, v77
	v_max_f32_e32 v104, v104, v104
	v_med3_f32 v104, v104, s9, v244
	v_mul_f32_e32 v104, 0xbfb8aa3b, v104
	v_fma_f32 v112, v80, v110, v149
	v_mul_f32_e32 v76, v76, v112
	v_max_f32_e32 v112, 0xda24260, v76
	v_lshl_or_b32 v76, v121, 16, v88
	v_mul_f32_e32 v88, v108, v110
	v_lshlrev_b32_e32 v110, 16, v174
	v_max_f32_e32 v110, v110, v110
	v_rcp_f32_e32 v114, v112
	v_med3_f32 v110, v110, s9, v244
	v_mul_f32_e32 v110, 0xbfb8aa3b, v110
	v_exp_f32_e32 v110, v110
	v_mul_f32_e32 v88, v80, v88
	v_mul_f32_e32 v88, v88, v114
	v_bfe_u32 v108, v88, 16, 1
	v_add3_u32 v120, v88, v108, s10
	v_add_f32_e32 v108, 1.0, v110
	v_lshlrev_b32_e32 v88, 16, v173
	v_rcp_f32_e32 v108, v108
	v_mul_f32_e32 v88, v112, v88
	v_bfe_u32 v114, v88, 16, 1
	v_add3_u32 v88, v88, v114, s10
	ds_write_b16_d16_hi v83, v88 offset:3456
	v_fma_f32 v88, v80, v108, v149
	v_mul_f32_e32 v88, v112, v88
	v_max_f32_e32 v88, 0xda24260, v88
	v_rcp_f32_e32 v112, v88
	v_mul_f32_e32 v108, v110, v108
	v_mul_f32_e32 v108, v80, v108
	v_mul_f32_e32 v106, v88, v106
	v_mul_f32_e32 v108, v108, v112
	v_bfe_u32 v110, v108, 16, 1
	v_add3_u32 v108, v108, v110, s10
	v_lshlrev_b32_e32 v110, 16, v177
	v_max_f32_e32 v110, v110, v110
	v_med3_f32 v110, v110, s9, v244
	v_mul_f32_e32 v110, 0xbfb8aa3b, v110
	v_exp_f32_e32 v110, v110
	v_bfe_u32 v114, v106, 16, 1
	v_add3_u32 v106, v106, v114, s10
	ds_write_b16_d16_hi v83, v106 offset:3600
	v_add_f32_e32 v112, 1.0, v110
	v_rcp_f32_e32 v112, v112
	v_and_b32_e32 v121, 0xffff0000, v108
	ds_write_b16_d16_hi v83, v108 offset:8208
	v_exp_f32_e32 v104, v104
	v_fma_f32 v106, v80, v112, v149
	v_mul_f32_e32 v88, v88, v106
	v_max_f32_e32 v88, 0xda24260, v88
	v_rcp_f32_e32 v106, v88
	v_mul_f32_e32 v108, v110, v112
	v_mul_f32_e32 v108, v80, v108
	v_lshl_or_b32 v79, v122, 16, v128
	v_mul_f32_e32 v106, v108, v106
	v_bfe_u32 v108, v106, 16, 1
	v_add3_u32 v122, v106, v108, s10
	v_add_f32_e32 v108, 1.0, v104
	v_lshlrev_b32_e32 v106, 16, v164
	v_rcp_f32_e32 v108, v108
	v_mul_f32_e32 v106, v88, v106
	v_bfe_u32 v110, v106, 16, 1
	v_add3_u32 v106, v106, v110, s10
	ds_write_b16_d16_hi v83, v106 offset:3744
	v_fma_f32 v106, v80, v108, v149
	v_mul_f32_e32 v88, v88, v106
	v_max_f32_e32 v88, 0xda24260, v88
	v_rcp_f32_e32 v106, v88
	v_mul_f32_e32 v104, v104, v108
	v_mul_f32_e32 v104, v80, v104
	v_lshlrev_b32_e32 v108, 16, v179
	v_mul_f32_e32 v104, v104, v106
	v_bfe_u32 v106, v104, 16, 1
	v_add3_u32 v104, v104, v106, s10
	v_lshlrev_b32_e32 v106, 16, v165
	v_max_f32_e32 v106, v106, v106
	v_med3_f32 v106, v106, s9, v244
	v_mul_f32_e32 v106, 0xbfb8aa3b, v106
	v_exp_f32_e32 v106, v106
	v_mul_f32_e32 v108, v88, v108
	v_bfe_u32 v112, v108, 16, 1
	v_add3_u32 v108, v108, v112, s10
	v_add_f32_e32 v110, 1.0, v106
	v_rcp_f32_e32 v110, v110
	ds_write_b16_d16_hi v83, v108 offset:3888
	v_lshl_or_b32 v74, v144, 16, v131
	v_and_b32_e32 v131, 0xffff0000, v104
	v_fma_f32 v108, v80, v110, v149
	v_mul_f32_e32 v88, v88, v108
	v_max_f32_e32 v88, 0xda24260, v88
	v_rcp_f32_e32 v108, v88
	ds_write_b16_d16_hi v83, v104 offset:8496
	v_mul_f32_e32 v104, v106, v110
	v_mul_f32_e32 v104, v80, v104
	v_mul_f32_e32 v104, v104, v108
	s_waitcnt vmcnt(2)
	v_lshlrev_b32_e32 v108, 16, v180
	v_max_f32_e32 v108, v108, v108
	v_med3_f32 v108, v108, s9, v244
	v_mul_f32_e32 v108, 0xbfb8aa3b, v108
	v_exp_f32_e32 v108, v108
	v_bfe_u32 v106, v104, 16, 1
	v_lshl_or_b32 v75, v153, 16, v132
	v_add3_u32 v132, v104, v106, s10
	v_add_f32_e32 v106, 1.0, v108
	v_lshlrev_b32_e32 v104, 16, v169
	v_rcp_f32_e32 v106, v106
	v_mul_f32_e32 v104, v88, v104
	v_bfe_u32 v110, v104, 16, 1
	v_add3_u32 v104, v104, v110, s10
	ds_write_b16_d16_hi v83, v104 offset:4032
	v_fma_f32 v104, v80, v106, v149
	v_mul_f32_e32 v88, v88, v104
	v_max_f32_e32 v88, 0xda24260, v88
	v_rcp_f32_e32 v104, v88
	v_mul_f32_e32 v106, v108, v106
	v_mul_f32_e32 v106, v80, v106
	s_waitcnt vmcnt(1)
	v_lshlrev_b32_e32 v102, 16, v102
	v_mul_f32_e32 v104, v106, v104
	v_bfe_u32 v106, v104, 16, 1
	v_add3_u32 v104, v104, v106, s10
	v_lshlrev_b32_e32 v106, 16, v166
	v_max_f32_e32 v106, v106, v106
	v_med3_f32 v106, v106, s9, v244
	v_mul_f32_e32 v106, 0xbfb8aa3b, v106
	v_exp_f32_e32 v106, v106
	v_mul_f32_e32 v102, v88, v102
	v_bfe_u32 v110, v102, 16, 1
	v_add3_u32 v102, v102, v110, s10
	v_add_f32_e32 v108, 1.0, v106
	v_rcp_f32_e32 v108, v108
	ds_write_b16_d16_hi v83, v102 offset:4176
	s_waitcnt vmcnt(0)
	v_lshlrev_b32_e32 v86, 16, v86
	v_max_f32_e32 v86, v86, v86
	v_fma_f32 v102, v80, v108, v149
	v_mul_f32_e32 v88, v88, v102
	v_max_f32_e32 v88, 0xda24260, v88
	v_rcp_f32_e32 v102, v88
	v_med3_f32 v86, v86, s9, v244
	v_mul_f32_e32 v86, 0xbfb8aa3b, v86
	v_lshl_or_b32 v69, v151, 16, v135
	v_and_b32_e32 v135, 0xffff0000, v104
	ds_write_b16_d16_hi v83, v104 offset:8784
	v_mul_f32_e32 v104, v106, v108
	v_exp_f32_e32 v86, v86
	v_mul_f32_e32 v104, v80, v104
	v_mul_f32_e32 v102, v104, v102
	v_bfe_u32 v104, v102, 16, 1
	v_lshl_or_b32 v70, v150, 16, v136
	v_add3_u32 v136, v102, v104, s10
	v_add_f32_e32 v104, 1.0, v86
	v_rcp_f32_e32 v104, v104
	v_lshlrev_b32_e32 v102, 16, v168
	v_mul_f32_e32 v102, v88, v102
	v_bfe_u32 v106, v102, 16, 1
	v_fmac_f32_e32 v149, v80, v104
	v_mul_f32_e32 v88, v88, v149
	v_add3_u32 v102, v102, v106, s10
	v_max_f32_e32 v88, 0xda24260, v88
	ds_write_b16_d16_hi v83, v102 offset:4320
	v_rcp_f32_e32 v102, v88
	v_mul_f32_e32 v86, v86, v104
	v_mul_f32_e32 v80, v80, v86
	v_and_b32_e32 v81, 0xffff0000, v64
	v_mul_f32_e32 v80, v80, v102
	v_bfe_u32 v86, v80, 16, 1
	v_add3_u32 v80, v80, v86, s10
	v_lshlrev_b32_e32 v86, 16, v167
	v_mul_f32_e32 v86, v88, v86
	v_bfe_u32 v102, v86, 16, 1
	v_add3_u32 v86, v86, v102, s10
	v_and_b32_e32 v85, 0xffff0000, v66
	v_and_b32_e32 v87, 0xffff0000, v65
	v_and_b32_e32 v105, 0xffff0000, v159
	v_and_b32_e32 v107, 0xffff0000, v163
	v_and_b32_e32 v109, 0xffff0000, v115
	v_and_b32_e32 v111, 0xffff0000, v172
	v_and_b32_e32 v113, 0xffff0000, v176
	v_and_b32_e32 v115, 0xffff0000, v175
	v_and_b32_e32 v117, 0xffff0000, v117
	v_and_b32_e32 v119, 0xffff0000, v119
	v_lshl_or_b32 v67, v142, 16, v141
	v_lshl_or_b32 v66, v143, 16, v140
	v_lshl_or_b32 v65, v145, 16, v139
	v_lshl_or_b32 v64, v146, 16, v138
	v_lshl_or_b32 v71, v147, 16, v137
	v_lshl_or_b32 v68, v152, 16, v134
	v_lshl_or_b32 v73, v154, 16, v130
	v_lshl_or_b32 v72, v155, 16, v129
	v_lshl_or_b32 v77, v118, 16, v126
	ds_write_b16_d16_hi v83, v120 offset:8064
	ds_write_b16_d16_hi v83, v122 offset:8352
	ds_write_b16_d16_hi v83, v132 offset:8640
	ds_write_b16_d16_hi v83, v136 offset:8928
	v_and_b32_e32 v137, 0xffff0000, v80
	ds_write_b16_d16_hi v83, v86 offset:4464
	ds_write_b16_d16_hi v83, v80 offset:9072
	v_and_b32_e32 v112, 0xffff0000, v170
	v_and_b32_e32 v104, 0xffff0000, v157
	v_and_b32_e32 v80, 0xffff0000, v178
	v_pk_mul_f32 v[112:113], v[88:89], v[112:113] op_sel_hi:[0,1]
	v_and_b32_e32 v108, 0xffff0000, v84
	v_pk_mul_f32 v[104:105], v[88:89], v[104:105] op_sel_hi:[0,1]
	v_and_b32_e32 v84, 0xffff0000, v182
	v_pk_mul_f32 v[80:81], v[88:89], v[80:81] op_sel_hi:[0,1]
	v_and_b32_e32 v120, 0xffff0000, v120
	v_cvt_pk_bf16_f32 v129, v112, v113
	v_cvt_pk_bf16_f32 v113, v104, v105
	v_pk_mul_f32 v[84:85], v[88:89], v[84:85] op_sel_hi:[0,1]
	v_cvt_pk_bf16_f32 v105, v80, v81
	v_pk_mul_f32 v[80:81], v[88:89], v[120:121] op_sel_hi:[0,1]
	v_and_b32_e32 v130, 0xffff0000, v122
	v_and_b32_e32 v102, 0xffff0000, v156
	v_and_b32_e32 v86, 0xffff0000, v181
	v_cvt_pk_bf16_f32 v104, v84, v85
	v_cvt_pk_bf16_f32 v84, v80, v81
	v_pk_mul_f32 v[80:81], v[88:89], v[130:131] op_sel_hi:[0,1]
	v_and_b32_e32 v134, 0xffff0000, v132
	v_and_b32_e32 v118, 0xffff0000, v133
	v_and_b32_e32 v116, 0xffff0000, v116
	v_and_b32_e32 v114, 0xffff0000, v123
	v_and_b32_e32 v110, 0xffff0000, v171
	v_and_b32_e32 v106, 0xffff0000, v158
	v_pk_mul_f32 v[102:103], v[88:89], v[102:103] op_sel_hi:[0,1]
	v_pk_mul_f32 v[86:87], v[88:89], v[86:87] op_sel_hi:[0,1]
	v_cvt_pk_bf16_f32 v85, v80, v81
	v_pk_mul_f32 v[80:81], v[88:89], v[134:135] op_sel_hi:[0,1]
	v_and_b32_e32 v136, 0xffff0000, v136
	s_movk_i32 s0, 0x50
	v_pk_mul_f32 v[118:119], v[88:89], v[118:119] op_sel_hi:[0,1]
	v_pk_mul_f32 v[116:117], v[88:89], v[116:117] op_sel_hi:[0,1]
	v_pk_mul_f32 v[114:115], v[88:89], v[114:115] op_sel_hi:[0,1]
	v_pk_mul_f32 v[110:111], v[88:89], v[110:111] op_sel_hi:[0,1]
	v_pk_mul_f32 v[108:109], v[88:89], v[108:109] op_sel_hi:[0,1]
	v_pk_mul_f32 v[106:107], v[88:89], v[106:107] op_sel_hi:[0,1]
	v_cvt_pk_bf16_f32 v102, v102, v103
	v_cvt_pk_bf16_f32 v103, v86, v87
	v_cvt_pk_bf16_f32 v86, v80, v81
	v_pk_mul_f32 v[80:81], v[88:89], v[136:137] op_sel_hi:[0,1]
	v_mad_u64_u32 v[138:139], s[2:3], v82, s0, v[92:93]
	v_cvt_pk_bf16_f32 v126, v118, v119
	v_cvt_pk_bf16_f32 v127, v116, v117
	v_cvt_pk_bf16_f32 v128, v114, v115
	v_cvt_pk_bf16_f32 v110, v110, v111
	v_cvt_pk_bf16_f32 v111, v108, v109
	v_cvt_pk_bf16_f32 v112, v106, v107
	v_cvt_pk_bf16_f32 v87, v80, v81
	v_lshl_add_u32 v80, v82, 2, v92
	ds_write_b128 v138, v[126:129] offset:9216
	ds_write_b128 v138, v[110:113] offset:9232
	ds_write_b128 v138, v[102:105] offset:9248
	ds_write_b128 v138, v[84:87] offset:9264
	ds_write_b32 v80, v88 offset:19456
	ds_write_b128 v138, v[76:79] offset:14336
	ds_write_b128 v138, v[72:75] offset:14352
	ds_write_b128 v138, v[68:71] offset:14368
	ds_write_b128 v138, v[64:67] offset:14384
	s_waitcnt lgkmcnt(0)
	v_or_b32_e32 v88, v95, v124
	v_lshlrev_b64 v[64:65], 11, v[88:89]
	v_lshl_add_u64 v[64:65], s[16:17], 0, v[64:65]
	v_lshlrev_b32_e32 v80, 2, v125
	s_movk_i32 s48, 0x90
	v_lshl_add_u64 v[64:65], v[64:65], 0, v[90:91]
	v_ashrrev_i32_e32 v81, 31, v80
	v_mad_u32_u24 v88, v124, s48, v92
	v_lshl_add_u64 v[104:105], v[80:81], 1, v[64:65]
	v_lshl_add_u32 v81, v125, 4, v88
	ds_read_b128 v[64:67], v81 offset:4608
	ds_read_b128 v[68:71], v81
	ds_read_b128 v[82:85], v81 offset:32
	ds_read_b128 v[106:109], v81 offset:4640
	s_waitcnt lgkmcnt(2)
	v_mfma_f32_32x32x16_bf16 v[64:79], v[64:67], v[68:71], 0
	v_cmp_le_i32_e32 vcc, v80, v124
	v_cvt_pk_bf16_f32 v32, v32, v33
	v_cvt_pk_bf16_f32 v33, v34, v35
	v_cvt_pk_bf16_f32 v34, v36, v37
	v_cvt_pk_bf16_f32 v35, v38, v39
	v_cvt_pk_bf16_f32 v36, v48, v49
	v_cvt_pk_bf16_f32 v37, v50, v51
	s_waitcnt lgkmcnt(0)
	v_mfma_f32_32x32x16_bf16 v[64:79], v[106:109], v[82:85], v[64:79]
	ds_read_b128 v[82:85], v81 offset:4672
	ds_read_b128 v[106:109], v81 offset:64
	v_cvt_pk_bf16_f32 v38, v52, v53
	v_cvt_pk_bf16_f32 v39, v54, v55
	s_mov_b32 s6, 0x16f00000
	s_mov_b64 s[4:5], 0x16f00600
	v_lshl_add_u64 v[102:103], v[104:105], 0, s[4:5]
	s_waitcnt lgkmcnt(0)
	v_mfma_f32_32x32x16_bf16 v[64:79], v[82:85], v[106:109], v[64:79]
	ds_read_b128 v[82:85], v81 offset:4704
	ds_read_b128 v[106:109], v81 offset:96
	v_or_b32_e32 v81, 2, v80
	s_waitcnt lgkmcnt(0)
	v_mfma_f32_32x32x16_bf16 v[64:79], v[82:85], v[106:109], v[64:79]
	s_nop 11
	v_cndmask_b32_e32 v64, 0, v64, vcc
	v_cmp_lt_i32_e32 vcc, v80, v124
	s_nop 1
	v_cndmask_b32_e32 v65, 0, v65, vcc
	v_cmp_le_i32_e32 vcc, v81, v124
	v_or_b32_e32 v81, 3, v80
	v_cvt_pk_bf16_f32 v84, v64, v65
	v_cndmask_b32_e32 v66, 0, v66, vcc
	v_cmp_le_i32_e32 vcc, v81, v124
	v_add_u32_e32 v81, 8, v80
	v_lshlrev_b32_e32 v64, 3, v125
	v_cndmask_b32_e32 v67, 0, v67, vcc
	v_cmp_le_i32_e32 vcc, v81, v124
	v_add_u32_e32 v81, 9, v80
	v_mul_u32_u24_e32 v65, 0x50, v124
	v_cndmask_b32_e32 v68, 0, v68, vcc
	v_cmp_le_i32_e32 vcc, v81, v124
	v_add_u32_e32 v81, 10, v80
	v_add3_u32 v114, v92, v64, v65
	v_cndmask_b32_e32 v69, 0, v69, vcc
	v_cmp_le_i32_e32 vcc, v81, v124
	v_add_u32_e32 v81, 11, v80
	v_cvt_pk_bf16_f32 v86, v68, v69
	v_cndmask_b32_e32 v70, 0, v70, vcc
	v_cmp_le_i32_e32 vcc, v81, v124
	v_add_u32_e32 v81, 16, v80
	v_add_u32_e32 v68, 0x3800, v114
	v_cndmask_b32_e32 v71, 0, v71, vcc
	v_cmp_le_i32_e32 vcc, v81, v124
	v_add_u32_e32 v81, 17, v80
	v_cvt_pk_bf16_f32 v85, v66, v67
	v_cndmask_b32_e32 v72, 0, v72, vcc
	v_cmp_le_i32_e32 vcc, v81, v124
	v_add_u32_e32 v81, 18, v80
	v_add_u32_e32 v88, v88, v64
	v_cndmask_b32_e32 v73, 0, v73, vcc
	v_cmp_le_i32_e32 vcc, v81, v124
	v_add_u32_e32 v81, 19, v80
	ds_read2_b64 v[64:67], v68 offset1:2
	ds_read2_b64 v[106:109], v68 offset0:4 offset1:6
	v_cndmask_b32_e32 v74, 0, v74, vcc
	v_cmp_le_i32_e32 vcc, v81, v124
	v_add_u32_e32 v81, 24, v80
	v_cvt_pk_bf16_f32 v87, v70, v71
	v_cndmask_b32_e32 v75, 0, v75, vcc
	v_cmp_le_i32_e32 vcc, v81, v124
	v_add_u32_e32 v81, 25, v80
	s_nop 0
	v_cndmask_b32_e32 v76, 0, v76, vcc
	v_cmp_le_i32_e32 vcc, v81, v124
	v_add_u32_e32 v81, 26, v80
	v_add_u32_e32 v80, 27, v80
	v_cndmask_b32_e32 v77, 0, v77, vcc
	v_cmp_le_i32_e32 vcc, v81, v124
	v_cvt_pk_bf16_f32 v81, v74, v75
	v_cvt_pk_bf16_f32 v82, v76, v77
	v_cndmask_b32_e32 v78, 0, v78, vcc
	v_cmp_le_i32_e32 vcc, v80, v124
	v_cvt_pk_bf16_f32 v80, v72, v73
	s_nop 0
	v_cndmask_b32_e32 v79, 0, v79, vcc
	v_cvt_pk_bf16_f32 v83, v78, v79
	s_waitcnt lgkmcnt(1)
	v_mfma_f32_32x32x16_bf16 v[64:79], v[64:67], v[84:87], 0
	s_waitcnt lgkmcnt(0)
	v_mfma_f32_32x32x16_bf16 v[64:79], v[106:109], v[80:83], v[64:79]
	ds_read2_b64 v[106:109], v88 offset1:2
	ds_read2_b64 v[110:113], v88 offset0:4 offset1:6
	s_waitcnt lgkmcnt(1)
	v_mfma_f32_32x32x16_bf16 v[64:79], v[32:35], v[106:109], v[64:79]
	v_cvt_pk_bf16_f32 v32, v40, v41
	v_cvt_pk_bf16_f32 v33, v42, v43
	v_cvt_pk_bf16_f32 v34, v44, v45
	v_cvt_pk_bf16_f32 v35, v46, v47
	s_waitcnt lgkmcnt(0)
	s_nop 0
	v_mfma_f32_32x32x16_bf16 v[64:79], v[32:35], v[110:113], v[64:79]
	ds_read2_b64 v[32:35], v88 offset0:8 offset1:10
	s_waitcnt lgkmcnt(0)
	v_mfma_f32_32x32x16_bf16 v[64:79], v[36:39], v[32:35], v[64:79]
	ds_read2_b64 v[32:35], v88 offset0:12 offset1:14
	v_cvt_pk_bf16_f32 v36, v56, v57
	v_cvt_pk_bf16_f32 v37, v58, v59
	v_cvt_pk_bf16_f32 v38, v60, v61
	v_cvt_pk_bf16_f32 v39, v62, v63
	s_waitcnt lgkmcnt(0)
	s_nop 0
	v_mfma_f32_32x32x16_bf16 v[64:79], v[36:39], v[32:35], v[64:79]
	v_add_co_u32_e32 v34, vcc, s6, v104
	s_nop 1
	v_addc_co_u32_e32 v35, vcc, 0, v105, vcc
	s_nop 7
	v_cvt_pk_bf16_f32 v32, v64, v65
	v_cvt_pk_bf16_f32 v33, v66, v67
	global_store_dwordx2 v[34:35], v[32:33], off offset:1536
	v_cvt_pk_bf16_f32 v32, v68, v69
	v_cvt_pk_bf16_f32 v33, v70, v71
	global_store_dwordx2 v[102:103], v[32:33], off offset:16
	v_cvt_pk_bf16_f32 v32, v72, v73
	v_cvt_pk_bf16_f32 v33, v74, v75
	global_store_dwordx2 v[102:103], v[32:33], off offset:32
	v_cvt_pk_bf16_f32 v32, v76, v77
	v_cvt_pk_bf16_f32 v33, v78, v79
	global_store_dwordx2 v[102:103], v[32:33], off offset:48
	v_add_u32_e32 v48, 0x4000, v114
	ds_read2_b64 v[32:35], v48 offset0:64 offset1:66
	ds_read2_b64 v[48:51], v48 offset0:68 offset1:70
	ds_read2_b64 v[52:55], v88 offset1:2
	v_cvt_pk_bf16_f32 v0, v0, v1
	v_cvt_pk_bf16_f32 v1, v2, v3
	v_cvt_pk_bf16_f32 v2, v4, v5
	v_cvt_pk_bf16_f32 v3, v6, v7
	ds_read2_b64 v[4:7], v88 offset0:4 offset1:6
	v_cvt_pk_bf16_f32 v8, v8, v9
	v_cvt_pk_bf16_f32 v9, v10, v11
	s_waitcnt lgkmcnt(3)
	v_mfma_f32_32x32x16_bf16 v[32:47], v[32:35], v[84:87], 0
	v_cvt_pk_bf16_f32 v10, v12, v13
	v_cvt_pk_bf16_f32 v11, v14, v15
	v_cvt_pk_bf16_f32 v12, v16, v17
	v_cvt_pk_bf16_f32 v13, v18, v19
	v_cvt_pk_bf16_f32 v14, v20, v21
	v_cvt_pk_bf16_f32 v15, v22, v23
	s_waitcnt lgkmcnt(2)
	v_mfma_f32_32x32x16_bf16 v[32:47], v[48:51], v[80:83], v[32:47]
	s_waitcnt lgkmcnt(1)
	v_mfma_f32_32x32x16_bf16 v[32:47], v[0:3], v[52:55], v[32:47]
	ds_read2_b64 v[0:3], v88 offset0:8 offset1:10
	s_waitcnt lgkmcnt(1)
	v_mfma_f32_32x32x16_bf16 v[32:47], v[8:11], v[4:7], v[32:47]
	ds_read2_b64 v[4:7], v88 offset0:12 offset1:14
	v_cvt_pk_bf16_f32 v8, v24, v25
	v_cvt_pk_bf16_f32 v9, v26, v27
	v_cvt_pk_bf16_f32 v10, v28, v29
	v_cvt_pk_bf16_f32 v11, v30, v31
	s_waitcnt lgkmcnt(1)
	v_mfma_f32_32x32x16_bf16 v[32:47], v[12:15], v[0:3], v[32:47]
	s_waitcnt lgkmcnt(0)
	v_mfma_f32_32x32x16_bf16 v[32:47], v[8:11], v[4:7], v[32:47]
	s_nop 11
	v_cvt_pk_bf16_f32 v0, v32, v33
	v_cvt_pk_bf16_f32 v1, v34, v35
	v_cvt_pk_bf16_f32 v2, v36, v37
	v_cvt_pk_bf16_f32 v3, v38, v39
	v_cvt_pk_bf16_f32 v4, v40, v41
	v_cvt_pk_bf16_f32 v5, v42, v43
	v_cvt_pk_bf16_f32 v6, v44, v45
	v_cvt_pk_bf16_f32 v7, v46, v47
	global_store_dwordx2 v[102:103], v[0:1], off offset:64
	global_store_dwordx2 v[102:103], v[2:3], off offset:80
	global_store_dwordx2 v[102:103], v[4:5], off offset:96
	global_store_dwordx2 v[102:103], v[6:7], off offset:112
	s_waitcnt lgkmcnt(0)
	v_lshl_add_u64 v[0:1], s[44:45], 0, v[160:161]
	v_add_co_u32_e32 v2, vcc, s20, v0
	s_movk_i32 s11, 0x3000
	s_nop 0
	v_addc_co_u32_e32 v3, vcc, 0, v1, vcc
	v_add_co_u32_e32 v4, vcc, s11, v0
	s_movk_i32 s7, 0x4000
	s_nop 0
	v_addc_co_u32_e32 v5, vcc, 0, v1, vcc
	v_add_co_u32_e32 v0, vcc, s7, v0
	v_readlane_b32 s0, v255, 22
	s_nop 0
	v_addc_co_u32_e32 v1, vcc, 0, v1, vcc
	global_load_dword v24, v[2:3], off offset:3072
	global_load_dword v25, v[4:5], off offset:1024
	global_load_dword v26, v[4:5], off offset:3072
	global_load_dword v27, v[0:1], off offset:1024
	v_or_b32_e32 v0, 1, v148
	v_mad_i64_i32 v[0:1], s[2:3], v0, 36, v[96:97]
	v_lshlrev_b64 v[0:1], 13, v[0:1]
	v_readlane_b32 s1, v255, 23
	v_readlane_b32 s2, v255, 1
	v_readlane_b32 s3, v255, 2
	v_lshl_add_u64 v[0:1], s[0:1], 0, v[0:1]
	v_lshl_add_u64 v[0:1], v[0:1], 0, v[98:99]
	v_lshl_add_u64 v[0:1], v[0:1], 0, v[100:101]
	global_load_dwordx2 v[2:3], v[0:1], off
	global_load_dwordx2 v[4:5], v[0:1], off offset:16
	global_load_dwordx2 v[6:7], v[0:1], off offset:32
	global_load_dwordx2 v[8:9], v[0:1], off offset:48
	s_movk_i32 s0, 0x1000
	v_add_co_u32_e32 v10, vcc, s0, v0
	s_mov_b32 s1, 0xf149f2ca
	s_nop 0
	v_addc_co_u32_e32 v11, vcc, 0, v1, vcc
	global_load_dwordx2 v[12:13], v[10:11], off
	global_load_dwordx2 v[14:15], v[10:11], off offset:16
	global_load_dwordx2 v[16:17], v[10:11], off offset:32
	global_load_dwordx2 v[18:19], v[10:11], off offset:48
	global_load_dwordx2 v[20:21], v[0:1], off offset:64
	global_load_dwordx2 v[22:23], v[0:1], off offset:80
	global_load_dwordx2 v[58:59], v[0:1], off offset:96
	s_nop 0
	global_load_dwordx2 v[0:1], v[0:1], off offset:112
	s_nop 0
	global_load_dwordx2 v[64:65], v[10:11], off offset:64
	global_load_dwordx2 v[72:73], v[10:11], off offset:80
	global_load_dwordx2 v[76:77], v[10:11], off offset:96
	s_nop 0
	global_load_dwordx2 v[10:11], v[10:11], off offset:112
	s_mov_b64 s[40:41], s[44:45]
	s_mov_b64 s[12:13], s[44:45]
	s_waitcnt vmcnt(18)
	v_max3_f32 v28, v24, s1, v25
	s_waitcnt vmcnt(16)
	v_max3_f32 v28, v28, v26, v27
	v_sub_f32_e32 v25, v25, v28
	v_mul_f32_e32 v25, 0x3fb8aa3b, v25
	v_sub_f32_e32 v24, v24, v28
	v_sub_f32_e32 v26, v26, v28
	v_exp_f32_e32 v25, v25
	v_mul_f32_e32 v24, 0x3fb8aa3b, v24
	v_mul_f32_e32 v26, 0x3fb8aa3b, v26
	v_sub_f32_e32 v27, v27, v28
	v_exp_f32_e32 v50, v24
	v_exp_f32_e32 v51, v26
	v_mul_f32_e32 v27, 0x3fb8aa3b, v27
	v_exp_f32_e32 v52, v27
	s_waitcnt vmcnt(15)
	v_lshlrev_b32_e32 v32, 16, v2
	v_and_b32_e32 v33, 0xffff0000, v2
	v_add_f32_e32 v2, 0, v25
	v_cndmask_b32_e64 v2, v2, 0, s[2:3]
	v_readlane_b32 s2, v255, 3
	v_lshlrev_b32_e32 v34, 16, v3
	v_and_b32_e32 v35, 0xffff0000, v3
	s_waitcnt vmcnt(14)
	v_lshlrev_b32_e32 v36, 16, v4
	v_and_b32_e32 v37, 0xffff0000, v4
	v_add_f32_e32 v3, 0, v50
	v_add_f32_e32 v4, v51, v2
	v_readlane_b32 s3, v255, 4
	v_add_f32_e32 v3, v25, v3
	v_add_f32_e32 v3, v51, v3
	v_cndmask_b32_e64 v2, v4, v2, s[2:3]
	v_readlane_b32 s2, v255, 5
	v_add_f32_e32 v4, v52, v2
	v_readlane_b32 s3, v255, 6
	v_add_f32_e32 v3, v52, v3
	v_lshlrev_b32_e32 v38, 16, v5
	v_cndmask_b32_e64 v2, v4, v2, s[2:3]
	v_div_scale_f32 v4, s[2:3], v3, v3, v2
	v_and_b32_e32 v39, 0xffff0000, v5
	v_rcp_f32_e32 v5, v4
	s_waitcnt vmcnt(13)
	v_lshlrev_b32_e32 v42, 16, v7
	v_and_b32_e32 v43, 0xffff0000, v7
	v_lshlrev_b32_e32 v40, 16, v6
	v_fma_f32 v7, -v4, v5, 1.0
	v_and_b32_e32 v41, 0xffff0000, v6
	v_div_scale_f32 v6, vcc, v2, v3, v2
	v_fmac_f32_e32 v5, v7, v5
	v_mul_f32_e32 v7, v6, v5
	s_waitcnt vmcnt(12)
	v_lshlrev_b32_e32 v44, 16, v8
	v_and_b32_e32 v45, 0xffff0000, v8
	v_fma_f32 v8, -v4, v7, v6
	v_fmac_f32_e32 v7, v8, v5
	v_fma_f32 v4, -v4, v7, v6
	s_waitcnt vmcnt(9)
	v_lshlrev_b32_e32 v24, 16, v16
	v_and_b32_e32 v25, 0xffff0000, v16
	v_div_fmas_f32 v4, v4, v5, v7
	v_mov_b32_e32 v16, v94
	v_div_fixup_f32 v116, v4, v3, v2
	s_add_u32 s2, s40, 0xb200000
	v_lshlrev_b32_e32 v46, 16, v9
	v_and_b32_e32 v47, 0xffff0000, v9
	v_lshlrev_b32_e32 v26, 16, v12
	v_and_b32_e32 v27, 0xffff0000, v12
	v_lshlrev_b32_e32 v28, 16, v13
	v_and_b32_e32 v29, 0xffff0000, v13
	v_lshlrev_b32_e32 v30, 16, v14
	v_and_b32_e32 v31, 0xffff0000, v14
	v_lshlrev_b32_e32 v48, 16, v15
	v_and_b32_e32 v49, 0xffff0000, v15
	v_lshlrev_b32_e32 v84, 16, v17
	v_and_b32_e32 v85, 0xffff0000, v17
	s_waitcnt vmcnt(8)
	v_lshlrev_b32_e32 v86, 16, v18
	v_and_b32_e32 v87, 0xffff0000, v18
	v_lshlrev_b32_e32 v96, 16, v19
	v_and_b32_e32 v97, 0xffff0000, v19
	s_waitcnt vmcnt(7)
	v_lshlrev_b32_e32 v54, 16, v20
	v_and_b32_e32 v55, 0xffff0000, v20
	v_lshlrev_b32_e32 v50, 16, v21
	v_and_b32_e32 v51, 0xffff0000, v21
	s_waitcnt vmcnt(6)
	v_lshlrev_b32_e32 v52, 16, v22
	v_and_b32_e32 v53, 0xffff0000, v22
	v_lshlrev_b32_e32 v82, 16, v23
	v_and_b32_e32 v83, 0xffff0000, v23
	s_waitcnt vmcnt(5)
	v_lshlrev_b32_e32 v56, 16, v58
	v_and_b32_e32 v57, 0xffff0000, v58
	v_lshlrev_b32_e32 v58, 16, v59
	v_and_b32_e32 v59, 0xffff0000, v59
	s_waitcnt vmcnt(4)
	v_lshlrev_b32_e32 v60, 16, v0
	v_and_b32_e32 v61, 0xffff0000, v0
	v_lshlrev_b32_e32 v62, 16, v1
	v_and_b32_e32 v63, 0xffff0000, v1
	s_waitcnt vmcnt(3)
	v_lshlrev_b32_e32 v66, 16, v64
	v_and_b32_e32 v67, 0xffff0000, v64
	v_lshlrev_b32_e32 v68, 16, v65
	v_and_b32_e32 v69, 0xffff0000, v65
	s_waitcnt vmcnt(2)
	v_lshlrev_b32_e32 v70, 16, v72
	v_and_b32_e32 v71, 0xffff0000, v72
	v_lshlrev_b32_e32 v72, 16, v73
	v_and_b32_e32 v73, 0xffff0000, v73
	s_waitcnt vmcnt(1)
	v_lshlrev_b32_e32 v74, 16, v76
	v_and_b32_e32 v75, 0xffff0000, v76
	v_lshlrev_b32_e32 v76, 16, v77
	v_and_b32_e32 v77, 0xffff0000, v77
	s_waitcnt vmcnt(0)
	v_lshlrev_b32_e32 v78, 16, v10
	v_and_b32_e32 v79, 0xffff0000, v10
	v_lshlrev_b32_e32 v80, 16, v11
	v_and_b32_e32 v81, 0xffff0000, v11
	v_sub_f32_e32 v117, 1.0, v116
	v_and_b32_e32 v118, 31, v16
	v_ashrrev_i32_e32 v119, 5, v16
	s_addc_u32 s3, s41, 0
	v_mov_b64_e32 v[64:65], s[2:3]
	s_movk_i32 s1, 0x1200
	v_mad_i64_i32 v[0:1], s[2:3], v95, s1, v[64:65]
	v_ashrrev_i32_e32 v17, 31, v16
	v_lshl_add_u64 v[0:1], v[0:1], 0, v[90:91]
	v_lshl_add_u64 v[0:1], v[16:17], 1, v[0:1]
	s_mov_b32 s37, 0x23000
	v_add_co_u32_e32 v12, vcc, s37, v0
	s_movk_i32 s2, 0x5000
	s_nop 0
	v_addc_co_u32_e32 v13, vcc, 0, v1, vcc
	global_load_ushort v88, v[12:13], off offset:3072
	global_load_ushort v109, v[12:13], off offset:1536
	v_add_co_u32_e32 v2, vcc, s20, v0
	s_mov_b32 s28, 0x9000
	s_nop 0
	v_addc_co_u32_e32 v3, vcc, 0, v1, vcc
	v_add_co_u32_e32 v4, vcc, s2, v0
	s_movk_i32 s2, 0x7000
	s_nop 0
	v_addc_co_u32_e32 v5, vcc, 0, v1, vcc
	v_add_co_u32_e32 v6, vcc, s2, v0
	s_mov_b32 s29, 0xb000
	s_nop 0
	v_addc_co_u32_e32 v7, vcc, 0, v1, vcc
	v_add_co_u32_e32 v18, vcc, s28, v0
	s_mov_b32 s18, 0xe000
	s_nop 0
	v_addc_co_u32_e32 v19, vcc, 0, v1, vcc
	v_add_co_u32_e32 v20, vcc, s29, v0
	s_mov_b32 s2, 0x10000
	s_nop 0
	v_addc_co_u32_e32 v21, vcc, 0, v1, vcc
	v_add_co_u32_e32 v22, vcc, s18, v0
	s_mov_b32 s30, 0x17000
	s_nop 0
	v_addc_co_u32_e32 v23, vcc, 0, v1, vcc
	v_add_co_u32_e32 v98, vcc, s2, v0
	s_mov_b32 s2, 0x14000
	s_nop 0
	v_addc_co_u32_e32 v99, vcc, 0, v1, vcc
	v_add_co_u32_e32 v8, vcc, s51, v0
	s_mov_b32 s31, 0x19000
	s_nop 0
	v_addc_co_u32_e32 v9, vcc, 0, v1, vcc
	v_add_co_u32_e32 v10, vcc, s2, v0
	s_mov_b32 s34, 0x1b000
	s_nop 0
	v_addc_co_u32_e32 v11, vcc, 0, v1, vcc
	v_add_co_u32_e32 v14, vcc, s30, v0
	s_mov_b32 s35, 0x1d000
	s_nop 0
	v_addc_co_u32_e32 v15, vcc, 0, v1, vcc
	v_add_co_u32_e32 v100, vcc, s31, v0
	s_mov_b32 s19, 0x20000
	s_nop 0
	v_addc_co_u32_e32 v101, vcc, 0, v1, vcc
	v_add_co_u32_e32 v102, vcc, s34, v0
	s_mov_b32 s36, 0x22000
	s_nop 0
	v_addc_co_u32_e32 v103, vcc, 0, v1, vcc
	v_add_co_u32_e32 v104, vcc, s35, v0
	s_mov_b32 s21, 0x21000
	s_nop 0
	v_addc_co_u32_e32 v105, vcc, 0, v1, vcc
	v_add_co_u32_e32 v106, vcc, s19, v0
	s_mov_b32 s42, 0x1f000
	s_nop 0
	v_addc_co_u32_e32 v107, vcc, 0, v1, vcc
	v_add_co_u32_e32 v120, vcc, s36, v0
	s_mov_b32 s17, 0x1e000
	s_nop 0
	v_addc_co_u32_e32 v121, vcc, 0, v1, vcc
	v_add_co_u32_e32 v110, vcc, s21, v0
	s_mov_b32 s16, 0x1c000
	s_nop 0
	v_addc_co_u32_e32 v111, vcc, 0, v1, vcc
	global_load_ushort v113, v[110:111], off offset:512
	global_load_ushort v108, v[110:111], off offset:1024
	global_load_ushort v122, v[110:111], off offset:2048
	s_nop 0
	global_load_ushort v110, v[12:13], off offset:2048
	global_load_ushort v112, v[120:121], off offset:1536
	global_load_ushort v145, v[120:121], off offset:2560
	global_load_ushort v123, v[104:105], off offset:3584
	global_load_ushort v124, v[106:107], off offset:512
	global_load_ushort v154, v[120:121], off offset:1024
	global_load_ushort v155, v[106:107], off offset:1536
	global_load_ushort v156, v[106:107], off
	global_load_ushort v159, v[104:105], off offset:3072
	global_load_ushort v162, v[104:105], off
	global_load_ushort v166, v[102:103], off offset:3584
	s_waitcnt vmcnt(15)
	v_lshlrev_b32_e32 v12, 16, v88
	v_max_f32_e32 v12, v12, v12
	v_med3_f32 v12, v12, s9, v244
	v_mul_f32_e32 v12, 0xbfb8aa3b, v12
	v_exp_f32_e32 v88, v12
	v_add_co_u32_e32 v12, vcc, s42, v0
	s_mov_b32 s2, 0x1a000
	v_add_f32_e32 v111, 1.0, v88
	v_addc_co_u32_e32 v13, vcc, 0, v1, vcc
	v_rcp_f32_e32 v111, v111
	v_add_co_u32_e32 v136, vcc, s17, v0
	s_waitcnt vmcnt(14)
	v_lshlrev_b32_e32 v109, 16, v109
	v_addc_co_u32_e32 v137, vcc, 0, v1, vcc
	v_add_co_u32_e32 v134, vcc, s16, v0
	v_fma_f32 v114, v117, v111, v116
	s_nop 0
	v_addc_co_u32_e32 v135, vcc, 0, v1, vcc
	v_max_f32_e32 v152, 0xda24260, v114
	v_add_co_u32_e32 v120, vcc, s2, v0
	v_mul_f32_e32 v88, v88, v111
	v_rcp_f32_e32 v111, v152
	v_addc_co_u32_e32 v121, vcc, 0, v1, vcc
	s_mov_b32 s2, 0x18000
	v_add_co_u32_e32 v138, vcc, s2, v0
	s_mov_b32 s2, 0x16000
	s_nop 0
	v_addc_co_u32_e32 v139, vcc, 0, v1, vcc
	v_mul_f32_e32 v88, v117, v88
	v_mul_f32_e32 v109, v152, v109
	global_load_ushort v125, v[14:15], off offset:512
	global_load_ushort v127, v[100:101], off offset:1536
	global_load_ushort v128, v[102:103], off offset:2560
	global_load_ushort v167, v[102:103], off offset:2048
	global_load_ushort v169, v[100:101], off offset:2560
	global_load_ushort v172, v[100:101], off offset:1024
	global_load_ushort v168, v[14:15], off offset:1536
	global_load_ushort v164, v[14:15], off
	v_add_co_u32_e32 v14, vcc, s2, v0
	v_bfe_u32 v114, v109, 16, 1
	v_mul_f32_e32 v88, v88, v111
	v_addc_co_u32_e32 v15, vcc, 0, v1, vcc
	s_mov_b32 s43, 0x15000
	v_add3_u32 v153, v109, v114, s10
	v_bfe_u32 v109, v88, 16, 1
	v_add_co_u32_e32 v140, vcc, s43, v0
	v_add3_u32 v114, v88, v109, s10
	s_nop 0
	v_addc_co_u32_e32 v141, vcc, 0, v1, vcc
	global_load_ushort v126, v[22:23], off offset:512
	global_load_ushort v129, v[98:99], off offset:1536
	global_load_ushort v130, v[8:9], off offset:2560
	global_load_ushort v131, v[10:11], off offset:3584
	global_load_ushort v158, v[10:11], off offset:3072
	global_load_ushort v115, v[10:11], off
	global_load_ushort v111, v[8:9], off offset:3584
	global_load_ushort v109, v[8:9], off offset:2048
	global_load_ushort v173, v[12:13], off offset:1024
	global_load_ushort v174, v[136:137], off offset:3584
	global_load_ushort v175, v[134:135], off offset:2560
	global_load_ushort v176, v[120:121], off offset:1536
	global_load_ushort v133, v[120:121], off offset:2048
	s_nop 0
	global_load_ushort v134, v[134:135], off offset:3072
	s_nop 0
	global_load_ushort v177, v[136:137], off offset:512
	global_load_ushort v135, v[12:13], off
	global_load_ushort v178, v[120:121], off offset:3072
	global_load_ushort v171, v[138:139], off offset:2048
	global_load_ushort v170, v[138:139], off offset:512
	global_load_ushort v165, v[14:15], off offset:1024
	global_load_ushort v163, v[140:141], off offset:3584
	global_load_ushort v160, v[140:141], off offset:512
	global_load_ushort v137, v[14:15], off
	s_nop 0
	global_load_ushort v139, v[138:139], off offset:1024
	s_mov_b32 s44, 0x13000
	v_add_co_u32_e32 v146, vcc, s44, v0
	s_mov_b32 s45, 0x11000
	s_nop 0
	v_addc_co_u32_e32 v147, vcc, 0, v1, vcc
	v_add_co_u32_e32 v106, vcc, s45, v0
	s_mov_b32 s46, 0xf000
	s_nop 0
	v_addc_co_u32_e32 v107, vcc, 0, v1, vcc
	v_add_co_u32_e32 v102, vcc, s46, v0
	s_mov_b32 s47, 0xd000
	s_nop 0
	v_addc_co_u32_e32 v103, vcc, 0, v1, vcc
	v_add_co_u32_e32 v104, vcc, s47, v0
	s_mov_b32 s15, 0xa000
	s_nop 0
	v_addc_co_u32_e32 v105, vcc, 0, v1, vcc
	v_add_co_u32_e32 v100, vcc, s15, v0
	s_mov_b32 s14, 0x8000
	s_waitcnt vmcnt(40)
	v_lshlrev_b32_e32 v8, 16, v145
	v_max_f32_e32 v8, v8, v8
	v_med3_f32 v8, v8, s9, v244
	v_mul_f32_e32 v8, 0xbfb8aa3b, v8
	v_exp_f32_e32 v88, v8
	v_addc_co_u32_e32 v101, vcc, 0, v1, vcc
	v_lshlrev_b32_e32 v122, 16, v122
	v_add_f32_e32 v120, 1.0, v88
	v_rcp_f32_e32 v120, v120
	v_add_co_u32_e32 v10, vcc, s14, v0
	v_max_f32_e32 v122, v122, v122
	v_fma_f32 v121, v117, v120, v116
	v_mul_f32_e32 v121, v152, v121
	v_addc_co_u32_e32 v11, vcc, 0, v1, vcc
	v_max_f32_e32 v121, 0xda24260, v121
	v_med3_f32 v122, v122, s9, v244
	v_add_co_u32_e32 v12, vcc, s27, v0
	v_rcp_f32_e32 v152, v121
	v_mul_f32_e32 v122, 0xbfb8aa3b, v122
	v_addc_co_u32_e32 v13, vcc, 0, v1, vcc
	v_exp_f32_e32 v122, v122
	v_add_co_u32_e32 v14, vcc, s7, v0
	v_mul_f32_e32 v88, v88, v120
	s_nop 0
	v_addc_co_u32_e32 v15, vcc, 0, v1, vcc
	v_mul_f32_e32 v88, v117, v88
	v_add_co_u32_e32 v8, vcc, s0, v0
	v_mul_f32_e32 v88, v88, v152
	global_load_ushort v132, v[0:1], off offset:2560
	global_load_ushort v136, v[2:3], off offset:3584
	global_load_ushort v138, v[4:5], off offset:512
	global_load_ushort v140, v[6:7], off offset:1536
	global_load_ushort v141, v[18:19], off offset:2560
	global_load_ushort v143, v[20:21], off offset:3584
	global_load_ushort v144, v[22:23], off offset:-4096
	global_load_ushort v142, v[4:5], off offset:-4096
	v_addc_co_u32_e32 v9, vcc, 0, v1, vcc
	global_load_ushort v157, v[146:147], off offset:2560
	global_load_ushort v150, v[146:147], off offset:3072
	global_load_ushort v151, v[106:107], off offset:2048
	global_load_ushort v149, v[102:103], off offset:1024
	global_load_ushort v148, v[100:101], off offset:3072
	s_nop 0
	global_load_ushort v146, v[10:11], off offset:2048
	global_load_ushort v147, v[12:13], off offset:1024
	global_load_ushort v145, v[8:9], off offset:3072
	v_bfe_u32 v120, v88, 16, 1
	v_add_f32_e32 v152, 1.0, v122
	v_add3_u32 v88, v88, v120, s10
	s_waitcnt vmcnt(53)
	v_lshlrev_b32_e32 v120, 16, v154
	v_rcp_f32_e32 v152, v152
	v_lshl_add_u32 v17, v16, 1, v92
	v_mul_f32_e32 v120, v121, v120
	ds_write_b16_d16_hi v17, v153 offset:4464
	v_bfe_u32 v153, v120, 16, 1
	v_add3_u32 v120, v120, v153, s10
	ds_write_b16_d16_hi v17, v120 offset:4320
	v_fma_f32 v120, v117, v152, v116
	v_mul_f32_e32 v120, v121, v120
	v_mul_f32_e32 v122, v122, v152
	s_waitcnt vmcnt(52)
	v_lshlrev_b32_e32 v152, 16, v155
	v_max_f32_e32 v120, 0xda24260, v120
	v_max_f32_e32 v152, v152, v152
	v_rcp_f32_e32 v121, v120
	v_med3_f32 v152, v152, s9, v244
	v_mul_f32_e32 v152, 0xbfb8aa3b, v152
	v_exp_f32_e32 v152, v152
	v_mul_f32_e32 v122, v117, v122
	v_mul_f32_e32 v121, v122, v121
	v_bfe_u32 v122, v121, 16, 1
	v_add3_u32 v153, v121, v122, s10
	v_add_f32_e32 v121, 1.0, v152
	v_lshlrev_b32_e32 v113, 16, v113
	v_rcp_f32_e32 v121, v121
	v_mul_f32_e32 v113, v120, v113
	v_bfe_u32 v122, v113, 16, 1
	v_add3_u32 v113, v113, v122, s10
	ds_write_b16_d16_hi v17, v113 offset:4176
	v_fma_f32 v113, v117, v121, v116
	s_waitcnt vmcnt(31)
	v_lshlrev_b32_e32 v122, 16, v173
	v_mul_f32_e32 v113, v120, v113
	v_max_f32_e32 v122, v122, v122
	v_max_f32_e32 v113, 0xda24260, v113
	v_med3_f32 v122, v122, s9, v244
	v_rcp_f32_e32 v120, v113
	v_mul_f32_e32 v122, 0xbfb8aa3b, v122
	v_exp_f32_e32 v122, v122
	v_mul_f32_e32 v121, v152, v121
	v_mul_f32_e32 v121, v117, v121
	v_mul_f32_e32 v120, v121, v120
	v_bfe_u32 v121, v120, 16, 1
	v_add_f32_e32 v152, 1.0, v122
	v_add3_u32 v120, v120, v121, s10
	v_lshlrev_b32_e32 v121, 16, v156
	v_rcp_f32_e32 v152, v152
	v_mul_f32_e32 v121, v113, v121
	v_bfe_u32 v154, v121, 16, 1
	v_add3_u32 v121, v121, v154, s10
	ds_write_b16_d16_hi v17, v121 offset:4032
	v_fma_f32 v121, v117, v152, v116
	v_mul_f32_e32 v113, v113, v121
	v_mul_f32_e32 v122, v122, v152
	s_waitcnt vmcnt(25)
	v_lshlrev_b32_e32 v152, 16, v177
	v_max_f32_e32 v113, 0xda24260, v113
	v_max_f32_e32 v152, v152, v152
	v_rcp_f32_e32 v121, v113
	v_med3_f32 v152, v152, s9, v244
	v_mul_f32_e32 v152, 0xbfb8aa3b, v152
	v_exp_f32_e32 v152, v152
	v_mul_f32_e32 v122, v117, v122
	v_mul_f32_e32 v121, v122, v121
	v_bfe_u32 v122, v121, 16, 1
	v_add3_u32 v154, v121, v122, s10
	v_add_f32_e32 v122, 1.0, v152
	v_lshlrev_b32_e32 v121, 16, v174
	v_rcp_f32_e32 v122, v122
	v_mul_f32_e32 v121, v113, v121
	v_bfe_u32 v155, v121, 16, 1
	v_add3_u32 v121, v121, v155, s10
	ds_write_b16_d16_hi v17, v121 offset:3888
	v_fma_f32 v121, v117, v122, v116
	v_mul_f32_e32 v122, v152, v122
	v_lshlrev_b32_e32 v152, 16, v162
	v_mul_f32_e32 v113, v113, v121
	v_max_f32_e32 v152, v152, v152
	v_max_f32_e32 v113, 0xda24260, v113
	v_med3_f32 v152, v152, s9, v244
	v_rcp_f32_e32 v121, v113
	v_mul_f32_e32 v152, 0xbfb8aa3b, v152
	v_exp_f32_e32 v152, v152
	v_mul_f32_e32 v122, v117, v122
	v_mul_f32_e32 v121, v122, v121
	v_bfe_u32 v122, v121, 16, 1
	v_add_f32_e32 v155, 1.0, v152
	v_add3_u32 v121, v121, v122, s10
	v_lshlrev_b32_e32 v122, 16, v159
	v_rcp_f32_e32 v155, v155
	v_mul_f32_e32 v122, v113, v122
	v_bfe_u32 v156, v122, 16, 1
	v_add3_u32 v122, v122, v156, s10
	ds_write_b16_d16_hi v17, v122 offset:3744
	v_fma_f32 v122, v117, v155, v116
	v_mul_f32_e32 v113, v113, v122
	v_mul_f32_e32 v152, v152, v155
	v_lshlrev_b32_e32 v155, 16, v166
	v_max_f32_e32 v113, 0xda24260, v113
	v_max_f32_e32 v155, v155, v155
	v_rcp_f32_e32 v122, v113
	v_med3_f32 v155, v155, s9, v244
	v_mul_f32_e32 v155, 0xbfb8aa3b, v155
	v_exp_f32_e32 v156, v155
	v_mul_f32_e32 v152, v117, v152
	v_mul_f32_e32 v122, v152, v122
	v_bfe_u32 v152, v122, 16, 1
	v_add3_u32 v155, v122, v152, s10
	v_add_f32_e32 v152, 1.0, v156
	v_lshlrev_b32_e32 v122, 16, v175
	v_rcp_f32_e32 v152, v152
	v_mul_f32_e32 v122, v113, v122
	v_bfe_u32 v159, v122, 16, 1
	v_add3_u32 v122, v122, v159, s10
	ds_write_b16_d16_hi v17, v122 offset:3600
	v_fma_f32 v122, v117, v152, v116
	v_mul_f32_e32 v113, v113, v122
	v_max_f32_e32 v113, 0xda24260, v113
	v_rcp_f32_e32 v122, v113
	v_mul_f32_e32 v152, v156, v152
	v_mul_f32_e32 v152, v117, v152
	ds_write_b16_d16_hi v17, v114 offset:9072
	v_mul_f32_e32 v122, v152, v122
	v_bfe_u32 v152, v122, 16, 1
	v_add3_u32 v122, v122, v152, s10
	v_lshlrev_b32_e32 v152, 16, v167
	v_mul_f32_e32 v152, v113, v152
	v_bfe_u32 v156, v152, 16, 1
	v_add3_u32 v152, v152, v156, s10
	ds_write_b16_d16_hi v17, v88 offset:8928
	ds_write_b16_d16_hi v17, v153 offset:8784
	ds_write_b16_d16_hi v17, v120 offset:8640
	ds_write_b16_d16_hi v17, v154 offset:8496
	ds_write_b16_d16_hi v17, v121 offset:8352
	ds_write_b16_d16_hi v17, v155 offset:8208
	ds_write_b16_d16_hi v17, v152 offset:3456
	ds_write_b16_d16_hi v17, v122 offset:8064
	s_waitcnt vmcnt(23)
	v_lshlrev_b32_e32 v152, 16, v178
	v_max_f32_e32 v152, v152, v152
	v_med3_f32 v152, v152, s9, v244
	v_mul_f32_e32 v152, 0xbfb8aa3b, v152
	v_exp_f32_e32 v152, v152
	v_lshlrev_b32_e32 v109, 16, v109
	v_add_f32_e32 v156, 1.0, v152
	v_rcp_f32_e32 v156, v156
	s_nop 0
	v_fma_f32 v159, v117, v156, v116
	v_mul_f32_e32 v113, v113, v159
	v_max_f32_e32 v113, 0xda24260, v113
	v_mul_f32_e32 v152, v152, v156
	v_rcp_f32_e32 v156, v113
	v_mul_f32_e32 v152, v117, v152
	v_mul_f32_e32 v152, v152, v156
	v_bfe_u32 v156, v152, 16, 1
	v_add3_u32 v156, v152, v156, s10
	v_lshlrev_b32_e32 v152, 16, v176
	v_mul_f32_e32 v152, v113, v152
	v_bfe_u32 v159, v152, 16, 1
	v_add3_u32 v152, v152, v159, s10
	ds_write_b16_d16_hi v17, v152 offset:3312
	ds_write_b16_d16_hi v17, v156 offset:7920
	v_lshlrev_b32_e32 v152, 16, v169
	v_max_f32_e32 v152, v152, v152
	v_med3_f32 v152, v152, s9, v244
	v_mul_f32_e32 v152, 0xbfb8aa3b, v152
	v_exp_f32_e32 v152, v152
	s_nop 0
	v_add_f32_e32 v159, 1.0, v152
	v_rcp_f32_e32 v159, v159
	s_nop 0
	v_fma_f32 v162, v117, v159, v116
	v_mul_f32_e32 v113, v113, v162
	v_max_f32_e32 v173, 0xda24260, v113
	v_rcp_f32_e32 v113, v173
	v_mul_f32_e32 v152, v152, v159
	v_mul_f32_e32 v152, v117, v152
	v_mul_f32_e32 v113, v152, v113
	v_bfe_u32 v152, v113, 16, 1
	v_add3_u32 v152, v113, v152, s10
	v_lshlrev_b32_e32 v113, 16, v172
	v_mul_f32_e32 v113, v173, v113
	v_bfe_u32 v159, v113, 16, 1
	v_add3_u32 v172, v113, v159, s10
	global_load_ushort v169, v[106:107], off offset:3072
	global_load_ushort v167, v[106:107], off offset:1536
	global_load_ushort v166, v[98:99], off offset:2560
	global_load_ushort v162, v[98:99], off offset:1024
	global_load_ushort v159, v[102:103], off offset:2048
	global_load_ushort v113, v[102:103], off offset:512
	s_nop 0
	global_load_ushort v107, v[22:23], off offset:1536
	global_load_ushort v106, v[22:23], off
	s_nop 0
	global_load_ushort v104, v[104:105], off offset:1024
	v_add_co_u32_e32 v22, vcc, s50, v0
	s_nop 1
	v_addc_co_u32_e32 v23, vcc, 0, v1, vcc
	global_load_ushort v103, v[22:23], off offset:3584
	global_load_ushort v102, v[22:23], off offset:512
	global_load_ushort v99, v[20:21], off offset:3072
	global_load_ushort v98, v[20:21], off
	s_nop 0
	global_load_ushort v21, v[100:101], off offset:2560
	global_load_ushort v20, v[18:19], off offset:3584
	s_nop 0
	global_load_ushort v19, v[18:19], off offset:2048
	s_waitcnt vmcnt(38)
	v_lshlrev_b32_e32 v18, 16, v171
	v_max_f32_e32 v18, v18, v18
	v_med3_f32 v18, v18, s9, v244
	v_mul_f32_e32 v18, 0xbfb8aa3b, v18
	v_exp_f32_e32 v18, v18
	ds_write_b16_d16_hi v17, v172 offset:3168
	ds_write_b16_d16_hi v17, v152 offset:7776
	v_add_f32_e32 v22, 1.0, v18
	v_rcp_f32_e32 v22, v22
	s_nop 0
	v_fma_f32 v23, v117, v22, v116
	v_mul_f32_e32 v18, v18, v22
	v_mul_f32_e32 v22, v173, v23
	v_max_f32_e32 v22, 0xda24260, v22
	v_rcp_f32_e32 v23, v22
	v_mul_f32_e32 v18, v117, v18
	v_mul_f32_e32 v18, v18, v23
	v_bfe_u32 v23, v18, 16, 1
	v_add3_u32 v23, v18, v23, s10
	s_waitcnt vmcnt(37)
	v_lshlrev_b32_e32 v18, 16, v170
	v_mul_f32_e32 v18, v22, v18
	v_bfe_u32 v100, v18, 16, 1
	v_add3_u32 v18, v18, v100, s10
	ds_write_b16_d16_hi v17, v18 offset:3024
	ds_write_b16_d16_hi v17, v23 offset:7632
	v_lshlrev_b32_e32 v18, 16, v168
	v_max_f32_e32 v18, v18, v18
	v_med3_f32 v18, v18, s9, v244
	v_mul_f32_e32 v18, 0xbfb8aa3b, v18
	v_exp_f32_e32 v18, v18
	s_nop 0
	v_add_f32_e32 v100, 1.0, v18
	v_rcp_f32_e32 v100, v100
	s_nop 0
	v_fma_f32 v101, v117, v100, v116
	v_mul_f32_e32 v22, v22, v101
	v_max_f32_e32 v22, 0xda24260, v22
	v_mul_f32_e32 v18, v18, v100
	v_rcp_f32_e32 v100, v22
	v_mul_f32_e32 v18, v117, v18
	v_mul_f32_e32 v18, v18, v100
	v_bfe_u32 v100, v18, 16, 1
	v_add3_u32 v18, v18, v100, s10
	v_lshlrev_b32_e32 v100, 16, v164
	v_mul_f32_e32 v100, v22, v100
	v_bfe_u32 v101, v100, 16, 1
	v_add3_u32 v100, v100, v101, s10
	ds_write_b16_d16_hi v17, v100 offset:2880
	ds_write_b16_d16_hi v17, v18 offset:7488
	s_waitcnt vmcnt(36)
	v_lshlrev_b32_e32 v100, 16, v165
	v_max_f32_e32 v100, v100, v100
	v_med3_f32 v100, v100, s9, v244
	v_mul_f32_e32 v100, 0xbfb8aa3b, v100
	v_exp_f32_e32 v100, v100
	s_nop 0
	v_add_f32_e32 v101, 1.0, v100
	v_rcp_f32_e32 v101, v101
	s_nop 0
	v_fma_f32 v105, v117, v101, v116
	v_mul_f32_e32 v22, v22, v105
	v_max_f32_e32 v22, 0xda24260, v22
	v_mul_f32_e32 v100, v100, v101
	v_rcp_f32_e32 v101, v22
	v_mul_f32_e32 v100, v117, v100
	v_mul_f32_e32 v100, v100, v101
	v_bfe_u32 v101, v100, 16, 1
	v_add3_u32 v101, v100, v101, s10
	s_waitcnt vmcnt(35)
	v_lshlrev_b32_e32 v100, 16, v163
	v_mul_f32_e32 v100, v22, v100
	v_bfe_u32 v105, v100, 16, 1
	v_add3_u32 v100, v100, v105, s10
	ds_write_b16_d16_hi v17, v100 offset:2736
	ds_write_b16_d16_hi v17, v101 offset:7344
	s_waitcnt vmcnt(34)
	v_lshlrev_b32_e32 v100, 16, v160
	v_max_f32_e32 v100, v100, v100
	v_med3_f32 v100, v100, s9, v244
	v_mul_f32_e32 v100, 0xbfb8aa3b, v100
	v_exp_f32_e32 v100, v100
	s_nop 0
	v_add_f32_e32 v105, 1.0, v100
	v_rcp_f32_e32 v105, v105
	s_nop 0
	v_fma_f32 v160, v117, v105, v116
	v_mul_f32_e32 v22, v22, v160
	v_mul_f32_e32 v100, v100, v105
	v_max_f32_e32 v105, 0xda24260, v22
	v_rcp_f32_e32 v22, v105
	v_mul_f32_e32 v100, v117, v100
	v_mul_f32_e32 v22, v100, v22
	v_bfe_u32 v100, v22, 16, 1
	v_add3_u32 v22, v22, v100, s10
	v_lshlrev_b32_e32 v100, 16, v158
	v_mul_f32_e32 v100, v105, v100
	v_bfe_u32 v158, v100, 16, 1
	v_add3_u32 v100, v100, v158, s10
	ds_write_b16_d16_hi v17, v100 offset:2592
	ds_write_b16_d16_hi v17, v22 offset:7200
	v_lshlrev_b32_e32 v100, 16, v115
	v_max_f32_e32 v100, v100, v100
	v_med3_f32 v100, v100, s9, v244
	v_mul_f32_e32 v100, 0xbfb8aa3b, v100
	v_exp_f32_e32 v100, v100
	s_nop 0
	v_add_f32_e32 v115, 1.0, v100
	v_rcp_f32_e32 v115, v115
	s_nop 0
	v_fma_f32 v158, v117, v115, v116
	v_mul_f32_e32 v105, v105, v158
	v_mul_f32_e32 v100, v100, v115
	v_max_f32_e32 v115, 0xda24260, v105
	v_rcp_f32_e32 v105, v115
	v_mul_f32_e32 v100, v117, v100
	v_mul_f32_e32 v100, v100, v105
	v_bfe_u32 v105, v100, 16, 1
	v_add3_u32 v105, v100, v105, s10
	s_waitcnt vmcnt(23)
	v_lshlrev_b32_e32 v100, 16, v157
	v_mul_f32_e32 v100, v115, v100
	v_bfe_u32 v157, v100, 16, 1
	v_add3_u32 v100, v100, v157, s10
	ds_write_b16_d16_hi v17, v100 offset:2448
	ds_write_b16_d16_hi v17, v105 offset:7056
	v_lshlrev_b32_e32 v100, 16, v111
	v_max_f32_e32 v100, v100, v100
	v_med3_f32 v100, v100, s9, v244
	v_mul_f32_e32 v100, 0xbfb8aa3b, v100
	v_exp_f32_e32 v100, v100
	s_nop 0
	v_add_f32_e32 v111, 1.0, v100
	v_rcp_f32_e32 v111, v111
	s_nop 0
	v_fma_f32 v157, v117, v111, v116
	v_mul_f32_e32 v100, v100, v111
	v_mul_f32_e32 v111, v115, v157
	v_max_f32_e32 v111, 0xda24260, v111
	v_rcp_f32_e32 v115, v111
	v_mul_f32_e32 v100, v117, v100
	v_mul_f32_e32 v109, v111, v109
	v_mul_f32_e32 v100, v100, v115
	v_bfe_u32 v115, v100, 16, 1
	v_add3_u32 v100, v100, v115, s10
	v_bfe_u32 v115, v109, 16, 1
	v_add3_u32 v109, v109, v115, s10
	ds_write_b16_d16_hi v17, v109 offset:2304
	ds_write_b16_d16_hi v17, v100 offset:6912
	s_waitcnt vmcnt(15)
	v_lshlrev_b32_e32 v109, 16, v169
	v_max_f32_e32 v109, v109, v109
	v_med3_f32 v109, v109, s9, v244
	v_mul_f32_e32 v109, 0xbfb8aa3b, v109
	v_exp_f32_e32 v109, v109
	s_nop 0
	v_add_f32_e32 v115, 1.0, v109
	v_rcp_f32_e32 v115, v115
	s_nop 0
	v_fma_f32 v157, v117, v115, v116
	v_mul_f32_e32 v111, v111, v157
	v_max_f32_e32 v111, 0xda24260, v111
	v_mul_f32_e32 v109, v109, v115
	v_rcp_f32_e32 v115, v111
	v_mul_f32_e32 v109, v117, v109
	v_mul_f32_e32 v109, v109, v115
	v_bfe_u32 v115, v109, 16, 1
	v_add3_u32 v109, v109, v115, s10
	s_waitcnt vmcnt(14)
	v_lshlrev_b32_e32 v115, 16, v167
	v_mul_f32_e32 v115, v111, v115
	v_bfe_u32 v157, v115, 16, 1
	v_add3_u32 v115, v115, v157, s10
	ds_write_b16_d16_hi v17, v115 offset:2160
	ds_write_b16_d16_hi v17, v109 offset:6768
	s_waitcnt vmcnt(13)
	v_lshlrev_b32_e32 v115, 16, v166
	v_max_f32_e32 v115, v115, v115
	v_med3_f32 v115, v115, s9, v244
	v_mul_f32_e32 v115, 0xbfb8aa3b, v115
	v_exp_f32_e32 v115, v115
	global_load_ushort v175, v[10:11], off offset:3072
	global_load_ushort v173, v[10:11], off offset:1536
	global_load_ushort v174, v[6:7], off offset:2560
	global_load_ushort v171, v[6:7], off offset:1024
	global_load_ushort v172, v[12:13], off offset:2048
	global_load_ushort v169, v[12:13], off offset:512
	global_load_ushort v170, v[4:5], off offset:1536
	global_load_ushort v166, v[4:5], off
	global_load_ushort v168, v[14:15], off offset:1024
	v_add_co_u32_e32 v4, vcc, s11, v0
	v_add_f32_e32 v157, 1.0, v115
	v_rcp_f32_e32 v157, v157
	v_addc_co_u32_e32 v5, vcc, 0, v1, vcc
	v_fma_f32 v158, v117, v157, v116
	v_mul_f32_e32 v111, v111, v158
	v_max_f32_e32 v111, 0xda24260, v111
	v_mul_f32_e32 v115, v115, v157
	v_rcp_f32_e32 v157, v111
	v_mul_f32_e32 v115, v117, v115
	v_mul_f32_e32 v115, v115, v157
	v_bfe_u32 v157, v115, 16, 1
	v_add3_u32 v157, v115, v157, s10
	s_waitcnt vmcnt(21)
	v_lshlrev_b32_e32 v115, 16, v162
	v_mul_f32_e32 v115, v111, v115
	v_bfe_u32 v158, v115, 16, 1
	v_add3_u32 v115, v115, v158, s10
	global_load_ushort v165, v[4:5], off offset:3584
	global_load_ushort v167, v[4:5], off offset:512
	global_load_ushort v163, v[2:3], off offset:3072
	global_load_ushort v164, v[2:3], off
	global_load_ushort v160, v[8:9], off offset:2560
	global_load_ushort v162, v[0:1], off offset:3584
	global_load_ushort v158, v[0:1], off offset:2048
	s_waitcnt vmcnt(27)
	v_lshlrev_b32_e32 v0, 16, v159
	v_max_f32_e32 v0, v0, v0
	v_med3_f32 v0, v0, s9, v244
	v_mul_f32_e32 v0, 0xbfb8aa3b, v0
	v_exp_f32_e32 v0, v0
	ds_write_b16_d16_hi v17, v115 offset:2016
	ds_write_b16_d16_hi v17, v157 offset:6624
	v_add_f32_e32 v1, 1.0, v0
	v_rcp_f32_e32 v1, v1
	s_nop 0
	v_fma_f32 v2, v117, v1, v116
	v_mul_f32_e32 v0, v0, v1
	v_mul_f32_e32 v1, v111, v2
	v_max_f32_e32 v1, 0xda24260, v1
	v_rcp_f32_e32 v2, v1
	v_mul_f32_e32 v0, v117, v0
	v_mul_f32_e32 v0, v0, v2
	v_bfe_u32 v2, v0, 16, 1
	v_add3_u32 v0, v0, v2, s10
	s_waitcnt vmcnt(26)
	v_lshlrev_b32_e32 v2, 16, v113
	v_mul_f32_e32 v2, v1, v2
	v_bfe_u32 v3, v2, 16, 1
	v_add3_u32 v2, v2, v3, s10
	ds_write_b16_d16_hi v17, v2 offset:1872
	ds_write_b16_d16_hi v17, v0 offset:6480
	s_waitcnt vmcnt(25)
	v_lshlrev_b32_e32 v2, 16, v107
	v_max_f32_e32 v2, v2, v2
	v_med3_f32 v2, v2, s9, v244
	v_mul_f32_e32 v2, 0xbfb8aa3b, v2
	v_exp_f32_e32 v2, v2
	s_nop 0
	v_add_f32_e32 v3, 1.0, v2
	v_rcp_f32_e32 v3, v3
	s_nop 0
	v_fma_f32 v4, v117, v3, v116
	v_mul_f32_e32 v1, v1, v4
	v_max_f32_e32 v1, 0xda24260, v1
	v_mul_f32_e32 v2, v2, v3
	v_rcp_f32_e32 v3, v1
	v_mul_f32_e32 v2, v117, v2
	v_mul_f32_e32 v2, v2, v3
	v_bfe_u32 v3, v2, 16, 1
	v_add3_u32 v159, v2, v3, s10
	s_waitcnt vmcnt(24)
	v_lshlrev_b32_e32 v2, 16, v106
	v_mul_f32_e32 v2, v1, v2
	v_bfe_u32 v3, v2, 16, 1
	v_add3_u32 v2, v2, v3, s10
	ds_write_b16_d16_hi v17, v2 offset:1728
	ds_write_b16_d16_hi v17, v159 offset:6336
	s_waitcnt vmcnt(23)
	v_lshlrev_b32_e32 v2, 16, v104
	v_max_f32_e32 v2, v2, v2
	v_med3_f32 v2, v2, s9, v244
	v_mul_f32_e32 v2, 0xbfb8aa3b, v2
	v_exp_f32_e32 v2, v2
	s_nop 0
	v_add_f32_e32 v3, 1.0, v2
	v_rcp_f32_e32 v3, v3
	s_nop 0
	v_fma_f32 v4, v117, v3, v116
	v_mul_f32_e32 v1, v1, v4
	v_max_f32_e32 v1, 0xda24260, v1
	v_mul_f32_e32 v2, v2, v3
	v_rcp_f32_e32 v3, v1
	v_mul_f32_e32 v2, v117, v2
	v_mul_f32_e32 v2, v2, v3
	v_bfe_u32 v3, v2, 16, 1
	v_add3_u32 v2, v2, v3, s10
	s_waitcnt vmcnt(22)
	v_lshlrev_b32_e32 v3, 16, v103
	v_mul_f32_e32 v3, v1, v3
	v_bfe_u32 v4, v3, 16, 1
	v_add3_u32 v3, v3, v4, s10
	ds_write_b16_d16_hi v17, v3 offset:1584
	ds_write_b16_d16_hi v17, v2 offset:6192
	s_waitcnt vmcnt(21)
	v_lshlrev_b32_e32 v3, 16, v102
	v_max_f32_e32 v3, v3, v3
	v_med3_f32 v3, v3, s9, v244
	v_mul_f32_e32 v3, 0xbfb8aa3b, v3
	v_exp_f32_e32 v3, v3
	s_nop 0
	v_add_f32_e32 v4, 1.0, v3
	v_rcp_f32_e32 v4, v4
	s_nop 0
	v_fma_f32 v5, v117, v4, v116
	v_mul_f32_e32 v1, v1, v5
	v_max_f32_e32 v1, 0xda24260, v1
	v_mul_f32_e32 v3, v3, v4
	v_rcp_f32_e32 v4, v1
	v_mul_f32_e32 v3, v117, v3
	v_mul_f32_e32 v3, v3, v4
	v_bfe_u32 v4, v3, 16, 1
	v_add3_u32 v102, v3, v4, s10
	s_waitcnt vmcnt(20)
	v_lshlrev_b32_e32 v3, 16, v99
	v_mul_f32_e32 v3, v1, v3
	v_bfe_u32 v4, v3, 16, 1
	v_add3_u32 v3, v3, v4, s10
	ds_write_b16_d16_hi v17, v3 offset:1440
	ds_write_b16_d16_hi v17, v102 offset:6048
	s_waitcnt vmcnt(19)
	v_lshlrev_b32_e32 v3, 16, v98
	v_max_f32_e32 v3, v3, v3
	v_med3_f32 v3, v3, s9, v244
	v_mul_f32_e32 v3, 0xbfb8aa3b, v3
	v_exp_f32_e32 v3, v3
	s_nop 0
	v_add_f32_e32 v4, 1.0, v3
	v_rcp_f32_e32 v4, v4
	s_nop 0
	v_fma_f32 v5, v117, v4, v116
	v_mul_f32_e32 v1, v1, v5
	v_max_f32_e32 v1, 0xda24260, v1
	v_mul_f32_e32 v3, v3, v4
	v_rcp_f32_e32 v4, v1
	v_mul_f32_e32 v3, v117, v3
	v_mul_f32_e32 v3, v3, v4
	v_bfe_u32 v4, v3, 16, 1
	v_add3_u32 v3, v3, v4, s10
	s_waitcnt vmcnt(18)
	v_lshlrev_b32_e32 v4, 16, v21
	v_mul_f32_e32 v4, v1, v4
	v_bfe_u32 v5, v4, 16, 1
	v_add3_u32 v4, v4, v5, s10
	ds_write_b16_d16_hi v17, v4 offset:1296
	ds_write_b16_d16_hi v17, v3 offset:5904
	s_waitcnt vmcnt(17)
	v_lshlrev_b32_e32 v4, 16, v20
	v_max_f32_e32 v4, v4, v4
	v_med3_f32 v4, v4, s9, v244
	v_mul_f32_e32 v4, 0xbfb8aa3b, v4
	v_exp_f32_e32 v4, v4
	s_nop 0
	v_add_f32_e32 v5, 1.0, v4
	v_rcp_f32_e32 v5, v5
	s_nop 0
	v_fma_f32 v6, v117, v5, v116
	v_mul_f32_e32 v1, v1, v6
	v_max_f32_e32 v12, 0xda24260, v1
	v_rcp_f32_e32 v1, v12
	v_mul_f32_e32 v4, v4, v5
	v_mul_f32_e32 v4, v117, v4
	v_mul_f32_e32 v1, v4, v1
	v_bfe_u32 v4, v1, 16, 1
	v_add3_u32 v20, v1, v4, s10
	s_waitcnt vmcnt(16)
	v_lshlrev_b32_e32 v1, 16, v19
	v_mul_f32_e32 v1, v12, v1
	v_bfe_u32 v4, v1, 16, 1
	v_add3_u32 v1, v1, v4, s10
	ds_write_b16_d16_hi v17, v1 offset:1152
	ds_write_b16_d16_hi v17, v20 offset:5760
	s_waitcnt vmcnt(15)
	v_lshlrev_b32_e32 v8, 16, v175
	v_max_f32_e32 v8, v8, v8
	v_med3_f32 v8, v8, s9, v244
	v_mul_f32_e32 v8, 0xbfb8aa3b, v8
	v_exp_f32_e32 v98, v8
	v_and_b32_e32 v113, 0xffff0000, v2
	v_lshl_or_b32 v2, v108, 16, v124
	v_and_b32_e32 v115, 0xffff0000, v3
	v_add_f32_e32 v13, 1.0, v98
	v_rcp_f32_e32 v104, v13
	v_lshl_or_b32 v3, v110, 16, v112
	v_lshl_or_b32 v11, v151, 16, v129
	v_and_b32_e32 v19, 0xffff0000, v114
	v_fma_f32 v106, v117, v104, v116
	v_mul_f32_e32 v12, v12, v106
	v_max_f32_e32 v106, 0xda24260, v12
	v_rcp_f32_e32 v108, v106
	v_mul_f32_e32 v98, v98, v104
	v_mul_f32_e32 v98, v117, v98
	v_lshl_or_b32 v7, v133, 16, v127
	v_mul_f32_e32 v98, v98, v108
	v_bfe_u32 v104, v98, 16, 1
	v_add3_u32 v98, v98, v104, s10
	s_waitcnt vmcnt(13)
	v_lshlrev_b32_e32 v104, 16, v174
	v_max_f32_e32 v104, v104, v104
	v_med3_f32 v104, v104, s9, v244
	v_mul_f32_e32 v104, 0xbfb8aa3b, v104
	v_exp_f32_e32 v104, v104
	v_lshlrev_b32_e32 v108, 16, v173
	v_mul_f32_e32 v108, v106, v108
	v_bfe_u32 v112, v108, 16, 1
	v_add_f32_e32 v110, 1.0, v104
	v_rcp_f32_e32 v110, v110
	v_add3_u32 v108, v108, v112, s10
	ds_write_b16_d16_hi v17, v108 offset:1008
	v_and_b32_e32 v129, 0xffff0000, v98
	v_fma_f32 v108, v117, v110, v116
	v_mul_f32_e32 v106, v106, v108
	v_max_f32_e32 v106, 0xda24260, v106
	v_rcp_f32_e32 v108, v106
	ds_write_b16_d16_hi v17, v98 offset:5616
	v_mul_f32_e32 v98, v104, v110
	v_mul_f32_e32 v98, v117, v98
	v_mul_f32_e32 v98, v98, v108
	s_waitcnt vmcnt(11)
	v_lshlrev_b32_e32 v108, 16, v172
	v_max_f32_e32 v108, v108, v108
	v_med3_f32 v108, v108, s9, v244
	v_mul_f32_e32 v108, 0xbfb8aa3b, v108
	v_exp_f32_e32 v108, v108
	v_bfe_u32 v104, v98, 16, 1
	v_add3_u32 v98, v98, v104, s10
	v_lshlrev_b32_e32 v104, 16, v171
	v_add_f32_e32 v110, 1.0, v108
	v_rcp_f32_e32 v110, v110
	v_mul_f32_e32 v104, v106, v104
	v_bfe_u32 v112, v104, 16, 1
	v_add3_u32 v104, v104, v112, s10
	ds_write_b16_d16_hi v17, v104 offset:864
	v_fma_f32 v104, v117, v110, v116
	v_mul_f32_e32 v104, v106, v104
	v_max_f32_e32 v104, 0xda24260, v104
	v_rcp_f32_e32 v106, v104
	v_mul_f32_e32 v108, v108, v110
	v_mul_f32_e32 v108, v117, v108
	s_waitcnt vmcnt(10)
	v_lshlrev_b32_e32 v110, 16, v169
	v_mul_f32_e32 v106, v108, v106
	v_bfe_u32 v108, v106, 16, 1
	v_add3_u32 v106, v106, v108, s10
	s_waitcnt vmcnt(9)
	v_lshlrev_b32_e32 v108, 16, v170
	v_max_f32_e32 v108, v108, v108
	v_med3_f32 v108, v108, s9, v244
	v_mul_f32_e32 v108, 0xbfb8aa3b, v108
	v_exp_f32_e32 v108, v108
	v_mul_f32_e32 v110, v104, v110
	v_bfe_u32 v114, v110, 16, 1
	v_add3_u32 v110, v110, v114, s10
	v_add_f32_e32 v112, 1.0, v108
	v_rcp_f32_e32 v112, v112
	ds_write_b16_d16_hi v17, v110 offset:720
	v_and_b32_e32 v127, 0xffff0000, v106
	ds_write_b16_d16_hi v17, v106 offset:5328
	v_fma_f32 v110, v117, v112, v116
	v_mul_f32_e32 v104, v104, v110
	v_max_f32_e32 v104, 0xda24260, v104
	v_rcp_f32_e32 v110, v104
	v_mul_f32_e32 v106, v108, v112
	v_mul_f32_e32 v106, v117, v106
	v_lshl_or_b32 v1, v135, 16, v123
	v_mul_f32_e32 v106, v106, v110
	s_waitcnt vmcnt(7)
	v_lshlrev_b32_e32 v110, 16, v168
	v_max_f32_e32 v110, v110, v110
	v_med3_f32 v110, v110, s9, v244
	v_mul_f32_e32 v110, 0xbfb8aa3b, v110
	v_exp_f32_e32 v110, v110
	v_bfe_u32 v108, v106, 16, 1
	v_add3_u32 v106, v106, v108, s10
	v_lshlrev_b32_e32 v108, 16, v166
	v_add_f32_e32 v112, 1.0, v110
	v_rcp_f32_e32 v112, v112
	v_mul_f32_e32 v108, v104, v108
	v_bfe_u32 v114, v108, 16, 1
	v_add3_u32 v108, v108, v114, s10
	ds_write_b16_d16_hi v17, v108 offset:576
	v_fma_f32 v108, v117, v112, v116
	v_mul_f32_e32 v104, v104, v108
	v_max_f32_e32 v104, 0xda24260, v104
	v_rcp_f32_e32 v108, v104
	v_mul_f32_e32 v110, v110, v112
	v_mul_f32_e32 v110, v117, v110
	s_waitcnt vmcnt(6)
	v_lshlrev_b32_e32 v112, 16, v165
	v_mul_f32_e32 v108, v110, v108
	v_bfe_u32 v110, v108, 16, 1
	v_add3_u32 v108, v108, v110, s10
	s_waitcnt vmcnt(5)
	v_lshlrev_b32_e32 v110, 16, v167
	v_max_f32_e32 v110, v110, v110
	v_med3_f32 v110, v110, s9, v244
	v_mul_f32_e32 v110, 0xbfb8aa3b, v110
	v_exp_f32_e32 v110, v110
	v_mul_f32_e32 v112, v104, v112
	v_bfe_u32 v123, v112, 16, 1
	v_add3_u32 v112, v112, v123, s10
	v_add_f32_e32 v114, 1.0, v110
	v_rcp_f32_e32 v114, v114
	ds_write_b16_d16_hi v17, v112 offset:432
	v_lshl_or_b32 v5, v137, 16, v131
	v_and_b32_e32 v131, 0xffff0000, v108
	v_fma_f32 v112, v117, v114, v116
	v_mul_f32_e32 v104, v104, v112
	v_max_f32_e32 v104, 0xda24260, v104
	v_rcp_f32_e32 v112, v104
	ds_write_b16_d16_hi v17, v108 offset:5040
	v_mul_f32_e32 v108, v110, v114
	v_mul_f32_e32 v108, v117, v108
	v_mul_f32_e32 v108, v108, v112
	s_waitcnt vmcnt(3)
	v_lshlrev_b32_e32 v112, 16, v164
	v_max_f32_e32 v112, v112, v112
	v_med3_f32 v112, v112, s9, v244
	v_mul_f32_e32 v112, 0xbfb8aa3b, v112
	v_exp_f32_e32 v112, v112
	v_bfe_u32 v110, v108, 16, 1
	v_add3_u32 v108, v108, v110, s10
	v_lshlrev_b32_e32 v110, 16, v163
	v_add_f32_e32 v114, 1.0, v112
	v_rcp_f32_e32 v114, v114
	v_mul_f32_e32 v110, v104, v110
	v_bfe_u32 v123, v110, 16, 1
	v_add3_u32 v110, v110, v123, s10
	ds_write_b16_d16_hi v17, v110 offset:288
	v_fma_f32 v110, v117, v114, v116
	v_mul_f32_e32 v104, v104, v110
	v_max_f32_e32 v104, 0xda24260, v104
	v_rcp_f32_e32 v110, v104
	v_mul_f32_e32 v112, v112, v114
	v_mul_f32_e32 v112, v117, v112
	s_waitcnt vmcnt(2)
	v_lshlrev_b32_e32 v114, 16, v160
	v_mul_f32_e32 v110, v112, v110
	v_bfe_u32 v112, v110, 16, 1
	v_add3_u32 v110, v110, v112, s10
	s_waitcnt vmcnt(1)
	v_lshlrev_b32_e32 v112, 16, v162
	v_max_f32_e32 v112, v112, v112
	v_med3_f32 v112, v112, s9, v244
	v_mul_f32_e32 v112, 0xbfb8aa3b, v112
	v_exp_f32_e32 v112, v112
	v_mul_f32_e32 v114, v104, v114
	v_bfe_u32 v124, v114, 16, 1
	v_add3_u32 v114, v114, v124, s10
	v_add_f32_e32 v123, 1.0, v112
	v_rcp_f32_e32 v123, v123
	ds_write_b16_d16_hi v17, v114 offset:144
	v_lshl_or_b32 v12, v145, 16, v132
	v_lshl_or_b32 v6, v139, 16, v125
	v_fma_f32 v114, v117, v123, v116
	v_mul_f32_e32 v104, v104, v114
	v_max_f32_e32 v132, 0xda24260, v104
	v_rcp_f32_e32 v104, v132
	v_and_b32_e32 v125, 0xffff0000, v110
	ds_write_b16_d16_hi v17, v110 offset:4752
	v_mul_f32_e32 v110, v112, v123
	v_mul_f32_e32 v110, v117, v110
	v_mul_f32_e32 v104, v110, v104
	v_bfe_u32 v110, v104, 16, 1
	v_add3_u32 v104, v104, v110, s10
	s_waitcnt vmcnt(0)
	v_lshlrev_b32_e32 v110, 16, v158
	v_mul_f32_e32 v110, v132, v110
	v_bfe_u32 v112, v110, 16, 1
	v_add3_u32 v110, v110, v112, s10
	v_and_b32_e32 v111, 0xffff0000, v0
	v_and_b32_e32 v109, 0xffff0000, v109
	v_and_b32_e32 v107, 0xffff0000, v105
	v_and_b32_e32 v105, 0xffff0000, v101
	v_and_b32_e32 v103, 0xffff0000, v23
	v_and_b32_e32 v101, 0xffff0000, v156
	v_and_b32_e32 v99, 0xffff0000, v155
	v_and_b32_e32 v23, 0xffff0000, v154
	v_and_b32_e32 v21, 0xffff0000, v153
	v_lshl_or_b32 v0, v134, 16, v128
	v_lshl_or_b32 v4, v150, 16, v130
	v_lshl_or_b32 v10, v149, 16, v126
	v_lshl_or_b32 v9, v144, 16, v143
	v_lshl_or_b32 v8, v148, 16, v141
	v_lshl_or_b32 v15, v146, 16, v140
	v_lshl_or_b32 v14, v147, 16, v138
	v_lshl_or_b32 v13, v142, 16, v136
	ds_write_b16_d16_hi v17, v98 offset:5472
	ds_write_b16_d16_hi v17, v106 offset:5184
	ds_write_b16_d16_hi v17, v108 offset:4896
	ds_write_b16_d16_hi v17, v110
	ds_write_b16_d16_hi v17, v104 offset:4608
	v_and_b32_e32 v124, 0xffff0000, v104
	v_and_b32_e32 v130, 0xffff0000, v108
	v_and_b32_e32 v126, 0xffff0000, v106
	v_and_b32_e32 v128, 0xffff0000, v98
	s_movk_i32 s0, 0x50
	v_pk_mul_f32 v[124:125], v[132:133], v[124:125] op_sel_hi:[0,1]
	v_pk_mul_f32 v[130:131], v[132:133], v[130:131] op_sel_hi:[0,1]
	v_pk_mul_f32 v[126:127], v[132:133], v[126:127] op_sel_hi:[0,1]
	v_pk_mul_f32 v[128:129], v[132:133], v[128:129] op_sel_hi:[0,1]
	v_and_b32_e32 v114, 0xffff0000, v20
	v_and_b32_e32 v112, 0xffff0000, v102
	v_and_b32_e32 v110, 0xffff0000, v159
	v_and_b32_e32 v108, 0xffff0000, v157
	v_and_b32_e32 v106, 0xffff0000, v100
	v_and_b32_e32 v104, 0xffff0000, v22
	v_and_b32_e32 v102, 0xffff0000, v18
	v_and_b32_e32 v100, 0xffff0000, v152
	v_and_b32_e32 v98, 0xffff0000, v122
	v_and_b32_e32 v22, 0xffff0000, v121
	v_and_b32_e32 v20, 0xffff0000, v120
	v_and_b32_e32 v18, 0xffff0000, v88
	v_mad_u64_u32 v[134:135], s[2:3], v16, s0, v[92:93]
	v_cvt_pk_bf16_f32 v124, v124, v125
	v_cvt_pk_bf16_f32 v125, v130, v131
	v_cvt_pk_bf16_f32 v126, v126, v127
	v_cvt_pk_bf16_f32 v127, v128, v129
	v_pk_mul_f32 v[114:115], v[132:133], v[114:115] op_sel_hi:[0,1]
	v_pk_mul_f32 v[112:113], v[132:133], v[112:113] op_sel_hi:[0,1]
	v_pk_mul_f32 v[110:111], v[132:133], v[110:111] op_sel_hi:[0,1]
	v_pk_mul_f32 v[108:109], v[132:133], v[108:109] op_sel_hi:[0,1]
	v_pk_mul_f32 v[106:107], v[132:133], v[106:107] op_sel_hi:[0,1]
	v_pk_mul_f32 v[104:105], v[132:133], v[104:105] op_sel_hi:[0,1]
	v_pk_mul_f32 v[102:103], v[132:133], v[102:103] op_sel_hi:[0,1]
	v_pk_mul_f32 v[100:101], v[132:133], v[100:101] op_sel_hi:[0,1]
	v_pk_mul_f32 v[98:99], v[132:133], v[98:99] op_sel_hi:[0,1]
	v_pk_mul_f32 v[22:23], v[132:133], v[22:23] op_sel_hi:[0,1]
	v_pk_mul_f32 v[20:21], v[132:133], v[20:21] op_sel_hi:[0,1]
	v_pk_mul_f32 v[18:19], v[132:133], v[18:19] op_sel_hi:[0,1]
	ds_write_b128 v134, v[124:127] offset:9216
	v_cvt_pk_bf16_f32 v124, v114, v115
	v_cvt_pk_bf16_f32 v125, v112, v113
	v_cvt_pk_bf16_f32 v126, v110, v111
	v_cvt_pk_bf16_f32 v127, v108, v109
	v_cvt_pk_bf16_f32 v106, v106, v107
	v_cvt_pk_bf16_f32 v107, v104, v105
	v_cvt_pk_bf16_f32 v108, v102, v103
	v_cvt_pk_bf16_f32 v109, v100, v101
	v_cvt_pk_bf16_f32 v98, v98, v99
	v_cvt_pk_bf16_f32 v99, v22, v23
	v_cvt_pk_bf16_f32 v100, v20, v21
	v_cvt_pk_bf16_f32 v101, v18, v19
	v_lshl_add_u32 v16, v16, 2, v92
	ds_write_b128 v134, v[124:127] offset:9232
	ds_write_b128 v134, v[106:109] offset:9248
	ds_write_b128 v134, v[98:101] offset:9264
	ds_write_b32 v16, v132 offset:19456
	ds_write_b128 v134, v[12:15] offset:14336
	ds_write_b128 v134, v[8:11] offset:14352
	ds_write_b128 v134, v[4:7] offset:14368
	ds_write_b128 v134, v[0:3] offset:14384
	s_waitcnt lgkmcnt(0)
	v_or_b32_e32 v88, v95, v118
	v_lshlrev_b64 v[0:1], 11, v[88:89]
	v_lshlrev_b32_e32 v100, 2, v119
	v_lshl_add_u64 v[0:1], s[40:41], 0, v[0:1]
	v_ashrrev_i32_e32 v101, 31, v100
	v_mad_u32_u24 v106, v118, s48, v92
	v_lshlrev_b32_e32 v95, 4, v119
	v_lshl_add_u64 v[0:1], v[0:1], 0, v[90:91]
	v_lshlrev_b64 v[102:103], 1, v[100:101]
	v_add_u32_e32 v107, v106, v95
	v_lshl_add_u64 v[104:105], v[0:1], 0, v[102:103]
	ds_read_b128 v[0:3], v107 offset:4608
	ds_read_b128 v[4:7], v107
	ds_read_b128 v[16:19], v107 offset:32
	ds_read_b128 v[20:23], v107 offset:4640
	s_waitcnt lgkmcnt(2)
	v_mfma_f32_32x32x16_bf16 v[0:15], v[0:3], v[4:7], 0
	v_cmp_ge_i32_e32 vcc, v100, v118
	v_cvt_pk_bf16_f32 v120, v32, v33
	v_cvt_pk_bf16_f32 v121, v34, v35
	v_cvt_pk_bf16_f32 v122, v36, v37
	v_cvt_pk_bf16_f32 v123, v38, v39
	v_lshl_add_u64 v[98:99], v[104:105], 0, s[4:5]
	global_load_dwordx2 v[196:197], v[98:99], off
	global_load_dwordx2 v[198:199], v[98:99], off offset:16
	global_load_dwordx2 v[200:201], v[98:99], off offset:32
	global_load_dwordx2 v[202:203], v[98:99], off offset:48
	global_load_dwordx2 v[230:231], v[98:99], off offset:64
	global_load_dwordx2 v[232:233], v[98:99], off offset:80
	global_load_dwordx2 v[234:235], v[98:99], off offset:96
	global_load_dwordx2 v[240:241], v[98:99], off offset:112
	s_waitcnt lgkmcnt(0)
	v_mfma_f32_32x32x16_bf16 v[0:15], v[20:23], v[16:19], v[0:15]
	ds_read_b128 v[16:19], v107 offset:4672
	ds_read_b128 v[20:23], v107 offset:64
	s_waitcnt lgkmcnt(0)
	v_mfma_f32_32x32x16_bf16 v[0:15], v[16:19], v[20:23], v[0:15]
	ds_read_b128 v[16:19], v107 offset:4704
	ds_read_b128 v[20:23], v107 offset:96
	s_waitcnt lgkmcnt(0)
	v_mfma_f32_32x32x16_bf16 v[0:15], v[16:19], v[20:23], v[0:15]
	v_or_b32_e32 v16, 1, v100
	s_nop 10
	v_cndmask_b32_e32 v0, 0, v0, vcc
	v_cmp_ge_i32_e32 vcc, v16, v118
	v_or_b32_e32 v16, 2, v100
	s_nop 0
	v_cndmask_b32_e32 v1, 0, v1, vcc
	v_cmp_ge_i32_e32 vcc, v16, v118
	v_or_b32_e32 v16, 3, v100
	s_nop 0
	v_cndmask_b32_e32 v2, 0, v2, vcc
	v_cmp_ge_i32_e32 vcc, v16, v118
	v_add_u32_e32 v16, 8, v100
	s_nop 0
	v_cndmask_b32_e32 v3, 0, v3, vcc
	v_cmp_ge_i32_e32 vcc, v16, v118
	v_add_u32_e32 v16, 9, v100
	v_cvt_pk_bf16_f32 v17, v2, v3
	v_cndmask_b32_e32 v4, 0, v4, vcc
	v_cmp_ge_i32_e32 vcc, v16, v118
	v_add_u32_e32 v16, 10, v100
	s_nop 0
	v_cndmask_b32_e32 v5, 0, v5, vcc
	v_cmp_ge_i32_e32 vcc, v16, v118
	v_add_u32_e32 v16, 11, v100
	v_cvt_pk_bf16_f32 v18, v4, v5
	v_cndmask_b32_e32 v6, 0, v6, vcc
	v_cmp_ge_i32_e32 vcc, v16, v118
	v_add_u32_e32 v16, 16, v100
	s_nop 0
	v_cndmask_b32_e32 v7, 0, v7, vcc
	v_cmp_ge_i32_e32 vcc, v16, v118
	v_add_u32_e32 v16, 17, v100
	v_cvt_pk_bf16_f32 v19, v6, v7
	v_cndmask_b32_e32 v8, 0, v8, vcc
	v_cmp_ge_i32_e32 vcc, v16, v118
	v_add_u32_e32 v16, 18, v100
	s_nop 0
	v_cndmask_b32_e32 v9, 0, v9, vcc
	v_cmp_ge_i32_e32 vcc, v16, v118
	v_add_u32_e32 v16, 19, v100
	v_cvt_pk_bf16_f32 v20, v8, v9
	v_cndmask_b32_e32 v10, 0, v10, vcc
	v_cmp_ge_i32_e32 vcc, v16, v118
	v_add_u32_e32 v16, 24, v100
	s_nop 0
	v_cndmask_b32_e32 v11, 0, v11, vcc
	v_cmp_ge_i32_e32 vcc, v16, v118
	v_add_u32_e32 v16, 25, v100
	v_cvt_pk_bf16_f32 v21, v10, v11
	v_cndmask_b32_e32 v12, 0, v12, vcc
	v_cmp_ge_i32_e32 vcc, v16, v118
	v_add_u32_e32 v16, 26, v100
	s_nop 0
	v_cndmask_b32_e32 v13, 0, v13, vcc
	v_cmp_ge_i32_e32 vcc, v16, v118
	v_add_u32_e32 v16, 27, v100
	v_cvt_pk_bf16_f32 v22, v12, v13
	v_cndmask_b32_e32 v14, 0, v14, vcc
	v_cmp_ge_i32_e32 vcc, v16, v118
	v_cvt_pk_bf16_f32 v16, v0, v1
	v_lshlrev_b32_e32 v0, 3, v119
	v_mul_u32_u24_e32 v1, 0x50, v118
	v_add3_u32 v107, v92, v0, v1
	v_add_u32_e32 v4, 0x3800, v107
	v_add_u32_e32 v106, v106, v0
	ds_read2_b64 v[0:3], v4 offset1:2
	ds_read2_b64 v[108:111], v4 offset0:4 offset1:6
	v_cndmask_b32_e32 v15, 0, v15, vcc
	v_cvt_pk_bf16_f32 v23, v14, v15
	s_waitcnt lgkmcnt(1)
	v_mfma_f32_32x32x16_bf16 v[0:15], v[0:3], v[16:19], 0
	v_add_co_u32_e32 v104, vcc, s6, v104
	s_nop 1
	v_addc_co_u32_e32 v105, vcc, 0, v105, vcc
	s_waitcnt lgkmcnt(0)
	v_mfma_f32_32x32x16_bf16 v[0:15], v[108:111], v[20:23], v[0:15]
	ds_read2_b64 v[108:111], v106 offset1:2
	ds_read2_b64 v[112:115], v106 offset0:4 offset1:6
	s_waitcnt lgkmcnt(1)
	v_mfma_f32_32x32x16_bf16 v[0:15], v[120:123], v[108:111], v[0:15]
	v_cvt_pk_bf16_f32 v108, v40, v41
	v_cvt_pk_bf16_f32 v109, v42, v43
	v_cvt_pk_bf16_f32 v110, v44, v45
	v_cvt_pk_bf16_f32 v111, v46, v47
	s_waitcnt lgkmcnt(0)
	s_nop 0
	v_mfma_f32_32x32x16_bf16 v[0:15], v[108:111], v[112:115], v[0:15]
	ds_read2_b64 v[108:111], v106 offset0:8 offset1:10
	v_cvt_pk_bf16_f32 v112, v54, v55
	v_cvt_pk_bf16_f32 v113, v50, v51
	v_cvt_pk_bf16_f32 v114, v52, v53
	v_cvt_pk_bf16_f32 v115, v82, v83
	s_waitcnt lgkmcnt(0)
	s_nop 0
	v_mfma_f32_32x32x16_bf16 v[0:15], v[112:115], v[108:111], v[0:15]
	ds_read2_b64 v[108:111], v106 offset0:12 offset1:14
	v_cvt_pk_bf16_f32 v112, v56, v57
	v_cvt_pk_bf16_f32 v113, v58, v59
	v_cvt_pk_bf16_f32 v114, v60, v61
	v_cvt_pk_bf16_f32 v115, v62, v63
	s_waitcnt lgkmcnt(0)
	s_nop 0
	v_mfma_f32_32x32x16_bf16 v[0:15], v[112:115], v[108:111], v[0:15]
	s_waitcnt vmcnt(7)
	v_lshlrev_b32_e32 v110, 16, v196
	v_and_b32_e32 v111, 0xffff0000, v196
	s_nop 7
	v_pk_add_f32 v[0:1], v[0:1], v[110:111]
	v_lshlrev_b32_e32 v108, 16, v197
	v_and_b32_e32 v109, 0xffff0000, v197
	v_pk_add_f32 v[2:3], v[2:3], v[108:109]
	v_mul_f32_e32 v108, v1, v1
	v_pk_fma_f32 v[108:109], v[0:1], v[0:1], v[108:109] op_sel_hi:[1,1,0]
	v_cvt_pk_bf16_f32 v0, v0, v1
	v_cvt_pk_bf16_f32 v1, v2, v3
	global_store_dwordx2 v[104:105], v[0:1], off offset:1536
	v_mul_f32_e32 v110, v3, v3
	v_pk_fma_f32 v[110:111], v[2:3], v[2:3], v[110:111] op_sel_hi:[1,1,0]
	s_waitcnt vmcnt(7)
	v_lshlrev_b32_e32 v2, 16, v198
	v_and_b32_e32 v3, 0xffff0000, v198
	v_lshlrev_b32_e32 v0, 16, v199
	v_and_b32_e32 v1, 0xffff0000, v199
	v_pk_add_f32 v[2:3], v[4:5], v[2:3]
	v_pk_add_f32 v[0:1], v[6:7], v[0:1]
	v_mul_f32_e32 v4, v3, v3
	v_mul_f32_e32 v6, v1, v1
	v_pk_fma_f32 v[4:5], v[2:3], v[2:3], v[4:5] op_sel_hi:[1,1,0]
	v_pk_fma_f32 v[6:7], v[0:1], v[0:1], v[6:7] op_sel_hi:[1,1,0]
	v_cvt_pk_bf16_f32 v2, v2, v3
	v_cvt_pk_bf16_f32 v3, v0, v1
	v_pk_add_f32 v[4:5], v[4:5], v[6:7]
	global_store_dwordx2 v[98:99], v[2:3], off offset:16
	v_pk_add_f32 v[108:109], v[108:109], v[110:111]
	s_waitcnt vmcnt(7)
	v_lshlrev_b32_e32 v2, 16, v200
	v_and_b32_e32 v3, 0xffff0000, v200
	v_pk_add_f32 v[2:3], v[8:9], v[2:3]
	v_lshlrev_b32_e32 v0, 16, v201
	v_and_b32_e32 v1, 0xffff0000, v201
	v_pk_add_f32 v[6:7], v[10:11], v[0:1]
	v_mul_f32_e32 v0, v3, v3
	v_pk_fma_f32 v[0:1], v[2:3], v[2:3], v[0:1] op_sel_hi:[1,1,0]
	v_cvt_pk_bf16_f32 v2, v2, v3
	v_cvt_pk_bf16_f32 v3, v6, v7
	global_store_dwordx2 v[98:99], v[2:3], off offset:32
	v_mul_f32_e32 v8, v7, v7
	v_pk_fma_f32 v[8:9], v[6:7], v[6:7], v[8:9] op_sel_hi:[1,1,0]
	v_pk_add_f32 v[4:5], v[108:109], v[4:5]
	v_pk_add_f32 v[0:1], v[0:1], v[8:9]
	s_nop 0
	v_pk_add_f32 v[0:1], v[4:5], v[0:1]
	s_waitcnt vmcnt(7)
	v_lshlrev_b32_e32 v4, 16, v202
	v_and_b32_e32 v5, 0xffff0000, v202
	v_lshlrev_b32_e32 v2, 16, v203
	v_and_b32_e32 v3, 0xffff0000, v203
	v_pk_add_f32 v[4:5], v[12:13], v[4:5]
	v_pk_add_f32 v[2:3], v[14:15], v[2:3]
	v_mul_f32_e32 v6, v5, v5
	v_mul_f32_e32 v8, v3, v3
	v_pk_fma_f32 v[6:7], v[4:5], v[4:5], v[6:7] op_sel_hi:[1,1,0]
	v_pk_fma_f32 v[8:9], v[2:3], v[2:3], v[8:9] op_sel_hi:[1,1,0]
	s_nop 0
	v_pk_add_f32 v[6:7], v[6:7], v[8:9]
	s_nop 0
	v_pk_add_f32 v[112:113], v[0:1], v[6:7]
	v_cvt_pk_bf16_f32 v0, v4, v5
	v_cvt_pk_bf16_f32 v1, v2, v3
	global_store_dwordx2 v[98:99], v[0:1], off offset:48
	v_add_u32_e32 v4, 0x4000, v107
	ds_read2_b64 v[0:3], v4 offset0:64 offset1:66
	ds_read2_b64 v[108:111], v4 offset0:68 offset1:70
	s_waitcnt lgkmcnt(1)
	v_mfma_f32_32x32x16_bf16 v[0:15], v[0:3], v[16:19], 0
	s_waitcnt lgkmcnt(0)
	v_mfma_f32_32x32x16_bf16 v[0:15], v[108:111], v[20:23], v[0:15]
	v_cvt_pk_bf16_f32 v108, v26, v27
	v_cvt_pk_bf16_f32 v109, v28, v29
	v_cvt_pk_bf16_f32 v110, v30, v31
	v_cvt_pk_bf16_f32 v111, v48, v49
	ds_read2_b64 v[16:19], v106 offset1:2
	ds_read2_b64 v[20:23], v106 offset0:4 offset1:6
	s_waitcnt lgkmcnt(1)
	v_mfma_f32_32x32x16_bf16 v[0:15], v[108:111], v[16:19], v[0:15]
	v_cvt_pk_bf16_f32 v16, v24, v25
	v_cvt_pk_bf16_f32 v17, v84, v85
	v_cvt_pk_bf16_f32 v18, v86, v87
	v_cvt_pk_bf16_f32 v19, v96, v97
	s_waitcnt lgkmcnt(0)
	s_nop 0
	v_mfma_f32_32x32x16_bf16 v[0:15], v[16:19], v[20:23], v[0:15]
	ds_read2_b64 v[16:19], v106 offset0:8 offset1:10
	v_cvt_pk_bf16_f32 v20, v66, v67
	v_cvt_pk_bf16_f32 v21, v68, v69
	v_cvt_pk_bf16_f32 v22, v70, v71
	v_cvt_pk_bf16_f32 v23, v72, v73
	s_waitcnt lgkmcnt(0)
	s_nop 0
	v_mfma_f32_32x32x16_bf16 v[0:15], v[20:23], v[16:19], v[0:15]
	ds_read2_b64 v[16:19], v106 offset0:12 offset1:14
	v_cvt_pk_bf16_f32 v20, v74, v75
	v_cvt_pk_bf16_f32 v21, v76, v77
	v_cvt_pk_bf16_f32 v22, v78, v79
	v_cvt_pk_bf16_f32 v23, v80, v81
	s_waitcnt lgkmcnt(0)
	s_nop 0
	v_mfma_f32_32x32x16_bf16 v[0:15], v[20:23], v[16:19], v[0:15]
	s_waitcnt vmcnt(7)
	v_lshlrev_b32_e32 v18, 16, v230
	v_and_b32_e32 v19, 0xffff0000, v230
	s_nop 7
	v_pk_add_f32 v[0:1], v[0:1], v[18:19]
	v_lshlrev_b32_e32 v16, 16, v231
	v_and_b32_e32 v17, 0xffff0000, v231
	v_pk_add_f32 v[2:3], v[2:3], v[16:17]
	v_mul_f32_e32 v16, v1, v1
	v_pk_fma_f32 v[16:17], v[0:1], v[0:1], v[16:17] op_sel_hi:[1,1,0]
	v_cvt_pk_bf16_f32 v0, v0, v1
	v_cvt_pk_bf16_f32 v1, v2, v3
	global_store_dwordx2 v[98:99], v[0:1], off offset:64
	v_mul_f32_e32 v18, v3, v3
	v_pk_fma_f32 v[18:19], v[2:3], v[2:3], v[18:19] op_sel_hi:[1,1,0]
	s_waitcnt vmcnt(7)
	v_lshlrev_b32_e32 v2, 16, v232
	v_and_b32_e32 v3, 0xffff0000, v232
	v_lshlrev_b32_e32 v0, 16, v233
	v_and_b32_e32 v1, 0xffff0000, v233
	v_pk_add_f32 v[2:3], v[4:5], v[2:3]
	v_pk_add_f32 v[0:1], v[6:7], v[0:1]
	v_mul_f32_e32 v4, v3, v3
	v_mul_f32_e32 v6, v1, v1
	v_pk_fma_f32 v[4:5], v[2:3], v[2:3], v[4:5] op_sel_hi:[1,1,0]
	v_pk_fma_f32 v[6:7], v[0:1], v[0:1], v[6:7] op_sel_hi:[1,1,0]
	v_cvt_pk_bf16_f32 v2, v2, v3
	v_cvt_pk_bf16_f32 v3, v0, v1
	v_pk_add_f32 v[4:5], v[4:5], v[6:7]
	global_store_dwordx2 v[98:99], v[2:3], off offset:80
	v_pk_add_f32 v[16:17], v[16:17], v[18:19]
	s_waitcnt vmcnt(7)
	v_lshlrev_b32_e32 v2, 16, v234
	v_and_b32_e32 v3, 0xffff0000, v234
	v_lshlrev_b32_e32 v0, 16, v235
	v_and_b32_e32 v1, 0xffff0000, v235
	v_pk_add_f32 v[2:3], v[8:9], v[2:3]
	v_pk_add_f32 v[6:7], v[10:11], v[0:1]
	v_mov_b32_e32 v0, v2
	v_mov_b32_e32 v8, v3
	v_cvt_pk_bf16_f32 v2, v2, v3
	v_cvt_pk_bf16_f32 v3, v6, v7
	global_store_dwordx2 v[98:99], v[2:3], off offset:96
	v_mov_b32_e32 v9, v7
	v_mov_b32_e32 v1, v6
	v_pk_mul_f32 v[8:9], v[8:9], v[8:9]
	v_pk_add_f32 v[16:17], v[112:113], v[16:17]
	v_pk_fma_f32 v[0:1], v[0:1], v[0:1], v[8:9]
	v_pk_add_f32 v[4:5], v[16:17], v[4:5]
	v_pk_add_f32 v[0:1], v[0:1], v[0:1] op_sel:[0,1] op_sel_hi:[1,0]
	s_nop 0
	v_pk_add_f32 v[0:1], v[4:5], v[0:1]
	s_waitcnt vmcnt(7)
	v_lshlrev_b32_e32 v4, 16, v240
	v_and_b32_e32 v5, 0xffff0000, v240
	v_lshlrev_b32_e32 v2, 16, v241
	v_and_b32_e32 v3, 0xffff0000, v241
	v_pk_add_f32 v[4:5], v[12:13], v[4:5]
	v_pk_add_f32 v[2:3], v[14:15], v[2:3]
	v_mov_b32_e32 v8, v5
	v_mov_b32_e32 v9, v3
	v_mov_b32_e32 v6, v4
	v_mov_b32_e32 v7, v2
	v_pk_mul_f32 v[8:9], v[8:9], v[8:9]
	s_nop 0
	v_pk_fma_f32 v[6:7], v[6:7], v[6:7], v[8:9]
	s_nop 0
	v_pk_add_f32 v[6:7], v[6:7], v[6:7] op_sel:[0,1] op_sel_hi:[1,0]
	s_nop 0
	v_pk_add_f32 v[114:115], v[0:1], v[6:7]
	v_cvt_pk_bf16_f32 v0, v4, v5
	v_cvt_pk_bf16_f32 v1, v2, v3
	global_store_dwordx2 v[98:99], v[0:1], off offset:112
	v_add_u32_e32 v95, v92, v95
	v_mad_u32_u24 v115, v118, s0, v95
	ds_read_b128 v[0:3], v95 offset:19456
	ds_read_b128 v[4:7], v95 offset:19488
	ds_read_b128 v[8:11], v95 offset:19520
	ds_read_b128 v[12:15], v95 offset:19552
	ds_read_b128 v[16:19], v115 offset:9216
	ds_read_b128 v[20:23], v115 offset:14336
	ds_read_b128 v[106:109], v115 offset:9248
	ds_read_b128 v[110:113], v115 offset:14368
	ds_read_b128 v[118:121], v115 offset:16896
	s_waitcnt lgkmcnt(8)
	v_pk_mul_f32 v[34:35], v[2:3], v[34:35]
	v_pk_mul_f32 v[32:33], v[0:1], v[32:33]
	s_waitcnt lgkmcnt(7)
	v_pk_mul_f32 v[38:39], v[6:7], v[38:39]
	v_pk_mul_f32 v[36:37], v[4:5], v[36:37]
	s_waitcnt lgkmcnt(6)
	v_pk_mul_f32 v[42:43], v[10:11], v[42:43]
	v_pk_mul_f32 v[40:41], v[8:9], v[40:41]
	s_waitcnt lgkmcnt(5)
	v_pk_mul_f32 v[46:47], v[14:15], v[46:47]
	v_pk_mul_f32 v[44:45], v[12:13], v[44:45]
	v_pk_mul_f32 v[0:1], v[0:1], v[26:27]
	v_pk_mul_f32 v[2:3], v[2:3], v[28:29]
	v_pk_mul_f32 v[4:5], v[4:5], v[30:31]
	v_pk_mul_f32 v[6:7], v[6:7], v[48:49]
	v_pk_mul_f32 v[8:9], v[8:9], v[24:25]
	v_pk_mul_f32 v[10:11], v[10:11], v[84:85]
	v_pk_mul_f32 v[12:13], v[12:13], v[86:87]
	v_pk_mul_f32 v[14:15], v[14:15], v[96:97]
	s_waitcnt lgkmcnt(3)
	v_mfma_f32_32x32x16_bf16 v[32:47], v[16:19], v[20:23], v[32:47]
	ds_read_b128 v[84:87], v115 offset:16928
	s_movk_i32 s4, 0x50
	s_waitcnt lgkmcnt(1)
	v_mfma_f32_32x32x16_bf16 v[0:15], v[16:19], v[118:121], v[0:15]
	v_mfma_f32_32x32x16_bf16 v[32:47], v[106:109], v[110:113], v[32:47]
	s_waitcnt lgkmcnt(0)
	v_mfma_f32_32x32x16_bf16 v[0:15], v[106:109], v[84:87], v[0:15]
	ds_read_b128 v[16:19], v95 offset:19584
	ds_read_b128 v[24:27], v95 offset:19616
	ds_read_b128 v[28:31], v95 offset:19648
	ds_read_b128 v[106:109], v95 offset:19680
	ds_read_b128 v[122:125], v115 offset:11776
	s_waitcnt lgkmcnt(4)
	v_pk_mul_f32 v[50:51], v[18:19], v[50:51]
	v_pk_mul_f32 v[48:49], v[16:17], v[54:55]
	s_waitcnt lgkmcnt(3)
	v_pk_mul_f32 v[54:55], v[26:27], v[82:83]
	v_pk_mul_f32 v[52:53], v[24:25], v[52:53]
	s_waitcnt lgkmcnt(2)
	v_pk_mul_f32 v[58:59], v[30:31], v[58:59]
	v_pk_mul_f32 v[56:57], v[28:29], v[56:57]
	s_waitcnt lgkmcnt(1)
	v_pk_mul_f32 v[62:63], v[108:109], v[62:63]
	v_pk_mul_f32 v[60:61], v[106:107], v[60:61]
	ds_read_b128 v[126:129], v115 offset:11808
	v_pk_mul_f32 v[16:17], v[16:17], v[66:67]
	s_waitcnt lgkmcnt(1)
	v_mfma_f32_32x32x16_bf16 v[48:63], v[122:125], v[20:23], v[48:63]
	v_mul_f32_e64 v18, v18, v68
	v_mul_f32_e64 v19, v19, v69
	v_mul_f32_e64 v20, v24, v70
	v_mul_f32_e64 v21, v25, v71
	v_mul_f32_e64 v22, v26, v72
	v_mul_f32_e64 v23, v27, v73
	v_pk_mul_f32 v[24:25], v[28:29], v[74:75]
	v_pk_mul_f32 v[26:27], v[30:31], v[76:77]
	v_pk_mul_f32 v[28:29], v[106:107], v[78:79]
	v_pk_mul_f32 v[30:31], v[108:109], v[80:81]
	s_waitcnt lgkmcnt(0)
	s_waitcnt lgkmcnt(0)
	v_mfma_f32_32x32x16_bf16 v[48:63], v[126:129], v[110:113], v[48:63]
	v_mfma_f32_32x32x16_bf16 v[16:31], v[122:125], v[118:121], v[16:31]
	v_mfma_f32_32x32x16_bf16 v[16:31], v[126:129], v[84:87], v[16:31]
	v_mad_i64_i32 v[64:65], s[2:3], v88, s1, v[64:65]
	v_lshl_add_u64 v[64:65], v[64:65], 0, v[90:91]
	v_lshl_add_u64 v[64:65], v[64:65], 0, v[102:103]
	s_mov_b64 s[48:49], 0x1000
	s_movk_i32 s5, 0x1000
	v_lshl_add_u64 v[72:73], v[64:65], 0, s[48:49]
	v_add_co_u32_e32 v64, vcc, s5, v64
	global_load_dwordx2 v[74:75], v[104:105], off offset:1536
	s_nop 0
	v_addc_co_u32_e32 v65, vcc, 0, v65, vcc
	global_load_dwordx2 v[76:77], v[64:65], off
	v_readlane_b32 s0, v255, 18
	v_readlane_b32 s1, v255, 19
	s_add_u32 s2, s40, s0
	v_mov_b32_e32 v66, v114
	s_addc_u32 s3, s41, s1
	s_nop 0
	v_permlane32_swap_b32_e32 v114, v66
	v_lshl_add_u64 v[64:65], v[100:101], 2, s[2:3]
	s_mov_b64 s[2:3], 0x4800
	v_add_f32_e32 v66, v114, v66
	v_lshl_add_u64 v[70:71], v[64:65], 0, s[2:3]
	v_add_co_u32_e32 v64, vcc, s7, v64
	v_fmamk_f32 v66, v66, 0x3c800000, v237
	s_nop 0
	v_addc_co_u32_e32 v65, vcc, 0, v65, vcc
	v_rsq_f32_e32 v68, v66
	global_load_dwordx4 v[64:67], v[64:65], off offset:2048
	global_load_dwordx4 v[206:209], v[70:71], off offset:32
	global_load_dwordx2 v[210:211], v[72:73], off offset:16
	global_load_dwordx2 v[212:213], v[98:99], off offset:16
	global_load_dwordx4 v[214:217], v[70:71], off offset:64
	global_load_dwordx2 v[218:219], v[72:73], off offset:32
	global_load_dwordx2 v[220:221], v[98:99], off offset:32
	global_load_dwordx4 v[222:225], v[70:71], off offset:96
	global_load_dwordx2 v[226:227], v[72:73], off offset:48
	global_load_dwordx2 v[228:229], v[98:99], off offset:48
	s_movk_i32 s6, 0x1200
	s_waitcnt vmcnt(11)
	v_lshlrev_b32_e32 v82, 16, v74
	v_and_b32_e32 v83, 0xffff0000, v74
	v_lshlrev_b32_e32 v74, 16, v75
	s_waitcnt vmcnt(10)
	v_lshlrev_b32_e32 v78, 16, v76
	v_mul_f32_e32 v69, 0xbfb8aa3b, v78
	v_exp_f32_e32 v69, v69
	v_and_b32_e32 v79, 0xffff0000, v76
	v_lshlrev_b32_e32 v76, 16, v77
	v_and_b32_e32 v77, 0xffff0000, v77
	v_add_f32_e32 v69, 1.0, v69
	v_rcp_f32_e32 v80, v69
	v_mul_f32_e32 v69, 0xbfb8aa3b, v79
	v_exp_f32_e32 v69, v69
	v_and_b32_e32 v75, 0xffff0000, v75
	v_add_f32_e32 v69, 1.0, v69
	v_rcp_f32_e32 v81, v69
	v_pk_mul_f32 v[82:83], v[68:69], v[82:83] op_sel_hi:[0,1]
	v_pk_mul_f32 v[74:75], v[68:69], v[74:75] op_sel_hi:[0,1]
	s_waitcnt vmcnt(9)
	v_pk_mul_f32 v[64:65], v[64:65], v[82:83]
	v_pk_mul_f32 v[78:79], v[80:81], v[78:79]
	v_pk_mul_f32 v[66:67], v[66:67], v[74:75]
	v_pk_mul_f32 v[64:65], v[64:65], v[78:79]
	s_nop 0
	v_cvt_pk_bf16_f32 v64, v64, v65
	v_mul_f32_e32 v65, 0xbfb8aa3b, v76
	v_exp_f32_e32 v65, v65
	s_nop 0
	v_add_f32_e32 v65, 1.0, v65
	v_rcp_f32_e32 v78, v65
	v_mul_f32_e32 v65, 0xbfb8aa3b, v77
	v_exp_f32_e32 v65, v65
	s_nop 0
	v_add_f32_e32 v65, 1.0, v65
	v_rcp_f32_e32 v79, v65
	s_nop 0
	v_pk_mul_f32 v[74:75], v[78:79], v[76:77]
	s_nop 0
	v_pk_mul_f32 v[66:67], v[66:67], v[74:75]
	s_nop 0
	v_cvt_pk_bf16_f32 v65, v66, v67
	global_store_dwordx2 v[104:105], v[64:65], off offset:1536
	s_nop 0
	s_waitcnt vmcnt(8)
	v_lshlrev_b32_e32 v78, 16, v210
	v_mul_f32_e32 v69, 0xbfb8aa3b, v78
	v_exp_f32_e32 v69, v69
	v_and_b32_e32 v79, 0xffff0000, v210
	s_waitcnt vmcnt(7)
	v_lshlrev_b32_e32 v82, 16, v212
	v_and_b32_e32 v83, 0xffff0000, v212
	v_add_f32_e32 v69, 1.0, v69
	v_rcp_f32_e32 v80, v69
	v_mul_f32_e32 v69, 0xbfb8aa3b, v79
	v_exp_f32_e32 v69, v69
	v_lshlrev_b32_e32 v74, 16, v211
	v_and_b32_e32 v75, 0xffff0000, v211
	v_lshlrev_b32_e32 v76, 16, v213
	v_add_f32_e32 v69, 1.0, v69
	v_rcp_f32_e32 v81, v69
	v_pk_mul_f32 v[82:83], v[68:69], v[82:83] op_sel_hi:[0,1]
	v_pk_mul_f32 v[64:65], v[206:207], v[82:83]
	v_and_b32_e32 v77, 0xffff0000, v213
	v_pk_mul_f32 v[78:79], v[80:81], v[78:79]
	v_pk_mul_f32 v[76:77], v[68:69], v[76:77] op_sel_hi:[0,1]
	v_pk_mul_f32 v[64:65], v[64:65], v[78:79]
	v_pk_mul_f32 v[66:67], v[208:209], v[76:77]
	v_cvt_pk_bf16_f32 v64, v64, v65
	v_mul_f32_e32 v65, 0xbfb8aa3b, v74
	v_exp_f32_e32 v65, v65
	s_nop 0
	v_add_f32_e32 v65, 1.0, v65
	v_rcp_f32_e32 v78, v65
	v_mul_f32_e32 v65, 0xbfb8aa3b, v75
	v_exp_f32_e32 v65, v65
	s_nop 0
	v_add_f32_e32 v65, 1.0, v65
	v_rcp_f32_e32 v79, v65
	s_nop 0
	v_pk_mul_f32 v[74:75], v[78:79], v[74:75]
	s_nop 0
	v_pk_mul_f32 v[66:67], v[66:67], v[74:75]
	s_nop 0
	v_cvt_pk_bf16_f32 v65, v66, v67
	global_store_dwordx2 v[98:99], v[64:65], off offset:16
	s_nop 0
	s_waitcnt vmcnt(6)
	v_lshlrev_b32_e32 v78, 16, v218
	v_mul_f32_e32 v69, 0xbfb8aa3b, v78
	v_exp_f32_e32 v69, v69
	v_and_b32_e32 v79, 0xffff0000, v218
	s_waitcnt vmcnt(5)
	v_lshlrev_b32_e32 v82, 16, v220
	v_and_b32_e32 v83, 0xffff0000, v220
	v_add_f32_e32 v69, 1.0, v69
	v_rcp_f32_e32 v80, v69
	v_mul_f32_e32 v69, 0xbfb8aa3b, v79
	v_exp_f32_e32 v69, v69
	v_lshlrev_b32_e32 v74, 16, v219
	v_and_b32_e32 v75, 0xffff0000, v219
	v_lshlrev_b32_e32 v76, 16, v221
	v_add_f32_e32 v69, 1.0, v69
	v_rcp_f32_e32 v81, v69
	v_pk_mul_f32 v[82:83], v[68:69], v[82:83] op_sel_hi:[0,1]
	v_pk_mul_f32 v[64:65], v[214:215], v[82:83]
	v_and_b32_e32 v77, 0xffff0000, v221
	v_pk_mul_f32 v[78:79], v[80:81], v[78:79]
	v_pk_mul_f32 v[76:77], v[68:69], v[76:77] op_sel_hi:[0,1]
	v_pk_mul_f32 v[64:65], v[64:65], v[78:79]
	v_pk_mul_f32 v[66:67], v[216:217], v[76:77]
	v_cvt_pk_bf16_f32 v64, v64, v65
	v_mul_f32_e32 v65, 0xbfb8aa3b, v74
	v_exp_f32_e32 v65, v65
	s_nop 0
	v_add_f32_e32 v65, 1.0, v65
	v_rcp_f32_e32 v78, v65
	v_mul_f32_e32 v65, 0xbfb8aa3b, v75
	v_exp_f32_e32 v65, v65
	s_nop 0
	v_add_f32_e32 v65, 1.0, v65
	v_rcp_f32_e32 v79, v65
	s_nop 0
	v_pk_mul_f32 v[74:75], v[78:79], v[74:75]
	s_nop 0
	v_pk_mul_f32 v[66:67], v[66:67], v[74:75]
	s_nop 0
	v_cvt_pk_bf16_f32 v65, v66, v67
	global_store_dwordx2 v[98:99], v[64:65], off offset:32
	s_nop 0
	s_waitcnt vmcnt(4)
	v_lshlrev_b32_e32 v78, 16, v226
	v_mul_f32_e32 v69, 0xbfb8aa3b, v78
	v_exp_f32_e32 v69, v69
	v_and_b32_e32 v79, 0xffff0000, v226
	s_waitcnt vmcnt(3)
	v_lshlrev_b32_e32 v82, 16, v228
	v_and_b32_e32 v83, 0xffff0000, v228
	v_add_f32_e32 v69, 1.0, v69
	v_rcp_f32_e32 v80, v69
	v_mul_f32_e32 v69, 0xbfb8aa3b, v79
	v_exp_f32_e32 v69, v69
	v_lshlrev_b32_e32 v74, 16, v227
	v_and_b32_e32 v75, 0xffff0000, v227
	v_lshlrev_b32_e32 v76, 16, v229
	v_add_f32_e32 v69, 1.0, v69
	v_rcp_f32_e32 v81, v69
	v_pk_mul_f32 v[82:83], v[68:69], v[82:83] op_sel_hi:[0,1]
	v_pk_mul_f32 v[64:65], v[222:223], v[82:83]
	v_and_b32_e32 v77, 0xffff0000, v229
	v_pk_mul_f32 v[78:79], v[80:81], v[78:79]
	v_pk_mul_f32 v[76:77], v[68:69], v[76:77] op_sel_hi:[0,1]
	v_pk_mul_f32 v[64:65], v[64:65], v[78:79]
	v_pk_mul_f32 v[66:67], v[224:225], v[76:77]
	v_cvt_pk_bf16_f32 v64, v64, v65
	v_mul_f32_e32 v65, 0xbfb8aa3b, v74
	v_exp_f32_e32 v65, v65
	s_nop 0
	v_add_f32_e32 v65, 1.0, v65
	v_rcp_f32_e32 v78, v65
	v_mul_f32_e32 v65, 0xbfb8aa3b, v75
	v_exp_f32_e32 v65, v65
	s_nop 0
	v_add_f32_e32 v65, 1.0, v65
	v_rcp_f32_e32 v79, v65
	s_nop 0
	v_pk_mul_f32 v[74:75], v[78:79], v[74:75]
	s_nop 0
	v_pk_mul_f32 v[66:67], v[66:67], v[74:75]
	s_nop 0
	v_cvt_pk_bf16_f32 v65, v66, v67
	global_store_dwordx2 v[98:99], v[64:65], off offset:48
	global_load_dwordx2 v[74:75], v[98:99], off offset:64
	global_load_dwordx2 v[76:77], v[72:73], off offset:64
	global_load_dwordx4 v[64:67], v[70:71], off offset:128
	global_load_dwordx2 v[212:213], v[98:99], off offset:80
	global_load_dwordx2 v[210:211], v[72:73], off offset:80
	global_load_dwordx4 v[206:209], v[70:71], off offset:160
	global_load_dwordx2 v[220:221], v[98:99], off offset:96
	global_load_dwordx2 v[218:219], v[72:73], off offset:96
	global_load_dwordx4 v[214:217], v[70:71], off offset:192
	global_load_dwordx2 v[228:229], v[98:99], off offset:112
	global_load_dwordx2 v[226:227], v[72:73], off offset:112
	global_load_dwordx4 v[222:225], v[70:71], off offset:224
	s_waitcnt vmcnt(11)
	v_lshlrev_b32_e32 v82, 16, v74
	s_waitcnt vmcnt(10)
	v_lshlrev_b32_e32 v78, 16, v76
	v_mul_f32_e32 v69, 0xbfb8aa3b, v78
	v_exp_f32_e32 v69, v69
	v_and_b32_e32 v79, 0xffff0000, v76
	v_and_b32_e32 v83, 0xffff0000, v74
	v_lshlrev_b32_e32 v76, 16, v77
	v_add_f32_e32 v69, 1.0, v69
	v_rcp_f32_e32 v80, v69
	v_mul_f32_e32 v69, 0xbfb8aa3b, v79
	v_exp_f32_e32 v69, v69
	v_and_b32_e32 v77, 0xffff0000, v77
	v_lshlrev_b32_e32 v74, 16, v75
	v_and_b32_e32 v75, 0xffff0000, v75
	v_add_f32_e32 v69, 1.0, v69
	v_rcp_f32_e32 v81, v69
	v_pk_mul_f32 v[82:83], v[68:69], v[82:83] op_sel_hi:[0,1]
	s_waitcnt vmcnt(9)
	v_pk_mul_f32 v[64:65], v[64:65], v[82:83]
	v_pk_mul_f32 v[74:75], v[68:69], v[74:75] op_sel_hi:[0,1]
	v_pk_mul_f32 v[78:79], v[80:81], v[78:79]
	v_pk_mul_f32 v[66:67], v[66:67], v[74:75]
	v_pk_mul_f32 v[64:65], v[64:65], v[78:79]
	s_nop 0
	v_cvt_pk_bf16_f32 v64, v64, v65
	v_mul_f32_e32 v65, 0xbfb8aa3b, v76
	v_exp_f32_e32 v65, v65
	s_nop 0
	v_add_f32_e32 v65, 1.0, v65
	v_rcp_f32_e32 v78, v65
	v_mul_f32_e32 v65, 0xbfb8aa3b, v77
	v_exp_f32_e32 v65, v65
	s_nop 0
	v_add_f32_e32 v65, 1.0, v65
	v_rcp_f32_e32 v79, v65
	s_nop 0
	v_pk_mul_f32 v[74:75], v[78:79], v[76:77]
	s_nop 0
	v_pk_mul_f32 v[66:67], v[66:67], v[74:75]
	s_nop 0
	v_cvt_pk_bf16_f32 v65, v66, v67
	global_store_dwordx2 v[98:99], v[64:65], off offset:64
	s_nop 0
	s_waitcnt vmcnt(9)
	v_lshlrev_b32_e32 v82, 16, v212
	s_waitcnt vmcnt(8)
	v_lshlrev_b32_e32 v78, 16, v210
	v_mul_f32_e32 v69, 0xbfb8aa3b, v78
	v_exp_f32_e32 v69, v69
	v_and_b32_e32 v79, 0xffff0000, v210
	v_and_b32_e32 v83, 0xffff0000, v212
	v_lshlrev_b32_e32 v76, 16, v211
	v_add_f32_e32 v69, 1.0, v69
	v_rcp_f32_e32 v80, v69
	v_mul_f32_e32 v69, 0xbfb8aa3b, v79
	v_exp_f32_e32 v69, v69
	v_and_b32_e32 v77, 0xffff0000, v211
	v_lshlrev_b32_e32 v74, 16, v213
	v_and_b32_e32 v75, 0xffff0000, v213
	v_add_f32_e32 v69, 1.0, v69
	v_rcp_f32_e32 v81, v69
	v_pk_mul_f32 v[82:83], v[68:69], v[82:83] op_sel_hi:[0,1]
	s_waitcnt vmcnt(7)
	v_pk_mul_f32 v[64:65], v[206:207], v[82:83]
	v_pk_mul_f32 v[74:75], v[68:69], v[74:75] op_sel_hi:[0,1]
	v_pk_mul_f32 v[78:79], v[80:81], v[78:79]
	v_pk_mul_f32 v[66:67], v[208:209], v[74:75]
	v_pk_mul_f32 v[64:65], v[64:65], v[78:79]
	s_nop 0
	v_cvt_pk_bf16_f32 v64, v64, v65
	v_mul_f32_e32 v65, 0xbfb8aa3b, v76
	v_exp_f32_e32 v65, v65
	s_nop 0
	v_add_f32_e32 v65, 1.0, v65
	v_rcp_f32_e32 v78, v65
	v_mul_f32_e32 v65, 0xbfb8aa3b, v77
	v_exp_f32_e32 v65, v65
	s_nop 0
	v_add_f32_e32 v65, 1.0, v65
	v_rcp_f32_e32 v79, v65
	s_nop 0
	v_pk_mul_f32 v[74:75], v[78:79], v[76:77]
	s_nop 0
	v_pk_mul_f32 v[66:67], v[66:67], v[74:75]
	s_nop 0
	v_cvt_pk_bf16_f32 v65, v66, v67
	global_store_dwordx2 v[98:99], v[64:65], off offset:80
	s_nop 0
	s_waitcnt vmcnt(7)
	v_lshlrev_b32_e32 v82, 16, v220
	s_waitcnt vmcnt(6)
	v_lshlrev_b32_e32 v78, 16, v218
	v_mul_f32_e32 v69, 0xbfb8aa3b, v78
	v_exp_f32_e32 v69, v69
	v_and_b32_e32 v79, 0xffff0000, v218
	v_and_b32_e32 v83, 0xffff0000, v220
	v_lshlrev_b32_e32 v76, 16, v219
	v_add_f32_e32 v69, 1.0, v69
	v_rcp_f32_e32 v80, v69
	v_mul_f32_e32 v69, 0xbfb8aa3b, v79
	v_exp_f32_e32 v69, v69
	v_and_b32_e32 v77, 0xffff0000, v219
	v_lshlrev_b32_e32 v74, 16, v221
	v_and_b32_e32 v75, 0xffff0000, v221
	v_add_f32_e32 v69, 1.0, v69
	v_rcp_f32_e32 v81, v69
	v_pk_mul_f32 v[82:83], v[68:69], v[82:83] op_sel_hi:[0,1]
	s_waitcnt vmcnt(5)
	v_pk_mul_f32 v[64:65], v[214:215], v[82:83]
	v_pk_mul_f32 v[74:75], v[68:69], v[74:75] op_sel_hi:[0,1]
	v_pk_mul_f32 v[78:79], v[80:81], v[78:79]
	v_pk_mul_f32 v[66:67], v[216:217], v[74:75]
	v_pk_mul_f32 v[64:65], v[64:65], v[78:79]
	s_nop 0
	v_cvt_pk_bf16_f32 v64, v64, v65
	v_mul_f32_e32 v65, 0xbfb8aa3b, v76
	v_exp_f32_e32 v65, v65
	s_nop 0
	v_add_f32_e32 v65, 1.0, v65
	v_rcp_f32_e32 v78, v65
	v_mul_f32_e32 v65, 0xbfb8aa3b, v77
	v_exp_f32_e32 v65, v65
	s_nop 0
	v_add_f32_e32 v65, 1.0, v65
	v_rcp_f32_e32 v79, v65
	s_nop 0
	v_pk_mul_f32 v[74:75], v[78:79], v[76:77]
	s_nop 0
	v_pk_mul_f32 v[66:67], v[66:67], v[74:75]
	s_nop 0
	v_cvt_pk_bf16_f32 v65, v66, v67
	global_store_dwordx2 v[98:99], v[64:65], off offset:96
	s_nop 0
	s_nop 0
	s_waitcnt vmcnt(5)
	v_lshlrev_b32_e32 v78, 16, v228
	s_waitcnt vmcnt(4)
	v_lshlrev_b32_e32 v74, 16, v226
	v_mul_f32_e32 v69, 0xbfb8aa3b, v74
	v_exp_f32_e32 v69, v69
	v_and_b32_e32 v75, 0xffff0000, v226
	v_lshlrev_b32_e32 v66, 16, v227
	v_and_b32_e32 v79, 0xffff0000, v228
	v_add_f32_e32 v69, 1.0, v69
	v_rcp_f32_e32 v76, v69
	v_mul_f32_e32 v69, 0xbfb8aa3b, v75
	v_exp_f32_e32 v69, v69
	v_and_b32_e32 v67, 0xffff0000, v227
	v_add_f32_e32 v69, 1.0, v69
	v_rcp_f32_e32 v77, v69
	v_pk_mul_f32 v[78:79], v[68:69], v[78:79] op_sel_hi:[0,1]
	v_mul_f32_e32 v69, 0xbfb8aa3b, v66
	v_exp_f32_e32 v69, v69
	s_waitcnt vmcnt(3)
	v_pk_mul_f32 v[70:71], v[222:223], v[78:79]
	v_pk_mul_f32 v[74:75], v[76:77], v[74:75]
	v_add_f32_e32 v69, 1.0, v69
	v_pk_mul_f32 v[70:71], v[70:71], v[74:75]
	v_lshlrev_b32_e32 v74, 16, v229
	v_cvt_pk_bf16_f32 v64, v70, v71
	v_rcp_f32_e32 v70, v69
	v_mul_f32_e32 v69, 0xbfb8aa3b, v67
	v_exp_f32_e32 v69, v69
	v_and_b32_e32 v75, 0xffff0000, v229
	v_add_f32_e32 v69, 1.0, v69
	v_rcp_f32_e32 v71, v69
	v_pk_mul_f32 v[68:69], v[68:69], v[74:75] op_sel_hi:[0,1]
	v_pk_mul_f32 v[68:69], v[224:225], v[68:69]
	v_pk_mul_f32 v[66:67], v[70:71], v[66:67]
	s_nop 0
	v_pk_mul_f32 v[66:67], v[68:69], v[66:67]
	s_nop 0
	v_cvt_pk_bf16_f32 v65, v66, v67
	global_store_dwordx2 v[98:99], v[64:65], off offset:112
	s_add_u32 s2, s12, 0xb200000
	v_and_b32_e32 v114, 31, v94
	v_ashrrev_i32_e32 v115, 5, v94
	s_addc_u32 s3, s13, 0
	v_mov_b64_e32 v[96:97], s[2:3]
	v_mad_i64_i32 v[64:65], s[2:3], v93, s6, v[96:97]
	v_ashrrev_i32_e32 v95, 31, v94
	v_lshl_add_u64 v[64:65], v[64:65], 0, v[90:91]
	v_lshl_add_u64 v[64:65], v[94:95], 1, v[64:65]
	v_add_co_u32_e32 v76, vcc, s37, v64
	s_movk_i32 s2, 0x5000
	s_nop 0
	v_addc_co_u32_e32 v77, vcc, 0, v65, vcc
	global_load_ushort v95, v[76:77], off offset:3072
	global_load_ushort v107, v[76:77], off offset:1536
	v_add_co_u32_e32 v66, vcc, s20, v64
	v_lshl_add_u32 v88, v94, 1, v92
	s_nop 0
	v_addc_co_u32_e32 v67, vcc, 0, v65, vcc
	v_add_co_u32_e32 v68, vcc, s2, v64
	s_movk_i32 s2, 0x7000
	s_nop 0
	v_addc_co_u32_e32 v69, vcc, 0, v65, vcc
	v_add_co_u32_e32 v70, vcc, s2, v64
	s_mov_b32 s2, 0x10000
	s_nop 0
	v_addc_co_u32_e32 v71, vcc, 0, v65, vcc
	v_add_co_u32_e32 v80, vcc, s28, v64
	s_waitcnt vmcnt(0)
	v_lshlrev_b32_e32 v107, 16, v107
	v_addc_co_u32_e32 v81, vcc, 0, v65, vcc
	v_add_co_u32_e32 v82, vcc, s29, v64
	v_readlane_b32 s28, v255, 28
	s_nop 0
	v_addc_co_u32_e32 v83, vcc, 0, v65, vcc
	v_add_co_u32_e32 v84, vcc, s18, v64
	v_readlane_b32 s29, v255, 29
	s_nop 0
	v_addc_co_u32_e32 v85, vcc, 0, v65, vcc
	v_add_co_u32_e32 v86, vcc, s2, v64
	s_mov_b32 s2, 0x14000
	s_nop 0
	v_addc_co_u32_e32 v87, vcc, 0, v65, vcc
	v_add_co_u32_e32 v72, vcc, s51, v64
	s_nop 1
	v_addc_co_u32_e32 v73, vcc, 0, v65, vcc
	v_add_co_u32_e32 v74, vcc, s2, v64
	s_mov_b32 s2, 0x1a000
	s_nop 0
	v_addc_co_u32_e32 v75, vcc, 0, v65, vcc
	v_add_co_u32_e32 v78, vcc, s30, v64
	s_nop 1
	v_addc_co_u32_e32 v79, vcc, 0, v65, vcc
	v_add_co_u32_e32 v98, vcc, s31, v64
	s_mov_b64 s[30:31], 0x4800
	s_nop 0
	v_addc_co_u32_e32 v99, vcc, 0, v65, vcc
	v_add_co_u32_e32 v100, vcc, s34, v64
	s_nop 1
	v_addc_co_u32_e32 v101, vcc, 0, v65, vcc
	v_add_co_u32_e32 v102, vcc, s35, v64
	s_mov_b64 s[34:35], 0x1200
	s_nop 0
	v_addc_co_u32_e32 v103, vcc, 0, v65, vcc
	v_add_co_u32_e32 v104, vcc, s19, v64
	v_readlane_b32 s18, v255, 26
	s_nop 0
	v_addc_co_u32_e32 v105, vcc, 0, v65, vcc
	v_add_co_u32_e32 v118, vcc, s36, v64
	v_readlane_b32 s36, v255, 30
	s_nop 0
	v_addc_co_u32_e32 v119, vcc, 0, v65, vcc
	v_add_co_u32_e32 v108, vcc, s21, v64
	v_readlane_b32 s19, v255, 27
	s_nop 0
	v_addc_co_u32_e32 v109, vcc, 0, v65, vcc
	global_load_ushort v111, v[108:109], off offset:512
	global_load_ushort v106, v[108:109], off offset:1024
	global_load_ushort v113, v[108:109], off offset:2048
	s_nop 0
	global_load_ushort v108, v[76:77], off offset:2048
	global_load_ushort v110, v[118:119], off offset:1536
	global_load_ushort v120, v[118:119], off offset:2560
	global_load_ushort v121, v[102:103], off offset:3584
	global_load_ushort v122, v[104:105], off offset:512
	global_load_ushort v152, v[118:119], off offset:1024
	global_load_ushort v153, v[104:105], off offset:1536
	global_load_ushort v154, v[104:105], off
	global_load_ushort v158, v[102:103], off offset:3072
	global_load_ushort v160, v[102:103], off
	global_load_ushort v165, v[100:101], off offset:3584
	v_lshlrev_b32_e32 v76, 16, v95
	v_max_f32_e32 v76, v76, v76
	v_med3_f32 v76, v76, s9, v244
	v_mul_f32_e32 v76, 0xbfb8aa3b, v76
	v_exp_f32_e32 v95, v76
	v_add_co_u32_e32 v76, vcc, s42, v64
	global_load_ushort v123, v[78:79], off offset:512
	global_load_ushort v124, v[98:99], off offset:1536
	global_load_ushort v126, v[100:101], off offset:2560
	global_load_ushort v166, v[100:101], off offset:2048
	global_load_ushort v168, v[98:99], off offset:2560
	global_load_ushort v171, v[98:99], off offset:1024
	global_load_ushort v167, v[78:79], off offset:1536
	global_load_ushort v163, v[78:79], off
	v_add_f32_e32 v109, 1.0, v95
	v_addc_co_u32_e32 v77, vcc, 0, v65, vcc
	v_rcp_f32_e32 v109, v109
	v_add_co_u32_e32 v134, vcc, s17, v64
	v_readlane_b32 s37, v255, 31
	s_nop 0
	v_addc_co_u32_e32 v135, vcc, 0, v65, vcc
	v_add_co_u32_e32 v132, vcc, s16, v64
	v_fma_f32 v112, v117, v109, v116
	s_nop 0
	v_addc_co_u32_e32 v133, vcc, 0, v65, vcc
	v_max_f32_e32 v150, 0xda24260, v112
	v_add_co_u32_e32 v118, vcc, s2, v64
	v_mul_f32_e32 v95, v95, v109
	v_rcp_f32_e32 v109, v150
	v_addc_co_u32_e32 v119, vcc, 0, v65, vcc
	s_mov_b32 s2, 0x18000
	v_add_co_u32_e32 v136, vcc, s2, v64
	s_mov_b32 s2, 0x16000
	s_nop 0
	v_addc_co_u32_e32 v137, vcc, 0, v65, vcc
	v_mul_f32_e32 v95, v117, v95
	v_mul_f32_e32 v107, v150, v107
	v_add_co_u32_e32 v78, vcc, s2, v64
	v_bfe_u32 v112, v107, 16, 1
	v_mul_f32_e32 v95, v95, v109
	v_addc_co_u32_e32 v79, vcc, 0, v65, vcc
	v_add3_u32 v151, v107, v112, s10
	v_bfe_u32 v107, v95, 16, 1
	v_add_co_u32_e32 v138, vcc, s43, v64
	v_add3_u32 v112, v95, v107, s10
	s_nop 0
	v_addc_co_u32_e32 v139, vcc, 0, v65, vcc
	global_load_ushort v125, v[84:85], off offset:512
	global_load_ushort v127, v[86:87], off offset:1536
	global_load_ushort v128, v[72:73], off offset:2560
	global_load_ushort v129, v[74:75], off offset:3584
	global_load_ushort v157, v[74:75], off offset:3072
	global_load_ushort v155, v[74:75], off
	global_load_ushort v109, v[72:73], off offset:3584
	global_load_ushort v107, v[72:73], off offset:2048
	global_load_ushort v172, v[76:77], off offset:1024
	global_load_ushort v173, v[134:135], off offset:3584
	global_load_ushort v174, v[132:133], off offset:2560
	global_load_ushort v175, v[118:119], off offset:1536
	global_load_ushort v131, v[118:119], off offset:2048
	s_nop 0
	global_load_ushort v132, v[132:133], off offset:3072
	s_nop 0
	global_load_ushort v176, v[134:135], off offset:512
	global_load_ushort v133, v[76:77], off
	global_load_ushort v177, v[118:119], off offset:3072
	global_load_ushort v170, v[136:137], off offset:2048
	global_load_ushort v169, v[136:137], off offset:512
	global_load_ushort v164, v[78:79], off offset:1024
	global_load_ushort v162, v[138:139], off offset:3584
	global_load_ushort v159, v[138:139], off offset:512
	global_load_ushort v135, v[78:79], off
	s_nop 0
	global_load_ushort v137, v[136:137], off offset:1024
	v_add_co_u32_e32 v144, vcc, s44, v64
	global_load_ushort v130, v[64:65], off offset:2560
	global_load_ushort v134, v[66:67], off offset:3584
	global_load_ushort v136, v[68:69], off offset:512
	global_load_ushort v138, v[70:71], off offset:1536
	global_load_ushort v139, v[80:81], off offset:2560
	global_load_ushort v141, v[82:83], off offset:3584
	global_load_ushort v142, v[84:85], off offset:-4096
	global_load_ushort v140, v[68:69], off offset:-4096
	v_addc_co_u32_e32 v145, vcc, 0, v65, vcc
	v_add_co_u32_e32 v100, vcc, s45, v64
	v_readlane_b32 s42, v255, 32
	s_nop 0
	v_addc_co_u32_e32 v101, vcc, 0, v65, vcc
	v_add_co_u32_e32 v102, vcc, s46, v64
	v_readlane_b32 s43, v255, 33
	s_nop 0
	v_addc_co_u32_e32 v103, vcc, 0, v65, vcc
	v_add_co_u32_e32 v104, vcc, s47, v64
	v_readlane_b32 s46, v255, 38
	s_nop 0
	v_addc_co_u32_e32 v105, vcc, 0, v65, vcc
	v_add_co_u32_e32 v98, vcc, s15, v64
	s_waitcnt vmcnt(53)
	v_lshlrev_b32_e32 v111, 16, v111
	v_addc_co_u32_e32 v99, vcc, 0, v65, vcc
	s_waitcnt vmcnt(51)
	v_lshlrev_b32_e32 v113, 16, v113
	s_waitcnt vmcnt(48)
	v_lshlrev_b32_e32 v72, 16, v120
	v_max_f32_e32 v72, v72, v72
	v_med3_f32 v72, v72, s9, v244
	v_mul_f32_e32 v72, 0xbfb8aa3b, v72
	v_exp_f32_e32 v95, v72
	v_add_co_u32_e32 v74, vcc, s14, v64
	v_max_f32_e32 v113, v113, v113
	v_add_f32_e32 v118, 1.0, v95
	v_rcp_f32_e32 v118, v118
	v_addc_co_u32_e32 v75, vcc, 0, v65, vcc
	v_med3_f32 v113, v113, s9, v244
	v_fma_f32 v119, v117, v118, v116
	v_mul_f32_e32 v119, v150, v119
	v_max_f32_e32 v119, 0xda24260, v119
	v_add_co_u32_e32 v76, vcc, s27, v64
	v_rcp_f32_e32 v120, v119
	v_mul_f32_e32 v113, 0xbfb8aa3b, v113
	v_addc_co_u32_e32 v77, vcc, 0, v65, vcc
	v_exp_f32_e32 v113, v113
	v_add_co_u32_e32 v78, vcc, s7, v64
	v_mul_f32_e32 v95, v95, v118
	s_nop 0
	v_addc_co_u32_e32 v79, vcc, 0, v65, vcc
	v_mul_f32_e32 v95, v117, v95
	v_add_co_u32_e32 v72, vcc, s5, v64
	v_mul_f32_e32 v95, v95, v120
	s_nop 0
	v_addc_co_u32_e32 v73, vcc, 0, v65, vcc
	global_load_ushort v156, v[144:145], off offset:2560
	global_load_ushort v148, v[144:145], off offset:3072
	global_load_ushort v149, v[100:101], off offset:2048
	global_load_ushort v147, v[102:103], off offset:1024
	global_load_ushort v146, v[98:99], off offset:3072
	s_nop 0
	global_load_ushort v144, v[74:75], off offset:2048
	global_load_ushort v145, v[76:77], off offset:1024
	global_load_ushort v143, v[72:73], off offset:3072
	v_bfe_u32 v118, v95, 16, 1
	v_add_f32_e32 v120, 1.0, v113
	v_add3_u32 v95, v95, v118, s10
	s_waitcnt vmcnt(53)
	v_lshlrev_b32_e32 v118, 16, v152
	v_rcp_f32_e32 v120, v120
	v_mul_f32_e32 v118, v119, v118
	v_bfe_u32 v150, v118, 16, 1
	v_add3_u32 v118, v118, v150, s10
	ds_write_b16_d16_hi v88, v118 offset:4320
	v_fma_f32 v118, v117, v120, v116
	v_mul_f32_e32 v118, v119, v118
	v_mul_f32_e32 v113, v113, v120
	s_waitcnt vmcnt(52)
	v_lshlrev_b32_e32 v120, 16, v153
	v_max_f32_e32 v118, 0xda24260, v118
	v_max_f32_e32 v120, v120, v120
	v_rcp_f32_e32 v119, v118
	v_med3_f32 v120, v120, s9, v244
	v_mul_f32_e32 v120, 0xbfb8aa3b, v120
	v_exp_f32_e32 v120, v120
	v_mul_f32_e32 v113, v117, v113
	v_mul_f32_e32 v113, v113, v119
	v_bfe_u32 v119, v113, 16, 1
	ds_write_b16_d16_hi v88, v151 offset:4464
	v_add3_u32 v151, v113, v119, s10
	v_add_f32_e32 v113, 1.0, v120
	v_rcp_f32_e32 v113, v113
	v_mul_f32_e32 v111, v118, v111
	v_bfe_u32 v119, v111, 16, 1
	v_add3_u32 v111, v111, v119, s10
	ds_write_b16_d16_hi v88, v111 offset:4176
	v_fma_f32 v111, v117, v113, v116
	s_waitcnt vmcnt(31)
	v_lshlrev_b32_e32 v119, 16, v172
	v_mul_f32_e32 v111, v118, v111
	v_max_f32_e32 v119, v119, v119
	v_max_f32_e32 v111, 0xda24260, v111
	v_med3_f32 v119, v119, s9, v244
	v_rcp_f32_e32 v118, v111
	v_mul_f32_e32 v119, 0xbfb8aa3b, v119
	v_exp_f32_e32 v119, v119
	v_mul_f32_e32 v113, v120, v113
	v_mul_f32_e32 v113, v117, v113
	v_mul_f32_e32 v113, v113, v118
	v_bfe_u32 v118, v113, 16, 1
	v_add_f32_e32 v120, 1.0, v119
	v_add3_u32 v118, v113, v118, s10
	v_lshlrev_b32_e32 v113, 16, v154
	v_rcp_f32_e32 v120, v120
	v_mul_f32_e32 v113, v111, v113
	v_bfe_u32 v150, v113, 16, 1
	v_add3_u32 v113, v113, v150, s10
	ds_write_b16_d16_hi v88, v113 offset:4032
	v_fma_f32 v113, v117, v120, v116
	v_mul_f32_e32 v111, v111, v113
	v_mul_f32_e32 v119, v119, v120
	s_waitcnt vmcnt(25)
	v_lshlrev_b32_e32 v120, 16, v176
	v_max_f32_e32 v111, 0xda24260, v111
	v_max_f32_e32 v120, v120, v120
	v_rcp_f32_e32 v113, v111
	v_med3_f32 v120, v120, s9, v244
	v_mul_f32_e32 v120, 0xbfb8aa3b, v120
	v_exp_f32_e32 v120, v120
	v_mul_f32_e32 v119, v117, v119
	v_mul_f32_e32 v113, v119, v113
	v_bfe_u32 v119, v113, 16, 1
	v_add3_u32 v152, v113, v119, s10
	v_add_f32_e32 v119, 1.0, v120
	v_lshlrev_b32_e32 v113, 16, v173
	v_rcp_f32_e32 v119, v119
	v_mul_f32_e32 v113, v111, v113
	v_bfe_u32 v150, v113, 16, 1
	v_add3_u32 v113, v113, v150, s10
	ds_write_b16_d16_hi v88, v113 offset:3888
	v_fma_f32 v113, v117, v119, v116
	v_mul_f32_e32 v119, v120, v119
	v_lshlrev_b32_e32 v120, 16, v160
	v_mul_f32_e32 v111, v111, v113
	v_max_f32_e32 v120, v120, v120
	v_max_f32_e32 v111, 0xda24260, v111
	v_med3_f32 v120, v120, s9, v244
	v_rcp_f32_e32 v113, v111
	v_mul_f32_e32 v120, 0xbfb8aa3b, v120
	v_exp_f32_e32 v120, v120
	v_mul_f32_e32 v119, v117, v119
	v_mul_f32_e32 v113, v119, v113
	v_bfe_u32 v119, v113, 16, 1
	v_add_f32_e32 v150, 1.0, v120
	v_add3_u32 v119, v113, v119, s10
	v_lshlrev_b32_e32 v113, 16, v158
	v_rcp_f32_e32 v150, v150
	v_mul_f32_e32 v113, v111, v113
	v_bfe_u32 v153, v113, 16, 1
	v_add3_u32 v113, v113, v153, s10
	ds_write_b16_d16_hi v88, v113 offset:3744
	v_fma_f32 v113, v117, v150, v116
	v_mul_f32_e32 v111, v111, v113
	v_mul_f32_e32 v120, v120, v150
	v_lshlrev_b32_e32 v150, 16, v165
	v_max_f32_e32 v111, 0xda24260, v111
	v_max_f32_e32 v150, v150, v150
	v_rcp_f32_e32 v113, v111
	v_med3_f32 v150, v150, s9, v244
	v_mul_f32_e32 v150, 0xbfb8aa3b, v150
	v_exp_f32_e32 v150, v150
	v_mul_f32_e32 v120, v117, v120
	v_mul_f32_e32 v113, v120, v113
	v_bfe_u32 v120, v113, 16, 1
	v_add3_u32 v153, v113, v120, s10
	v_add_f32_e32 v120, 1.0, v150
	v_lshlrev_b32_e32 v113, 16, v174
	v_rcp_f32_e32 v120, v120
	v_mul_f32_e32 v113, v111, v113
	v_bfe_u32 v154, v113, 16, 1
	v_add3_u32 v113, v113, v154, s10
	ds_write_b16_d16_hi v88, v113 offset:3600
	v_fma_f32 v113, v117, v120, v116
	v_mul_f32_e32 v111, v111, v113
	v_max_f32_e32 v111, 0xda24260, v111
	v_rcp_f32_e32 v113, v111
	v_mul_f32_e32 v120, v150, v120
	v_mul_f32_e32 v120, v117, v120
	v_readlane_b32 s47, v255, 39
	v_mul_f32_e32 v113, v120, v113
	v_bfe_u32 v120, v113, 16, 1
	v_add3_u32 v120, v113, v120, s10
	v_lshlrev_b32_e32 v113, 16, v166
	v_mul_f32_e32 v113, v111, v113
	v_bfe_u32 v150, v113, 16, 1
	v_add3_u32 v113, v113, v150, s10
	ds_write_b16_d16_hi v88, v112 offset:9072
	ds_write_b16_d16_hi v88, v95 offset:8928
	ds_write_b16_d16_hi v88, v151 offset:8784
	ds_write_b16_d16_hi v88, v118 offset:8640
	ds_write_b16_d16_hi v88, v152 offset:8496
	ds_write_b16_d16_hi v88, v119 offset:8352
	ds_write_b16_d16_hi v88, v153 offset:8208
	ds_write_b16_d16_hi v88, v113 offset:3456
	ds_write_b16_d16_hi v88, v120 offset:8064
	s_waitcnt vmcnt(23)
	v_lshlrev_b32_e32 v113, 16, v177
	v_max_f32_e32 v113, v113, v113
	v_med3_f32 v113, v113, s9, v244
	v_mul_f32_e32 v113, 0xbfb8aa3b, v113
	v_exp_f32_e32 v113, v113
	v_lshlrev_b32_e32 v107, 16, v107
	v_add_f32_e32 v150, 1.0, v113
	v_rcp_f32_e32 v150, v150
	s_nop 0
	v_fma_f32 v154, v117, v150, v116
	v_mul_f32_e32 v111, v111, v154
	v_max_f32_e32 v111, 0xda24260, v111
	v_mul_f32_e32 v113, v113, v150
	v_rcp_f32_e32 v150, v111
	v_mul_f32_e32 v113, v117, v113
	v_mul_f32_e32 v113, v113, v150
	v_bfe_u32 v150, v113, 16, 1
	v_add3_u32 v154, v113, v150, s10
	v_lshlrev_b32_e32 v113, 16, v175
	v_mul_f32_e32 v113, v111, v113
	v_bfe_u32 v150, v113, 16, 1
	v_add3_u32 v113, v113, v150, s10
	ds_write_b16_d16_hi v88, v113 offset:3312
	ds_write_b16_d16_hi v88, v154 offset:7920
	v_lshlrev_b32_e32 v113, 16, v168
	v_max_f32_e32 v113, v113, v113
	v_med3_f32 v113, v113, s9, v244
	v_mul_f32_e32 v113, 0xbfb8aa3b, v113
	v_exp_f32_e32 v113, v113
	s_nop 0
	v_add_f32_e32 v150, 1.0, v113
	v_rcp_f32_e32 v150, v150
	s_nop 0
	v_fma_f32 v158, v117, v150, v116
	v_mul_f32_e32 v111, v111, v158
	v_max_f32_e32 v172, 0xda24260, v111
	v_rcp_f32_e32 v111, v172
	v_mul_f32_e32 v113, v113, v150
	v_mul_f32_e32 v113, v117, v113
	v_mul_f32_e32 v111, v113, v111
	v_bfe_u32 v113, v111, 16, 1
	v_add3_u32 v150, v111, v113, s10
	v_lshlrev_b32_e32 v111, 16, v171
	v_mul_f32_e32 v111, v172, v111
	v_bfe_u32 v113, v111, 16, 1
	v_add3_u32 v171, v111, v113, s10
	global_load_ushort v168, v[100:101], off offset:3072
	global_load_ushort v166, v[100:101], off offset:1536
	global_load_ushort v165, v[86:87], off offset:2560
	global_load_ushort v160, v[86:87], off offset:1024
	global_load_ushort v158, v[102:103], off offset:2048
	global_load_ushort v113, v[102:103], off offset:512
	global_load_ushort v111, v[84:85], off offset:1536
	s_nop 0
	global_load_ushort v103, v[84:85], off
	global_load_ushort v102, v[104:105], off offset:1024
	v_add_co_u32_e32 v84, vcc, s50, v64
	s_nop 1
	v_addc_co_u32_e32 v85, vcc, 0, v65, vcc
	global_load_ushort v101, v[84:85], off offset:3584
	global_load_ushort v100, v[84:85], off offset:512
	global_load_ushort v87, v[82:83], off offset:3072
	global_load_ushort v86, v[82:83], off
	s_nop 0
	global_load_ushort v83, v[98:99], off offset:2560
	global_load_ushort v82, v[80:81], off offset:3584
	s_nop 0
	global_load_ushort v81, v[80:81], off offset:2048
	s_waitcnt vmcnt(38)
	v_lshlrev_b32_e32 v80, 16, v170
	v_max_f32_e32 v80, v80, v80
	v_med3_f32 v80, v80, s9, v244
	v_mul_f32_e32 v80, 0xbfb8aa3b, v80
	v_exp_f32_e32 v80, v80
	ds_write_b16_d16_hi v88, v171 offset:3168
	ds_write_b16_d16_hi v88, v150 offset:7776
	v_add_f32_e32 v84, 1.0, v80
	v_rcp_f32_e32 v84, v84
	s_nop 0
	v_fma_f32 v85, v117, v84, v116
	v_mul_f32_e32 v80, v80, v84
	v_mul_f32_e32 v84, v172, v85
	v_max_f32_e32 v84, 0xda24260, v84
	v_rcp_f32_e32 v85, v84
	v_mul_f32_e32 v80, v117, v80
	v_mul_f32_e32 v80, v80, v85
	v_bfe_u32 v85, v80, 16, 1
	v_add3_u32 v85, v80, v85, s10
	s_waitcnt vmcnt(37)
	v_lshlrev_b32_e32 v80, 16, v169
	v_mul_f32_e32 v80, v84, v80
	v_bfe_u32 v98, v80, 16, 1
	v_add3_u32 v80, v80, v98, s10
	ds_write_b16_d16_hi v88, v80 offset:3024
	ds_write_b16_d16_hi v88, v85 offset:7632
	v_lshlrev_b32_e32 v80, 16, v167
	v_max_f32_e32 v80, v80, v80
	v_med3_f32 v80, v80, s9, v244
	v_mul_f32_e32 v80, 0xbfb8aa3b, v80
	v_exp_f32_e32 v80, v80
	s_nop 0
	v_add_f32_e32 v98, 1.0, v80
	v_rcp_f32_e32 v98, v98
	s_nop 0
	v_fma_f32 v99, v117, v98, v116
	v_mul_f32_e32 v84, v84, v99
	v_max_f32_e32 v84, 0xda24260, v84
	v_mul_f32_e32 v80, v80, v98
	v_rcp_f32_e32 v98, v84
	v_mul_f32_e32 v80, v117, v80
	v_mul_f32_e32 v80, v80, v98
	v_bfe_u32 v98, v80, 16, 1
	v_add3_u32 v80, v80, v98, s10
	v_lshlrev_b32_e32 v98, 16, v163
	v_mul_f32_e32 v98, v84, v98
	v_bfe_u32 v99, v98, 16, 1
	v_add3_u32 v98, v98, v99, s10
	ds_write_b16_d16_hi v88, v98 offset:2880
	ds_write_b16_d16_hi v88, v80 offset:7488
	s_waitcnt vmcnt(36)
	v_lshlrev_b32_e32 v98, 16, v164
	v_max_f32_e32 v98, v98, v98
	v_med3_f32 v98, v98, s9, v244
	v_mul_f32_e32 v98, 0xbfb8aa3b, v98
	v_exp_f32_e32 v98, v98
	s_nop 0
	v_add_f32_e32 v99, 1.0, v98
	v_rcp_f32_e32 v99, v99
	s_nop 0
	v_fma_f32 v104, v117, v99, v116
	v_mul_f32_e32 v84, v84, v104
	v_max_f32_e32 v84, 0xda24260, v84
	v_mul_f32_e32 v98, v98, v99
	v_rcp_f32_e32 v99, v84
	v_mul_f32_e32 v98, v117, v98
	v_mul_f32_e32 v98, v98, v99
	v_bfe_u32 v99, v98, 16, 1
	v_add3_u32 v99, v98, v99, s10
	s_waitcnt vmcnt(35)
	v_lshlrev_b32_e32 v98, 16, v162
	v_mul_f32_e32 v98, v84, v98
	v_bfe_u32 v104, v98, 16, 1
	v_add3_u32 v98, v98, v104, s10
	ds_write_b16_d16_hi v88, v98 offset:2736
	ds_write_b16_d16_hi v88, v99 offset:7344
	s_waitcnt vmcnt(34)
	v_lshlrev_b32_e32 v98, 16, v159
	v_max_f32_e32 v98, v98, v98
	v_med3_f32 v98, v98, s9, v244
	v_mul_f32_e32 v98, 0xbfb8aa3b, v98
	v_exp_f32_e32 v98, v98
	s_nop 0
	v_add_f32_e32 v104, 1.0, v98
	v_rcp_f32_e32 v104, v104
	s_nop 0
	v_fma_f32 v105, v117, v104, v116
	v_mul_f32_e32 v84, v84, v105
	v_mul_f32_e32 v98, v98, v104
	v_max_f32_e32 v104, 0xda24260, v84
	v_rcp_f32_e32 v84, v104
	v_mul_f32_e32 v98, v117, v98
	v_mul_f32_e32 v84, v98, v84
	v_bfe_u32 v98, v84, 16, 1
	v_add3_u32 v84, v84, v98, s10
	v_lshlrev_b32_e32 v98, 16, v157
	v_mul_f32_e32 v98, v104, v98
	v_bfe_u32 v105, v98, 16, 1
	v_add3_u32 v98, v98, v105, s10
	ds_write_b16_d16_hi v88, v98 offset:2592
	ds_write_b16_d16_hi v88, v84 offset:7200
	v_lshlrev_b32_e32 v98, 16, v155
	v_max_f32_e32 v98, v98, v98
	v_med3_f32 v98, v98, s9, v244
	v_mul_f32_e32 v98, 0xbfb8aa3b, v98
	v_exp_f32_e32 v98, v98
	s_nop 0
	v_add_f32_e32 v105, 1.0, v98
	v_rcp_f32_e32 v105, v105
	s_nop 0
	v_fma_f32 v155, v117, v105, v116
	v_mul_f32_e32 v104, v104, v155
	v_max_f32_e32 v104, 0xda24260, v104
	v_mul_f32_e32 v98, v98, v105
	v_rcp_f32_e32 v105, v104
	v_mul_f32_e32 v98, v117, v98
	v_mul_f32_e32 v98, v98, v105
	v_bfe_u32 v105, v98, 16, 1
	v_add3_u32 v105, v98, v105, s10
	s_waitcnt vmcnt(23)
	v_lshlrev_b32_e32 v98, 16, v156
	v_mul_f32_e32 v98, v104, v98
	v_bfe_u32 v155, v98, 16, 1
	v_add3_u32 v98, v98, v155, s10
	ds_write_b16_d16_hi v88, v98 offset:2448
	ds_write_b16_d16_hi v88, v105 offset:7056
	v_lshlrev_b32_e32 v98, 16, v109
	v_max_f32_e32 v98, v98, v98
	v_med3_f32 v98, v98, s9, v244
	v_mul_f32_e32 v98, 0xbfb8aa3b, v98
	v_exp_f32_e32 v98, v98
	s_nop 0
	v_add_f32_e32 v109, 1.0, v98
	v_rcp_f32_e32 v109, v109
	s_nop 0
	v_fma_f32 v155, v117, v109, v116
	v_mul_f32_e32 v104, v104, v155
	v_max_f32_e32 v104, 0xda24260, v104
	v_mul_f32_e32 v98, v98, v109
	v_rcp_f32_e32 v109, v104
	v_mul_f32_e32 v98, v117, v98
	v_mul_f32_e32 v107, v104, v107
	v_mul_f32_e32 v98, v98, v109
	v_bfe_u32 v109, v98, 16, 1
	v_add3_u32 v98, v98, v109, s10
	v_bfe_u32 v109, v107, 16, 1
	v_add3_u32 v107, v107, v109, s10
	ds_write_b16_d16_hi v88, v107 offset:2304
	ds_write_b16_d16_hi v88, v98 offset:6912
	s_waitcnt vmcnt(15)
	v_lshlrev_b32_e32 v107, 16, v168
	v_max_f32_e32 v107, v107, v107
	v_med3_f32 v107, v107, s9, v244
	v_mul_f32_e32 v107, 0xbfb8aa3b, v107
	v_exp_f32_e32 v107, v107
	s_nop 0
	v_add_f32_e32 v109, 1.0, v107
	v_rcp_f32_e32 v109, v109
	s_nop 0
	v_fma_f32 v155, v117, v109, v116
	v_mul_f32_e32 v104, v104, v155
	v_max_f32_e32 v104, 0xda24260, v104
	v_mul_f32_e32 v107, v107, v109
	v_rcp_f32_e32 v109, v104
	v_mul_f32_e32 v107, v117, v107
	v_mul_f32_e32 v107, v107, v109
	v_bfe_u32 v109, v107, 16, 1
	v_add3_u32 v107, v107, v109, s10
	s_waitcnt vmcnt(14)
	v_lshlrev_b32_e32 v109, 16, v166
	v_mul_f32_e32 v109, v104, v109
	v_bfe_u32 v155, v109, 16, 1
	v_add3_u32 v109, v109, v155, s10
	ds_write_b16_d16_hi v88, v109 offset:2160
	ds_write_b16_d16_hi v88, v107 offset:6768
	s_waitcnt vmcnt(13)
	v_lshlrev_b32_e32 v109, 16, v165
	v_max_f32_e32 v109, v109, v109
	v_med3_f32 v109, v109, s9, v244
	v_mul_f32_e32 v109, 0xbfb8aa3b, v109
	v_exp_f32_e32 v109, v109
	global_load_ushort v172, v[74:75], off offset:3072
	global_load_ushort v170, v[74:75], off offset:1536
	global_load_ushort v171, v[70:71], off offset:2560
	global_load_ushort v168, v[70:71], off offset:1024
	global_load_ushort v169, v[76:77], off offset:2048
	global_load_ushort v166, v[76:77], off offset:512
	global_load_ushort v167, v[68:69], off offset:1536
	global_load_ushort v162, v[68:69], off
	global_load_ushort v164, v[78:79], off offset:1024
	v_add_co_u32_e32 v68, vcc, s11, v64
	v_add_f32_e32 v155, 1.0, v109
	v_rcp_f32_e32 v155, v155
	v_addc_co_u32_e32 v69, vcc, 0, v65, vcc
	v_fma_f32 v156, v117, v155, v116
	v_mul_f32_e32 v104, v104, v156
	v_max_f32_e32 v173, 0xda24260, v104
	v_rcp_f32_e32 v104, v173
	v_mul_f32_e32 v109, v109, v155
	v_mul_f32_e32 v109, v117, v109
	v_mul_f32_e32 v104, v109, v104
	v_bfe_u32 v109, v104, 16, 1
	v_add3_u32 v104, v104, v109, s10
	s_waitcnt vmcnt(21)
	v_lshlrev_b32_e32 v109, 16, v160
	v_mul_f32_e32 v109, v173, v109
	v_bfe_u32 v155, v109, 16, 1
	v_add3_u32 v109, v109, v155, s10
	global_load_ushort v163, v[68:69], off offset:3584
	global_load_ushort v165, v[68:69], off offset:512
	global_load_ushort v159, v[66:67], off offset:3072
	global_load_ushort v160, v[66:67], off
	global_load_ushort v156, v[72:73], off offset:2560
	global_load_ushort v157, v[64:65], off offset:3584
	global_load_ushort v155, v[64:65], off offset:2048
	s_waitcnt vmcnt(27)
	v_lshlrev_b32_e32 v64, 16, v158
	v_max_f32_e32 v64, v64, v64
	v_med3_f32 v64, v64, s9, v244
	v_mul_f32_e32 v64, 0xbfb8aa3b, v64
	v_exp_f32_e32 v64, v64
	ds_write_b16_d16_hi v88, v109 offset:2016
	ds_write_b16_d16_hi v88, v104 offset:6624
	v_add_f32_e32 v65, 1.0, v64
	v_rcp_f32_e32 v65, v65
	s_nop 0
	v_fma_f32 v66, v117, v65, v116
	v_mul_f32_e32 v64, v64, v65
	v_mul_f32_e32 v65, v173, v66
	v_max_f32_e32 v65, 0xda24260, v65
	v_rcp_f32_e32 v66, v65
	v_mul_f32_e32 v64, v117, v64
	v_mul_f32_e32 v64, v64, v66
	v_bfe_u32 v66, v64, 16, 1
	v_add3_u32 v64, v64, v66, s10
	s_waitcnt vmcnt(26)
	v_lshlrev_b32_e32 v66, 16, v113
	v_mul_f32_e32 v66, v65, v66
	v_bfe_u32 v67, v66, 16, 1
	v_add3_u32 v66, v66, v67, s10
	ds_write_b16_d16_hi v88, v66 offset:1872
	ds_write_b16_d16_hi v88, v64 offset:6480
	s_waitcnt vmcnt(25)
	v_lshlrev_b32_e32 v66, 16, v111
	v_max_f32_e32 v66, v66, v66
	v_med3_f32 v66, v66, s9, v244
	v_mul_f32_e32 v66, 0xbfb8aa3b, v66
	v_exp_f32_e32 v66, v66
	s_nop 0
	v_add_f32_e32 v67, 1.0, v66
	v_rcp_f32_e32 v67, v67
	s_nop 0
	v_fma_f32 v68, v117, v67, v116
	v_mul_f32_e32 v65, v65, v68
	v_max_f32_e32 v65, 0xda24260, v65
	v_mul_f32_e32 v66, v66, v67
	v_rcp_f32_e32 v67, v65
	v_mul_f32_e32 v66, v117, v66
	v_mul_f32_e32 v66, v66, v67
	v_bfe_u32 v67, v66, 16, 1
	v_add3_u32 v158, v66, v67, s10
	s_waitcnt vmcnt(24)
	v_lshlrev_b32_e32 v66, 16, v103
	v_mul_f32_e32 v66, v65, v66
	v_bfe_u32 v67, v66, 16, 1
	v_add3_u32 v66, v66, v67, s10
	ds_write_b16_d16_hi v88, v66 offset:1728
	ds_write_b16_d16_hi v88, v158 offset:6336
	s_waitcnt vmcnt(23)
	v_lshlrev_b32_e32 v66, 16, v102
	v_max_f32_e32 v66, v66, v66
	v_med3_f32 v66, v66, s9, v244
	v_mul_f32_e32 v66, 0xbfb8aa3b, v66
	v_exp_f32_e32 v66, v66
	s_nop 0
	v_add_f32_e32 v67, 1.0, v66
	v_rcp_f32_e32 v67, v67
	s_nop 0
	v_fma_f32 v68, v117, v67, v116
	v_mul_f32_e32 v65, v65, v68
	v_max_f32_e32 v65, 0xda24260, v65
	v_mul_f32_e32 v66, v66, v67
	v_rcp_f32_e32 v67, v65
	v_mul_f32_e32 v66, v117, v66
	v_mul_f32_e32 v66, v66, v67
	v_bfe_u32 v67, v66, 16, 1
	v_add3_u32 v66, v66, v67, s10
	s_waitcnt vmcnt(22)
	v_lshlrev_b32_e32 v67, 16, v101
	v_mul_f32_e32 v67, v65, v67
	v_bfe_u32 v68, v67, 16, 1
	v_add3_u32 v67, v67, v68, s10
	ds_write_b16_d16_hi v88, v67 offset:1584
	ds_write_b16_d16_hi v88, v66 offset:6192
	s_waitcnt vmcnt(21)
	v_lshlrev_b32_e32 v67, 16, v100
	v_max_f32_e32 v67, v67, v67
	v_med3_f32 v67, v67, s9, v244
	v_mul_f32_e32 v67, 0xbfb8aa3b, v67
	v_exp_f32_e32 v67, v67
	s_nop 0
	v_add_f32_e32 v68, 1.0, v67
	v_rcp_f32_e32 v68, v68
	s_nop 0
	v_fma_f32 v69, v117, v68, v116
	v_mul_f32_e32 v65, v65, v69
	v_max_f32_e32 v65, 0xda24260, v65
	v_mul_f32_e32 v67, v67, v68
	v_rcp_f32_e32 v68, v65
	v_mul_f32_e32 v67, v117, v67
	v_mul_f32_e32 v67, v67, v68
	v_bfe_u32 v68, v67, 16, 1
	v_add3_u32 v100, v67, v68, s10
	s_waitcnt vmcnt(20)
	v_lshlrev_b32_e32 v67, 16, v87
	v_mul_f32_e32 v67, v65, v67
	v_bfe_u32 v68, v67, 16, 1
	v_add3_u32 v67, v67, v68, s10
	ds_write_b16_d16_hi v88, v67 offset:1440
	ds_write_b16_d16_hi v88, v100 offset:6048
	s_waitcnt vmcnt(19)
	v_lshlrev_b32_e32 v67, 16, v86
	v_max_f32_e32 v67, v67, v67
	v_med3_f32 v67, v67, s9, v244
	v_mul_f32_e32 v67, 0xbfb8aa3b, v67
	v_exp_f32_e32 v67, v67
	s_nop 0
	v_add_f32_e32 v68, 1.0, v67
	v_rcp_f32_e32 v68, v68
	s_nop 0
	v_fma_f32 v69, v117, v68, v116
	v_mul_f32_e32 v65, v65, v69
	v_max_f32_e32 v65, 0xda24260, v65
	v_mul_f32_e32 v67, v67, v68
	v_rcp_f32_e32 v68, v65
	v_mul_f32_e32 v67, v117, v67
	v_mul_f32_e32 v67, v67, v68
	v_bfe_u32 v68, v67, 16, 1
	v_add3_u32 v67, v67, v68, s10
	s_waitcnt vmcnt(18)
	v_lshlrev_b32_e32 v68, 16, v83
	v_mul_f32_e32 v68, v65, v68
	v_bfe_u32 v69, v68, 16, 1
	v_add3_u32 v68, v68, v69, s10
	ds_write_b16_d16_hi v88, v68 offset:1296
	ds_write_b16_d16_hi v88, v67 offset:5904
	s_waitcnt vmcnt(17)
	v_lshlrev_b32_e32 v68, 16, v82
	v_max_f32_e32 v68, v68, v68
	v_med3_f32 v68, v68, s9, v244
	v_mul_f32_e32 v68, 0xbfb8aa3b, v68
	v_exp_f32_e32 v68, v68
	s_nop 0
	v_add_f32_e32 v69, 1.0, v68
	v_rcp_f32_e32 v69, v69
	s_nop 0
	v_fma_f32 v70, v117, v69, v116
	v_mul_f32_e32 v65, v65, v70
	v_max_f32_e32 v76, 0xda24260, v65
	v_rcp_f32_e32 v65, v76
	v_mul_f32_e32 v68, v68, v69
	v_mul_f32_e32 v68, v117, v68
	v_mul_f32_e32 v65, v68, v65
	v_bfe_u32 v68, v65, 16, 1
	v_add3_u32 v82, v65, v68, s10
	s_waitcnt vmcnt(16)
	v_lshlrev_b32_e32 v65, 16, v81
	v_mul_f32_e32 v65, v76, v65
	v_bfe_u32 v68, v65, 16, 1
	v_add3_u32 v65, v65, v68, s10
	ds_write_b16_d16_hi v88, v65 offset:1152
	ds_write_b16_d16_hi v88, v82 offset:5760
	s_waitcnt vmcnt(15)
	v_lshlrev_b32_e32 v72, 16, v172
	v_max_f32_e32 v72, v72, v72
	v_med3_f32 v72, v72, s9, v244
	v_mul_f32_e32 v72, 0xbfb8aa3b, v72
	v_exp_f32_e32 v86, v72
	v_and_b32_e32 v111, 0xffff0000, v66
	v_lshl_or_b32 v66, v106, 16, v122
	v_and_b32_e32 v113, 0xffff0000, v67
	v_add_f32_e32 v77, 1.0, v86
	v_rcp_f32_e32 v102, v77
	v_lshl_or_b32 v67, v108, 16, v110
	v_and_b32_e32 v81, 0xffff0000, v112
	v_lshl_or_b32 v75, v149, 16, v127
	v_fma_f32 v106, v117, v102, v116
	v_mul_f32_e32 v76, v76, v106
	v_max_f32_e32 v106, 0xda24260, v76
	v_rcp_f32_e32 v108, v106
	v_mul_f32_e32 v86, v86, v102
	v_mul_f32_e32 v86, v117, v86
	v_lshl_or_b32 v65, v133, 16, v121
	v_mul_f32_e32 v86, v86, v108
	v_bfe_u32 v102, v86, 16, 1
	v_add3_u32 v86, v86, v102, s10
	s_waitcnt vmcnt(13)
	v_lshlrev_b32_e32 v102, 16, v171
	v_max_f32_e32 v102, v102, v102
	v_med3_f32 v102, v102, s9, v244
	v_mul_f32_e32 v102, 0xbfb8aa3b, v102
	v_exp_f32_e32 v102, v102
	v_lshlrev_b32_e32 v108, 16, v170
	v_mul_f32_e32 v108, v106, v108
	v_bfe_u32 v112, v108, 16, 1
	v_add_f32_e32 v110, 1.0, v102
	v_rcp_f32_e32 v110, v110
	v_add3_u32 v108, v108, v112, s10
	ds_write_b16_d16_hi v88, v108 offset:1008
	v_and_b32_e32 v127, 0xffff0000, v86
	v_fma_f32 v108, v117, v110, v116
	v_mul_f32_e32 v106, v106, v108
	v_max_f32_e32 v106, 0xda24260, v106
	v_rcp_f32_e32 v108, v106
	ds_write_b16_d16_hi v88, v86 offset:5616
	v_mul_f32_e32 v86, v102, v110
	v_mul_f32_e32 v86, v117, v86
	v_mul_f32_e32 v86, v86, v108
	s_waitcnt vmcnt(11)
	v_lshlrev_b32_e32 v108, 16, v169
	v_max_f32_e32 v108, v108, v108
	v_med3_f32 v108, v108, s9, v244
	v_mul_f32_e32 v108, 0xbfb8aa3b, v108
	v_exp_f32_e32 v108, v108
	v_bfe_u32 v102, v86, 16, 1
	v_add3_u32 v86, v86, v102, s10
	v_lshlrev_b32_e32 v102, 16, v168
	v_add_f32_e32 v110, 1.0, v108
	v_rcp_f32_e32 v110, v110
	v_mul_f32_e32 v102, v106, v102
	v_bfe_u32 v112, v102, 16, 1
	v_add3_u32 v102, v102, v112, s10
	ds_write_b16_d16_hi v88, v102 offset:864
	v_fma_f32 v102, v117, v110, v116
	v_mul_f32_e32 v102, v106, v102
	v_max_f32_e32 v102, 0xda24260, v102
	v_rcp_f32_e32 v106, v102
	v_mul_f32_e32 v108, v108, v110
	v_mul_f32_e32 v108, v117, v108
	s_waitcnt vmcnt(10)
	v_lshlrev_b32_e32 v110, 16, v166
	v_mul_f32_e32 v106, v108, v106
	v_bfe_u32 v108, v106, 16, 1
	v_add3_u32 v106, v106, v108, s10
	s_waitcnt vmcnt(9)
	v_lshlrev_b32_e32 v108, 16, v167
	v_max_f32_e32 v108, v108, v108
	v_med3_f32 v108, v108, s9, v244
	v_mul_f32_e32 v108, 0xbfb8aa3b, v108
	v_exp_f32_e32 v108, v108
	v_mul_f32_e32 v110, v102, v110
	v_bfe_u32 v121, v110, 16, 1
	v_add3_u32 v110, v110, v121, s10
	v_add_f32_e32 v112, 1.0, v108
	v_rcp_f32_e32 v112, v112
	ds_write_b16_d16_hi v88, v110 offset:720
	v_lshl_or_b32 v74, v147, 16, v125
	v_and_b32_e32 v125, 0xffff0000, v106
	v_fma_f32 v110, v117, v112, v116
	v_mul_f32_e32 v102, v102, v110
	v_max_f32_e32 v102, 0xda24260, v102
	v_rcp_f32_e32 v110, v102
	ds_write_b16_d16_hi v88, v106 offset:5328
	v_mul_f32_e32 v106, v108, v112
	v_mul_f32_e32 v106, v117, v106
	v_mul_f32_e32 v106, v106, v110
	s_waitcnt vmcnt(7)
	v_lshlrev_b32_e32 v110, 16, v164
	v_max_f32_e32 v110, v110, v110
	v_med3_f32 v110, v110, s9, v244
	v_mul_f32_e32 v110, 0xbfb8aa3b, v110
	v_exp_f32_e32 v110, v110
	v_bfe_u32 v108, v106, 16, 1
	v_add3_u32 v106, v106, v108, s10
	v_lshlrev_b32_e32 v108, 16, v162
	v_add_f32_e32 v112, 1.0, v110
	v_rcp_f32_e32 v112, v112
	v_mul_f32_e32 v108, v102, v108
	v_bfe_u32 v121, v108, 16, 1
	v_add3_u32 v108, v108, v121, s10
	ds_write_b16_d16_hi v88, v108 offset:576
	v_fma_f32 v108, v117, v112, v116
	v_mul_f32_e32 v102, v102, v108
	v_max_f32_e32 v102, 0xda24260, v102
	v_rcp_f32_e32 v108, v102
	v_mul_f32_e32 v110, v110, v112
	v_mul_f32_e32 v110, v117, v110
	s_waitcnt vmcnt(6)
	v_lshlrev_b32_e32 v112, 16, v163
	v_mul_f32_e32 v108, v110, v108
	v_bfe_u32 v110, v108, 16, 1
	v_add3_u32 v108, v108, v110, s10
	s_waitcnt vmcnt(5)
	v_lshlrev_b32_e32 v110, 16, v165
	v_max_f32_e32 v110, v110, v110
	v_med3_f32 v110, v110, s9, v244
	v_mul_f32_e32 v110, 0xbfb8aa3b, v110
	v_exp_f32_e32 v110, v110
	v_mul_f32_e32 v112, v102, v112
	v_bfe_u32 v122, v112, 16, 1
	v_add3_u32 v112, v112, v122, s10
	v_add_f32_e32 v121, 1.0, v110
	v_rcp_f32_e32 v121, v121
	ds_write_b16_d16_hi v88, v112 offset:432
	v_lshl_or_b32 v69, v135, 16, v129
	v_and_b32_e32 v129, 0xffff0000, v108
	v_fma_f32 v112, v117, v121, v116
	v_mul_f32_e32 v102, v102, v112
	v_max_f32_e32 v102, 0xda24260, v102
	v_rcp_f32_e32 v112, v102
	ds_write_b16_d16_hi v88, v108 offset:5040
	v_mul_f32_e32 v108, v110, v121
	v_mul_f32_e32 v108, v117, v108
	v_mul_f32_e32 v108, v108, v112
	s_waitcnt vmcnt(3)
	v_lshlrev_b32_e32 v112, 16, v160
	v_max_f32_e32 v112, v112, v112
	v_med3_f32 v112, v112, s9, v244
	v_mul_f32_e32 v112, 0xbfb8aa3b, v112
	v_exp_f32_e32 v112, v112
	v_bfe_u32 v110, v108, 16, 1
	v_add3_u32 v108, v108, v110, s10
	v_lshlrev_b32_e32 v110, 16, v159
	v_add_f32_e32 v121, 1.0, v112
	v_rcp_f32_e32 v121, v121
	v_mul_f32_e32 v110, v102, v110
	v_bfe_u32 v122, v110, 16, 1
	v_add3_u32 v110, v110, v122, s10
	ds_write_b16_d16_hi v88, v110 offset:288
	v_fma_f32 v110, v117, v121, v116
	v_mul_f32_e32 v102, v102, v110
	v_max_f32_e32 v102, 0xda24260, v102
	v_rcp_f32_e32 v110, v102
	v_mul_f32_e32 v112, v112, v121
	v_mul_f32_e32 v112, v117, v112
	s_waitcnt vmcnt(2)
	v_lshlrev_b32_e32 v121, 16, v156
	v_mul_f32_e32 v110, v112, v110
	v_bfe_u32 v112, v110, 16, 1
	v_add3_u32 v110, v110, v112, s10
	s_waitcnt vmcnt(1)
	v_lshlrev_b32_e32 v112, 16, v157
	v_max_f32_e32 v112, v112, v112
	v_med3_f32 v112, v112, s9, v244
	v_mul_f32_e32 v112, 0xbfb8aa3b, v112
	v_exp_f32_e32 v112, v112
	v_mul_f32_e32 v121, v102, v121
	v_lshl_or_b32 v70, v137, 16, v123
	v_and_b32_e32 v123, 0xffff0000, v110
	v_add_f32_e32 v122, 1.0, v112
	v_rcp_f32_e32 v122, v122
	ds_write_b16_d16_hi v88, v110 offset:4752
	v_lshl_or_b32 v71, v131, 16, v124
	v_bfe_u32 v124, v121, 16, 1
	v_fmac_f32_e32 v116, v117, v122
	v_mul_f32_e32 v102, v102, v116
	v_max_f32_e32 v116, 0xda24260, v102
	v_rcp_f32_e32 v102, v116
	v_mul_f32_e32 v110, v112, v122
	v_mul_f32_e32 v110, v117, v110
	v_readlane_b32 s9, v255, 34
	v_mul_f32_e32 v102, v110, v102
	v_bfe_u32 v110, v102, 16, 1
	v_add3_u32 v102, v102, v110, s10
	s_waitcnt vmcnt(0)
	v_lshlrev_b32_e32 v110, 16, v155
	v_mul_f32_e32 v110, v116, v110
	v_bfe_u32 v112, v110, 16, 1
	v_add3_u32 v121, v121, v124, s10
	v_add3_u32 v110, v110, v112, s10
	v_readlane_b32 s10, v255, 36
	v_and_b32_e32 v109, 0xffff0000, v64
	v_and_b32_e32 v107, 0xffff0000, v107
	v_and_b32_e32 v105, 0xffff0000, v105
	v_and_b32_e32 v103, 0xffff0000, v99
	v_and_b32_e32 v101, 0xffff0000, v85
	v_and_b32_e32 v99, 0xffff0000, v154
	v_and_b32_e32 v87, 0xffff0000, v153
	v_and_b32_e32 v85, 0xffff0000, v152
	v_and_b32_e32 v83, 0xffff0000, v151
	v_lshl_or_b32 v64, v132, 16, v126
	v_lshl_or_b32 v68, v148, 16, v128
	v_lshl_or_b32 v73, v142, 16, v141
	v_lshl_or_b32 v72, v146, 16, v139
	v_lshl_or_b32 v79, v144, 16, v138
	v_lshl_or_b32 v78, v145, 16, v136
	v_lshl_or_b32 v77, v140, 16, v134
	v_lshl_or_b32 v76, v143, 16, v130
	ds_write_b16_d16_hi v88, v86 offset:5472
	ds_write_b16_d16_hi v88, v106 offset:5184
	ds_write_b16_d16_hi v88, v108 offset:4896
	ds_write_b16_d16_hi v88, v121 offset:144
	ds_write_b16_d16_hi v88, v110
	ds_write_b16_d16_hi v88, v102 offset:4608
	v_and_b32_e32 v122, 0xffff0000, v102
	v_and_b32_e32 v128, 0xffff0000, v108
	v_and_b32_e32 v124, 0xffff0000, v106
	v_and_b32_e32 v126, 0xffff0000, v86
	v_pk_mul_f32 v[122:123], v[116:117], v[122:123] op_sel_hi:[0,1]
	v_pk_mul_f32 v[128:129], v[116:117], v[128:129] op_sel_hi:[0,1]
	v_pk_mul_f32 v[124:125], v[116:117], v[124:125] op_sel_hi:[0,1]
	v_pk_mul_f32 v[126:127], v[116:117], v[126:127] op_sel_hi:[0,1]
	v_and_b32_e32 v112, 0xffff0000, v82
	v_and_b32_e32 v110, 0xffff0000, v100
	v_and_b32_e32 v108, 0xffff0000, v158
	v_and_b32_e32 v106, 0xffff0000, v104
	v_and_b32_e32 v104, 0xffff0000, v98
	v_and_b32_e32 v102, 0xffff0000, v84
	v_and_b32_e32 v100, 0xffff0000, v80
	v_and_b32_e32 v98, 0xffff0000, v150
	v_and_b32_e32 v86, 0xffff0000, v120
	v_and_b32_e32 v84, 0xffff0000, v119
	v_and_b32_e32 v82, 0xffff0000, v118
	v_and_b32_e32 v80, 0xffff0000, v95
	v_mad_u64_u32 v[130:131], s[2:3], v94, s4, v[92:93]
	v_cvt_pk_bf16_f32 v122, v122, v123
	v_cvt_pk_bf16_f32 v123, v128, v129
	v_cvt_pk_bf16_f32 v124, v124, v125
	v_cvt_pk_bf16_f32 v125, v126, v127
	v_pk_mul_f32 v[112:113], v[116:117], v[112:113] op_sel_hi:[0,1]
	v_pk_mul_f32 v[110:111], v[116:117], v[110:111] op_sel_hi:[0,1]
	v_pk_mul_f32 v[108:109], v[116:117], v[108:109] op_sel_hi:[0,1]
	v_pk_mul_f32 v[106:107], v[116:117], v[106:107] op_sel_hi:[0,1]
	v_pk_mul_f32 v[104:105], v[116:117], v[104:105] op_sel_hi:[0,1]
	v_pk_mul_f32 v[102:103], v[116:117], v[102:103] op_sel_hi:[0,1]
	v_pk_mul_f32 v[100:101], v[116:117], v[100:101] op_sel_hi:[0,1]
	v_pk_mul_f32 v[98:99], v[116:117], v[98:99] op_sel_hi:[0,1]
	v_pk_mul_f32 v[86:87], v[116:117], v[86:87] op_sel_hi:[0,1]
	v_pk_mul_f32 v[84:85], v[116:117], v[84:85] op_sel_hi:[0,1]
	v_pk_mul_f32 v[82:83], v[116:117], v[82:83] op_sel_hi:[0,1]
	v_pk_mul_f32 v[80:81], v[116:117], v[80:81] op_sel_hi:[0,1]
	ds_write_b128 v130, v[122:125] offset:9216
	v_cvt_pk_bf16_f32 v122, v112, v113
	v_cvt_pk_bf16_f32 v123, v110, v111
	v_cvt_pk_bf16_f32 v124, v108, v109
	v_cvt_pk_bf16_f32 v125, v106, v107
	v_cvt_pk_bf16_f32 v104, v104, v105
	v_cvt_pk_bf16_f32 v105, v102, v103
	v_cvt_pk_bf16_f32 v106, v100, v101
	v_cvt_pk_bf16_f32 v107, v98, v99
	v_cvt_pk_bf16_f32 v98, v86, v87
	v_cvt_pk_bf16_f32 v99, v84, v85
	v_cvt_pk_bf16_f32 v100, v82, v83
	v_cvt_pk_bf16_f32 v101, v80, v81
	v_lshl_add_u32 v80, v94, 2, v92
	ds_write_b128 v130, v[122:125] offset:9232
	ds_write_b128 v130, v[104:107] offset:9248
	ds_write_b128 v130, v[98:101] offset:9264
	ds_write_b32 v80, v116 offset:19456
	ds_write_b128 v130, v[76:79] offset:14336
	ds_write_b128 v130, v[72:75] offset:14352
	ds_write_b128 v130, v[68:71] offset:14368
	ds_write_b128 v130, v[64:67] offset:14384
	s_waitcnt lgkmcnt(0)
	v_or_b32_e32 v88, v93, v114
	v_lshlrev_b64 v[64:65], 11, v[88:89]
	v_lshlrev_b32_e32 v98, 2, v115
	v_lshl_add_u64 v[64:65], s[12:13], 0, v[64:65]
	v_ashrrev_i32_e32 v99, 31, v98
	v_lshl_add_u64 v[64:65], v[64:65], 0, v[90:91]
	v_lshlrev_b64 v[100:101], 1, v[98:99]
	v_lshl_add_u64 v[102:103], v[64:65], 0, v[100:101]
	s_mov_b64 s[2:3], 0x16f00600
	v_lshl_add_u64 v[94:95], v[102:103], 0, s[2:3]
	global_load_dwordx2 v[196:197], v[94:95], off
	global_load_dwordx2 v[198:199], v[94:95], off offset:16
	global_load_dwordx2 v[200:201], v[94:95], off offset:32
	global_load_dwordx2 v[202:203], v[94:95], off offset:48
	global_load_dwordx2 v[230:231], v[94:95], off offset:64
	global_load_dwordx2 v[232:233], v[94:95], off offset:80
	global_load_dwordx2 v[234:235], v[94:95], off offset:96
	global_load_dwordx2 v[240:241], v[94:95], off offset:112
	s_movk_i32 s2, 0x90
	v_mad_u32_u24 v89, v114, s2, v92
	v_lshl_add_u32 v93, v115, 4, v89
	ds_read_b128 v[64:67], v93 offset:4608
	ds_read_b128 v[68:71], v93
	ds_read_b128 v[80:83], v93 offset:32
	ds_read_b128 v[84:87], v93 offset:4640
	s_waitcnt lgkmcnt(2)
	v_mfma_f32_32x32x16_bf16 v[64:79], v[64:67], v[68:71], 0
	v_cmp_ge_i32_e32 vcc, v98, v114
	v_cvt_pk_bf16_f32 v32, v32, v33
	v_cvt_pk_bf16_f32 v33, v34, v35
	v_cvt_pk_bf16_f32 v34, v36, v37
	v_cvt_pk_bf16_f32 v35, v38, v39
	v_cvt_pk_bf16_f32 v36, v48, v49
	v_cvt_pk_bf16_f32 v37, v50, v51
	s_waitcnt lgkmcnt(0)
	v_mfma_f32_32x32x16_bf16 v[64:79], v[84:87], v[80:83], v[64:79]
	ds_read_b128 v[80:83], v93 offset:4672
	ds_read_b128 v[84:87], v93 offset:64
	v_cvt_pk_bf16_f32 v38, v52, v53
	v_cvt_pk_bf16_f32 v39, v54, v55
	s_mov_b32 s2, 0x16f00000
	s_waitcnt lgkmcnt(0)
	v_mfma_f32_32x32x16_bf16 v[64:79], v[80:83], v[84:87], v[64:79]
	ds_read_b128 v[80:83], v93 offset:4704
	ds_read_b128 v[84:87], v93 offset:96
	s_waitcnt lgkmcnt(0)
	v_mfma_f32_32x32x16_bf16 v[64:79], v[80:83], v[84:87], v[64:79]
	v_or_b32_e32 v80, 1, v98
	s_nop 10
	v_cndmask_b32_e32 v64, 0, v64, vcc
	v_cmp_ge_i32_e32 vcc, v80, v114
	v_or_b32_e32 v80, 2, v98
	s_nop 0
	v_cndmask_b32_e32 v65, 0, v65, vcc
	v_cmp_ge_i32_e32 vcc, v80, v114
	v_or_b32_e32 v80, 3, v98
	s_nop 0
	v_cndmask_b32_e32 v66, 0, v66, vcc
	v_cmp_ge_i32_e32 vcc, v80, v114
	v_add_u32_e32 v80, 8, v98
	s_nop 0
	v_cndmask_b32_e32 v67, 0, v67, vcc
	v_cmp_ge_i32_e32 vcc, v80, v114
	v_add_u32_e32 v80, 9, v98
	v_cvt_pk_bf16_f32 v81, v66, v67
	v_cndmask_b32_e32 v68, 0, v68, vcc
	v_cmp_ge_i32_e32 vcc, v80, v114
	v_add_u32_e32 v80, 10, v98
	s_nop 0
	v_cndmask_b32_e32 v69, 0, v69, vcc
	v_cmp_ge_i32_e32 vcc, v80, v114
	v_add_u32_e32 v80, 11, v98
	v_cvt_pk_bf16_f32 v82, v68, v69
	v_cndmask_b32_e32 v70, 0, v70, vcc
	v_cmp_ge_i32_e32 vcc, v80, v114
	v_add_u32_e32 v80, 16, v98
	s_nop 0
	v_cndmask_b32_e32 v71, 0, v71, vcc
	v_cmp_ge_i32_e32 vcc, v80, v114
	v_add_u32_e32 v80, 17, v98
	v_cvt_pk_bf16_f32 v83, v70, v71
	v_cndmask_b32_e32 v72, 0, v72, vcc
	v_cmp_ge_i32_e32 vcc, v80, v114
	v_add_u32_e32 v80, 18, v98
	s_nop 0
	v_cndmask_b32_e32 v73, 0, v73, vcc
	v_cmp_ge_i32_e32 vcc, v80, v114
	v_add_u32_e32 v80, 19, v98
	v_cvt_pk_bf16_f32 v84, v72, v73
	v_cndmask_b32_e32 v74, 0, v74, vcc
	v_cmp_ge_i32_e32 vcc, v80, v114
	v_add_u32_e32 v80, 24, v98
	s_nop 0
	v_cndmask_b32_e32 v75, 0, v75, vcc
	v_cmp_ge_i32_e32 vcc, v80, v114
	v_add_u32_e32 v80, 25, v98
	v_cvt_pk_bf16_f32 v85, v74, v75
	v_cndmask_b32_e32 v76, 0, v76, vcc
	v_cmp_ge_i32_e32 vcc, v80, v114
	v_add_u32_e32 v80, 26, v98
	s_nop 0
	v_cndmask_b32_e32 v77, 0, v77, vcc
	v_cmp_ge_i32_e32 vcc, v80, v114
	v_add_u32_e32 v80, 27, v98
	v_cvt_pk_bf16_f32 v86, v76, v77
	v_cndmask_b32_e32 v78, 0, v78, vcc
	v_cmp_ge_i32_e32 vcc, v80, v114
	v_cvt_pk_bf16_f32 v80, v64, v65
	v_lshlrev_b32_e32 v64, 3, v115
	v_mul_u32_u24_e32 v65, 0x50, v114
	v_add3_u32 v92, v92, v64, v65
	v_add_u32_e32 v68, 0x3800, v92
	v_add_u32_e32 v89, v89, v64
	ds_read2_b64 v[64:67], v68 offset1:2
	ds_read2_b64 v[104:107], v68 offset0:4 offset1:6
	v_cndmask_b32_e32 v79, 0, v79, vcc
	v_cvt_pk_bf16_f32 v87, v78, v79
	s_waitcnt lgkmcnt(1)
	v_mfma_f32_32x32x16_bf16 v[64:79], v[64:67], v[80:83], 0
	v_add_co_u32_e32 v48, vcc, s2, v102
	s_nop 1
	v_addc_co_u32_e32 v49, vcc, 0, v103, vcc
	s_waitcnt lgkmcnt(0)
	v_mfma_f32_32x32x16_bf16 v[64:79], v[104:107], v[84:87], v[64:79]
	ds_read2_b64 v[104:107], v89 offset1:2
	ds_read2_b64 v[108:111], v89 offset0:4 offset1:6
	s_waitcnt lgkmcnt(1)
	v_mfma_f32_32x32x16_bf16 v[64:79], v[32:35], v[104:107], v[64:79]
	v_cvt_pk_bf16_f32 v32, v40, v41
	v_cvt_pk_bf16_f32 v33, v42, v43
	v_cvt_pk_bf16_f32 v34, v44, v45
	v_cvt_pk_bf16_f32 v35, v46, v47
	s_waitcnt lgkmcnt(0)
	s_nop 0
	v_mfma_f32_32x32x16_bf16 v[64:79], v[32:35], v[108:111], v[64:79]
	ds_read2_b64 v[32:35], v89 offset0:8 offset1:10
	s_waitcnt lgkmcnt(0)
	v_mfma_f32_32x32x16_bf16 v[64:79], v[36:39], v[32:35], v[64:79]
	ds_read2_b64 v[32:35], v89 offset0:12 offset1:14
	v_cvt_pk_bf16_f32 v36, v56, v57
	v_cvt_pk_bf16_f32 v37, v58, v59
	v_cvt_pk_bf16_f32 v38, v60, v61
	v_cvt_pk_bf16_f32 v39, v62, v63
	s_waitcnt lgkmcnt(0)
	s_nop 0
	v_mfma_f32_32x32x16_bf16 v[64:79], v[36:39], v[32:35], v[64:79]
	s_waitcnt vmcnt(7)
	v_lshlrev_b32_e32 v34, 16, v196
	v_and_b32_e32 v35, 0xffff0000, v196
	v_lshlrev_b32_e32 v32, 16, v197
	v_and_b32_e32 v33, 0xffff0000, v197
	s_nop 5
	v_pk_add_f32 v[34:35], v[64:65], v[34:35]
	v_pk_add_f32 v[32:33], v[66:67], v[32:33]
	v_mul_f32_e32 v36, v35, v35
	v_mul_f32_e32 v38, v33, v33
	v_pk_fma_f32 v[36:37], v[34:35], v[34:35], v[36:37] op_sel_hi:[1,1,0]
	v_pk_fma_f32 v[38:39], v[32:33], v[32:33], v[38:39] op_sel_hi:[1,1,0]
	v_cvt_pk_bf16_f32 v34, v34, v35
	v_cvt_pk_bf16_f32 v35, v32, v33
	v_pk_add_f32 v[36:37], v[36:37], v[38:39]
	global_store_dwordx2 v[48:49], v[34:35], off offset:1536
	s_waitcnt vmcnt(7)
	v_lshlrev_b32_e32 v34, 16, v198
	v_and_b32_e32 v35, 0xffff0000, v198
	v_lshlrev_b32_e32 v32, 16, v199
	v_and_b32_e32 v33, 0xffff0000, v199
	v_pk_add_f32 v[34:35], v[68:69], v[34:35]
	v_pk_add_f32 v[32:33], v[70:71], v[32:33]
	v_mul_f32_e32 v38, v35, v35
	v_mul_f32_e32 v40, v33, v33
	v_pk_fma_f32 v[38:39], v[34:35], v[34:35], v[38:39] op_sel_hi:[1,1,0]
	v_pk_fma_f32 v[40:41], v[32:33], v[32:33], v[40:41] op_sel_hi:[1,1,0]
	v_cvt_pk_bf16_f32 v34, v34, v35
	v_cvt_pk_bf16_f32 v35, v32, v33
	v_pk_add_f32 v[38:39], v[38:39], v[40:41]
	global_store_dwordx2 v[94:95], v[34:35], off offset:16
	v_pk_add_f32 v[36:37], v[36:37], v[38:39]
	s_waitcnt vmcnt(7)
	v_lshlrev_b32_e32 v34, 16, v200
	v_and_b32_e32 v35, 0xffff0000, v200
	v_pk_add_f32 v[34:35], v[72:73], v[34:35]
	v_lshlrev_b32_e32 v32, 16, v201
	v_and_b32_e32 v33, 0xffff0000, v201
	v_pk_add_f32 v[38:39], v[74:75], v[32:33]
	v_mul_f32_e32 v32, v35, v35
	v_pk_fma_f32 v[32:33], v[34:35], v[34:35], v[32:33] op_sel_hi:[1,1,0]
	v_cvt_pk_bf16_f32 v34, v34, v35
	v_cvt_pk_bf16_f32 v35, v38, v39
	global_store_dwordx2 v[94:95], v[34:35], off offset:32
	v_mul_f32_e32 v40, v39, v39
	v_pk_fma_f32 v[40:41], v[38:39], v[38:39], v[40:41] op_sel_hi:[1,1,0]
	s_nop 0
	v_pk_add_f32 v[32:33], v[32:33], v[40:41]
	s_nop 0
	v_pk_add_f32 v[32:33], v[36:37], v[32:33]
	s_waitcnt vmcnt(7)
	v_lshlrev_b32_e32 v36, 16, v202
	v_and_b32_e32 v37, 0xffff0000, v202
	v_lshlrev_b32_e32 v34, 16, v203
	v_and_b32_e32 v35, 0xffff0000, v203
	v_pk_add_f32 v[36:37], v[76:77], v[36:37]
	v_pk_add_f32 v[34:35], v[78:79], v[34:35]
	v_mul_f32_e32 v38, v37, v37
	v_mul_f32_e32 v40, v35, v35
	v_pk_fma_f32 v[38:39], v[36:37], v[36:37], v[38:39] op_sel_hi:[1,1,0]
	v_pk_fma_f32 v[40:41], v[34:35], v[34:35], v[40:41] op_sel_hi:[1,1,0]
	s_nop 0
	v_pk_add_f32 v[38:39], v[38:39], v[40:41]
	s_nop 0
	v_pk_add_f32 v[58:59], v[32:33], v[38:39]
	v_cvt_pk_bf16_f32 v32, v36, v37
	v_cvt_pk_bf16_f32 v33, v34, v35
	global_store_dwordx2 v[94:95], v[32:33], off offset:48
	v_add_u32_e32 v36, 0x4000, v92
	ds_read2_b64 v[32:35], v36 offset0:64 offset1:66
	ds_read2_b64 v[50:53], v36 offset0:68 offset1:70
	v_cvt_pk_bf16_f32 v0, v0, v1
	v_cvt_pk_bf16_f32 v1, v2, v3
	v_cvt_pk_bf16_f32 v2, v4, v5
	s_waitcnt lgkmcnt(1)
	v_mfma_f32_32x32x16_bf16 v[32:47], v[32:35], v[80:83], 0
	v_cvt_pk_bf16_f32 v3, v6, v7
	v_cvt_pk_bf16_f32 v4, v16, v17
	v_cvt_pk_bf16_f32 v5, v18, v19
	v_cvt_pk_bf16_f32 v6, v20, v21
	v_cvt_pk_bf16_f32 v7, v22, v23
	s_waitcnt lgkmcnt(0)
	v_mfma_f32_32x32x16_bf16 v[32:47], v[50:53], v[84:87], v[32:47]
	ds_read2_b64 v[50:53], v89 offset1:2
	ds_read2_b64 v[54:57], v89 offset0:4 offset1:6
	s_waitcnt lgkmcnt(1)
	v_mfma_f32_32x32x16_bf16 v[32:47], v[0:3], v[50:53], v[32:47]
	v_cvt_pk_bf16_f32 v0, v8, v9
	v_cvt_pk_bf16_f32 v1, v10, v11
	v_cvt_pk_bf16_f32 v2, v12, v13
	v_cvt_pk_bf16_f32 v3, v14, v15
	s_waitcnt lgkmcnt(0)
	s_nop 0
	v_mfma_f32_32x32x16_bf16 v[32:47], v[0:3], v[54:57], v[32:47]
	ds_read2_b64 v[0:3], v89 offset0:8 offset1:10
	s_waitcnt lgkmcnt(0)
	v_mfma_f32_32x32x16_bf16 v[32:47], v[4:7], v[0:3], v[32:47]
	ds_read2_b64 v[0:3], v89 offset0:12 offset1:14
	v_cvt_pk_bf16_f32 v4, v24, v25
	v_cvt_pk_bf16_f32 v5, v26, v27
	v_cvt_pk_bf16_f32 v6, v28, v29
	v_cvt_pk_bf16_f32 v7, v30, v31
	s_waitcnt lgkmcnt(0)
	s_nop 0
	v_mfma_f32_32x32x16_bf16 v[32:47], v[4:7], v[0:3], v[32:47]
	s_waitcnt vmcnt(7)
	v_lshlrev_b32_e32 v2, 16, v230
	v_and_b32_e32 v3, 0xffff0000, v230
	v_lshlrev_b32_e32 v0, 16, v231
	v_and_b32_e32 v1, 0xffff0000, v231
	s_nop 5
	v_pk_add_f32 v[2:3], v[32:33], v[2:3]
	v_pk_add_f32 v[0:1], v[34:35], v[0:1]
	v_mul_f32_e32 v4, v3, v3
	v_mul_f32_e32 v6, v1, v1
	v_pk_fma_f32 v[4:5], v[2:3], v[2:3], v[4:5] op_sel_hi:[1,1,0]
	v_pk_fma_f32 v[6:7], v[0:1], v[0:1], v[6:7] op_sel_hi:[1,1,0]
	v_cvt_pk_bf16_f32 v2, v2, v3
	v_cvt_pk_bf16_f32 v3, v0, v1
	v_pk_add_f32 v[4:5], v[4:5], v[6:7]
	global_store_dwordx2 v[94:95], v[2:3], off offset:64
	v_pk_add_f32 v[4:5], v[58:59], v[4:5]
	s_waitcnt vmcnt(7)
	v_lshlrev_b32_e32 v2, 16, v232
	v_and_b32_e32 v3, 0xffff0000, v232
	v_lshlrev_b32_e32 v0, 16, v233
	v_and_b32_e32 v1, 0xffff0000, v233
	v_pk_add_f32 v[2:3], v[36:37], v[2:3]
	v_pk_add_f32 v[0:1], v[38:39], v[0:1]
	v_mul_f32_e32 v6, v3, v3
	v_mul_f32_e32 v8, v1, v1
	v_pk_fma_f32 v[6:7], v[2:3], v[2:3], v[6:7] op_sel_hi:[1,1,0]
	v_pk_fma_f32 v[8:9], v[0:1], v[0:1], v[8:9] op_sel_hi:[1,1,0]
	v_cvt_pk_bf16_f32 v2, v2, v3
	v_cvt_pk_bf16_f32 v3, v0, v1
	v_pk_add_f32 v[6:7], v[6:7], v[8:9]
	global_store_dwordx2 v[94:95], v[2:3], off offset:80
	v_pk_add_f32 v[4:5], v[4:5], v[6:7]
	s_waitcnt vmcnt(7)
	v_lshlrev_b32_e32 v2, 16, v234
	v_and_b32_e32 v3, 0xffff0000, v234
	v_lshlrev_b32_e32 v0, 16, v235
	v_and_b32_e32 v1, 0xffff0000, v235
	v_pk_add_f32 v[2:3], v[40:41], v[2:3]
	v_pk_add_f32 v[6:7], v[42:43], v[0:1]
	v_mov_b32_e32 v0, v2
	v_mov_b32_e32 v8, v3
	v_cvt_pk_bf16_f32 v2, v2, v3
	v_cvt_pk_bf16_f32 v3, v6, v7
	global_store_dwordx2 v[94:95], v[2:3], off offset:96
	v_mov_b32_e32 v9, v7
	v_mov_b32_e32 v1, v6
	v_pk_mul_f32 v[8:9], v[8:9], v[8:9]
	s_nop 0
	v_pk_fma_f32 v[0:1], v[0:1], v[0:1], v[8:9]
	s_nop 0
	v_pk_add_f32 v[0:1], v[0:1], v[0:1] op_sel:[0,1] op_sel_hi:[1,0]
	s_nop 0
	v_pk_add_f32 v[0:1], v[4:5], v[0:1]
	s_waitcnt vmcnt(7)
	v_lshlrev_b32_e32 v4, 16, v240
	v_and_b32_e32 v5, 0xffff0000, v240
	v_lshlrev_b32_e32 v2, 16, v241
	v_and_b32_e32 v3, 0xffff0000, v241
	v_pk_add_f32 v[4:5], v[44:45], v[4:5]
	v_pk_add_f32 v[2:3], v[46:47], v[2:3]
	v_mov_b32_e32 v8, v5
	v_mov_b32_e32 v9, v3
	v_mov_b32_e32 v6, v4
	v_mov_b32_e32 v7, v2
	v_pk_mul_f32 v[8:9], v[8:9], v[8:9]
	v_cvt_pk_bf16_f32 v4, v4, v5
	v_pk_fma_f32 v[6:7], v[6:7], v[6:7], v[8:9]
	v_cvt_pk_bf16_f32 v5, v2, v3
	v_pk_add_f32 v[6:7], v[6:7], v[6:7] op_sel:[0,1] op_sel_hi:[1,0]
	global_store_dwordx2 v[94:95], v[4:5], off offset:112
	v_pk_add_f32 v[0:1], v[0:1], v[6:7]
	s_waitcnt lgkmcnt(0)
	s_nop 0
	v_mov_b32_e32 v1, v0
	s_nop 1
	v_permlane32_swap_b32_e32 v0, v1
	v_add_f32_e32 v0, v0, v1
	v_fmamk_f32 v0, v0, 0x3c800000, v237
	v_rsq_f32_e32 v4, v0
	v_mad_i64_i32 v[0:1], s[2:3], v88, s6, v[96:97]
	v_lshl_add_u64 v[0:1], v[0:1], 0, v[90:91]
	v_lshl_add_u64 v[0:1], v[0:1], 0, v[100:101]
	v_lshl_add_u64 v[8:9], v[0:1], 0, s[48:49]
	v_add_co_u32_e32 v0, vcc, s5, v0
	global_load_dwordx2 v[10:11], v[48:49], off offset:1536
	s_nop 0
	v_addc_co_u32_e32 v1, vcc, 0, v1, vcc
	global_load_dwordx2 v[12:13], v[0:1], off
	s_add_u32 s2, s12, s0
	s_addc_u32 s3, s13, s1
	v_lshl_add_u64 v[0:1], v[98:99], 2, s[2:3]
	v_lshl_add_u64 v[6:7], v[0:1], 0, s[30:31]
	v_add_co_u32_e32 v0, vcc, s7, v0
	v_readlane_b32 s48, v254, 11
	s_nop 0
	v_addc_co_u32_e32 v1, vcc, 0, v1, vcc
	global_load_dwordx4 v[0:3], v[0:1], off offset:2048
	global_load_dwordx4 v[206:209], v[6:7], off offset:32
	global_load_dwordx2 v[210:211], v[8:9], off offset:16
	global_load_dwordx2 v[212:213], v[94:95], off offset:16
	global_load_dwordx4 v[214:217], v[6:7], off offset:64
	global_load_dwordx2 v[218:219], v[8:9], off offset:32
	global_load_dwordx2 v[220:221], v[94:95], off offset:32
	global_load_dwordx4 v[222:225], v[6:7], off offset:96
	global_load_dwordx2 v[226:227], v[8:9], off offset:48
	global_load_dwordx2 v[228:229], v[94:95], off offset:48
	v_readlane_b32 s49, v254, 12
	s_waitcnt vmcnt(11)
	v_lshlrev_b32_e32 v18, 16, v10
	v_and_b32_e32 v19, 0xffff0000, v10
	v_lshlrev_b32_e32 v10, 16, v11
	s_waitcnt vmcnt(10)
	v_lshlrev_b32_e32 v14, 16, v12
	v_mul_f32_e32 v5, 0xbfb8aa3b, v14
	v_exp_f32_e32 v5, v5
	v_and_b32_e32 v15, 0xffff0000, v12
	v_lshlrev_b32_e32 v12, 16, v13
	v_and_b32_e32 v13, 0xffff0000, v13
	v_add_f32_e32 v5, 1.0, v5
	v_rcp_f32_e32 v16, v5
	v_mul_f32_e32 v5, 0xbfb8aa3b, v15
	v_exp_f32_e32 v5, v5
	v_and_b32_e32 v11, 0xffff0000, v11
	v_add_f32_e32 v5, 1.0, v5
	v_rcp_f32_e32 v17, v5
	v_pk_mul_f32 v[18:19], v[4:5], v[18:19] op_sel_hi:[0,1]
	s_waitcnt vmcnt(9)
	v_pk_mul_f32 v[0:1], v[0:1], v[18:19]
	v_pk_mul_f32 v[10:11], v[4:5], v[10:11] op_sel_hi:[0,1]
	v_pk_mul_f32 v[14:15], v[16:17], v[14:15]
	v_pk_mul_f32 v[2:3], v[2:3], v[10:11]
	v_pk_mul_f32 v[0:1], v[0:1], v[14:15]
	s_nop 0
	v_cvt_pk_bf16_f32 v0, v0, v1
	v_mul_f32_e32 v1, 0xbfb8aa3b, v12
	v_exp_f32_e32 v1, v1
	s_nop 0
	v_add_f32_e32 v1, 1.0, v1
	v_rcp_f32_e32 v14, v1
	v_mul_f32_e32 v1, 0xbfb8aa3b, v13
	v_exp_f32_e32 v1, v1
	s_nop 0
	v_add_f32_e32 v1, 1.0, v1
	v_rcp_f32_e32 v15, v1
	s_nop 0
	v_pk_mul_f32 v[10:11], v[14:15], v[12:13]
	s_nop 0
	v_pk_mul_f32 v[2:3], v[2:3], v[10:11]
	s_nop 0
	v_cvt_pk_bf16_f32 v1, v2, v3
	global_store_dwordx2 v[48:49], v[0:1], off offset:1536
	s_nop 0
	s_waitcnt vmcnt(8)
	v_lshlrev_b32_e32 v14, 16, v210
	v_mul_f32_e32 v5, 0xbfb8aa3b, v14
	v_exp_f32_e32 v5, v5
	v_and_b32_e32 v15, 0xffff0000, v210
	s_waitcnt vmcnt(7)
	v_lshlrev_b32_e32 v18, 16, v212
	v_and_b32_e32 v19, 0xffff0000, v212
	v_add_f32_e32 v5, 1.0, v5
	v_rcp_f32_e32 v16, v5
	v_mul_f32_e32 v5, 0xbfb8aa3b, v15
	v_exp_f32_e32 v5, v5
	v_lshlrev_b32_e32 v10, 16, v211
	v_and_b32_e32 v11, 0xffff0000, v211
	v_lshlrev_b32_e32 v12, 16, v213
	v_add_f32_e32 v5, 1.0, v5
	v_rcp_f32_e32 v17, v5
	v_pk_mul_f32 v[18:19], v[4:5], v[18:19] op_sel_hi:[0,1]
	v_pk_mul_f32 v[0:1], v[206:207], v[18:19]
	v_and_b32_e32 v13, 0xffff0000, v213
	v_pk_mul_f32 v[14:15], v[16:17], v[14:15]
	v_pk_mul_f32 v[12:13], v[4:5], v[12:13] op_sel_hi:[0,1]
	v_pk_mul_f32 v[0:1], v[0:1], v[14:15]
	v_pk_mul_f32 v[2:3], v[208:209], v[12:13]
	v_cvt_pk_bf16_f32 v0, v0, v1
	v_mul_f32_e32 v1, 0xbfb8aa3b, v10
	v_exp_f32_e32 v1, v1
	s_nop 0
	v_add_f32_e32 v1, 1.0, v1
	v_rcp_f32_e32 v14, v1
	v_mul_f32_e32 v1, 0xbfb8aa3b, v11
	v_exp_f32_e32 v1, v1
	s_nop 0
	v_add_f32_e32 v1, 1.0, v1
	v_rcp_f32_e32 v15, v1
	s_nop 0
	v_pk_mul_f32 v[10:11], v[14:15], v[10:11]
	s_nop 0
	v_pk_mul_f32 v[2:3], v[2:3], v[10:11]
	s_nop 0
	v_cvt_pk_bf16_f32 v1, v2, v3
	global_store_dwordx2 v[94:95], v[0:1], off offset:16
	s_nop 0
	s_waitcnt vmcnt(6)
	v_lshlrev_b32_e32 v14, 16, v218
	v_mul_f32_e32 v5, 0xbfb8aa3b, v14
	v_exp_f32_e32 v5, v5
	v_and_b32_e32 v15, 0xffff0000, v218
	s_waitcnt vmcnt(5)
	v_lshlrev_b32_e32 v18, 16, v220
	v_and_b32_e32 v19, 0xffff0000, v220
	v_add_f32_e32 v5, 1.0, v5
	v_rcp_f32_e32 v16, v5
	v_mul_f32_e32 v5, 0xbfb8aa3b, v15
	v_exp_f32_e32 v5, v5
	v_lshlrev_b32_e32 v10, 16, v219
	v_and_b32_e32 v11, 0xffff0000, v219
	v_lshlrev_b32_e32 v12, 16, v221
	v_add_f32_e32 v5, 1.0, v5
	v_rcp_f32_e32 v17, v5
	v_pk_mul_f32 v[18:19], v[4:5], v[18:19] op_sel_hi:[0,1]
	v_pk_mul_f32 v[0:1], v[214:215], v[18:19]
	v_and_b32_e32 v13, 0xffff0000, v221
	v_pk_mul_f32 v[14:15], v[16:17], v[14:15]
	v_pk_mul_f32 v[12:13], v[4:5], v[12:13] op_sel_hi:[0,1]
	v_pk_mul_f32 v[0:1], v[0:1], v[14:15]
	v_pk_mul_f32 v[2:3], v[216:217], v[12:13]
	v_cvt_pk_bf16_f32 v0, v0, v1
	v_mul_f32_e32 v1, 0xbfb8aa3b, v10
	v_exp_f32_e32 v1, v1
	s_nop 0
	v_add_f32_e32 v1, 1.0, v1
	v_rcp_f32_e32 v14, v1
	v_mul_f32_e32 v1, 0xbfb8aa3b, v11
	v_exp_f32_e32 v1, v1
	s_nop 0
	v_add_f32_e32 v1, 1.0, v1
	v_rcp_f32_e32 v15, v1
	s_nop 0
	v_pk_mul_f32 v[10:11], v[14:15], v[10:11]
	s_nop 0
	v_pk_mul_f32 v[2:3], v[2:3], v[10:11]
	s_nop 0
	v_cvt_pk_bf16_f32 v1, v2, v3
	global_store_dwordx2 v[94:95], v[0:1], off offset:32
	s_nop 0
	s_waitcnt vmcnt(4)
	v_lshlrev_b32_e32 v14, 16, v226
	v_mul_f32_e32 v5, 0xbfb8aa3b, v14
	v_exp_f32_e32 v5, v5
	v_and_b32_e32 v15, 0xffff0000, v226
	s_waitcnt vmcnt(3)
	v_lshlrev_b32_e32 v18, 16, v228
	v_and_b32_e32 v19, 0xffff0000, v228
	v_add_f32_e32 v5, 1.0, v5
	v_rcp_f32_e32 v16, v5
	v_mul_f32_e32 v5, 0xbfb8aa3b, v15
	v_exp_f32_e32 v5, v5
	v_lshlrev_b32_e32 v10, 16, v227
	v_and_b32_e32 v11, 0xffff0000, v227
	v_lshlrev_b32_e32 v12, 16, v229
	v_add_f32_e32 v5, 1.0, v5
	v_rcp_f32_e32 v17, v5
	v_pk_mul_f32 v[18:19], v[4:5], v[18:19] op_sel_hi:[0,1]
	v_pk_mul_f32 v[0:1], v[222:223], v[18:19]
	v_and_b32_e32 v13, 0xffff0000, v229
	v_pk_mul_f32 v[14:15], v[16:17], v[14:15]
	v_pk_mul_f32 v[12:13], v[4:5], v[12:13] op_sel_hi:[0,1]
	v_pk_mul_f32 v[0:1], v[0:1], v[14:15]
	v_pk_mul_f32 v[2:3], v[224:225], v[12:13]
	v_cvt_pk_bf16_f32 v0, v0, v1
	v_mul_f32_e32 v1, 0xbfb8aa3b, v10
	v_exp_f32_e32 v1, v1
	s_nop 0
	v_add_f32_e32 v1, 1.0, v1
	v_rcp_f32_e32 v14, v1
	v_mul_f32_e32 v1, 0xbfb8aa3b, v11
	v_exp_f32_e32 v1, v1
	s_nop 0
	v_add_f32_e32 v1, 1.0, v1
	v_rcp_f32_e32 v15, v1
	s_nop 0
	v_pk_mul_f32 v[10:11], v[14:15], v[10:11]
	s_nop 0
	v_pk_mul_f32 v[2:3], v[2:3], v[10:11]
	s_nop 0
	v_cvt_pk_bf16_f32 v1, v2, v3
	global_store_dwordx2 v[94:95], v[0:1], off offset:48
	global_load_dwordx2 v[10:11], v[94:95], off offset:64
	global_load_dwordx2 v[12:13], v[8:9], off offset:64
	global_load_dwordx4 v[0:3], v[6:7], off offset:128
	global_load_dwordx2 v[212:213], v[94:95], off offset:80
	global_load_dwordx2 v[210:211], v[8:9], off offset:80
	global_load_dwordx4 v[206:209], v[6:7], off offset:160
	global_load_dwordx2 v[220:221], v[94:95], off offset:96
	global_load_dwordx2 v[218:219], v[8:9], off offset:96
	global_load_dwordx4 v[214:217], v[6:7], off offset:192
	global_load_dwordx2 v[228:229], v[94:95], off offset:112
	global_load_dwordx2 v[226:227], v[8:9], off offset:112
	global_load_dwordx4 v[222:225], v[6:7], off offset:224
	s_waitcnt vmcnt(11)
	v_lshlrev_b32_e32 v18, 16, v10
	s_waitcnt vmcnt(10)
	v_lshlrev_b32_e32 v14, 16, v12
	v_mul_f32_e32 v5, 0xbfb8aa3b, v14
	v_exp_f32_e32 v5, v5
	v_and_b32_e32 v15, 0xffff0000, v12
	v_and_b32_e32 v19, 0xffff0000, v10
	v_lshlrev_b32_e32 v12, 16, v13
	v_add_f32_e32 v5, 1.0, v5
	v_rcp_f32_e32 v16, v5
	v_mul_f32_e32 v5, 0xbfb8aa3b, v15
	v_exp_f32_e32 v5, v5
	v_and_b32_e32 v13, 0xffff0000, v13
	v_lshlrev_b32_e32 v10, 16, v11
	v_and_b32_e32 v11, 0xffff0000, v11
	v_add_f32_e32 v5, 1.0, v5
	v_rcp_f32_e32 v17, v5
	v_pk_mul_f32 v[18:19], v[4:5], v[18:19] op_sel_hi:[0,1]
	s_waitcnt vmcnt(9)
	v_pk_mul_f32 v[0:1], v[0:1], v[18:19]
	v_pk_mul_f32 v[10:11], v[4:5], v[10:11] op_sel_hi:[0,1]
	v_pk_mul_f32 v[14:15], v[16:17], v[14:15]
	v_pk_mul_f32 v[2:3], v[2:3], v[10:11]
	v_pk_mul_f32 v[0:1], v[0:1], v[14:15]
	s_nop 0
	v_cvt_pk_bf16_f32 v0, v0, v1
	v_mul_f32_e32 v1, 0xbfb8aa3b, v12
	v_exp_f32_e32 v1, v1
	s_nop 0
	v_add_f32_e32 v1, 1.0, v1
	v_rcp_f32_e32 v14, v1
	v_mul_f32_e32 v1, 0xbfb8aa3b, v13
	v_exp_f32_e32 v1, v1
	s_nop 0
	v_add_f32_e32 v1, 1.0, v1
	v_rcp_f32_e32 v15, v1
	s_nop 0
	v_pk_mul_f32 v[10:11], v[14:15], v[12:13]
	s_nop 0
	v_pk_mul_f32 v[2:3], v[2:3], v[10:11]
	s_nop 0
	v_cvt_pk_bf16_f32 v1, v2, v3
	global_store_dwordx2 v[94:95], v[0:1], off offset:64
	s_nop 0
	s_waitcnt vmcnt(9)
	v_lshlrev_b32_e32 v18, 16, v212
	s_waitcnt vmcnt(8)
	v_lshlrev_b32_e32 v14, 16, v210
	v_mul_f32_e32 v5, 0xbfb8aa3b, v14
	v_exp_f32_e32 v5, v5
	v_and_b32_e32 v15, 0xffff0000, v210
	v_and_b32_e32 v19, 0xffff0000, v212
	v_lshlrev_b32_e32 v12, 16, v211
	v_add_f32_e32 v5, 1.0, v5
	v_rcp_f32_e32 v16, v5
	v_mul_f32_e32 v5, 0xbfb8aa3b, v15
	v_exp_f32_e32 v5, v5
	v_and_b32_e32 v13, 0xffff0000, v211
	v_lshlrev_b32_e32 v10, 16, v213
	v_and_b32_e32 v11, 0xffff0000, v213
	v_add_f32_e32 v5, 1.0, v5
	v_rcp_f32_e32 v17, v5
	v_pk_mul_f32 v[18:19], v[4:5], v[18:19] op_sel_hi:[0,1]
	s_waitcnt vmcnt(7)
	v_pk_mul_f32 v[0:1], v[206:207], v[18:19]
	v_pk_mul_f32 v[10:11], v[4:5], v[10:11] op_sel_hi:[0,1]
	v_pk_mul_f32 v[14:15], v[16:17], v[14:15]
	v_pk_mul_f32 v[2:3], v[208:209], v[10:11]
	v_pk_mul_f32 v[0:1], v[0:1], v[14:15]
	s_nop 0
	v_cvt_pk_bf16_f32 v0, v0, v1
	v_mul_f32_e32 v1, 0xbfb8aa3b, v12
	v_exp_f32_e32 v1, v1
	s_nop 0
	v_add_f32_e32 v1, 1.0, v1
	v_rcp_f32_e32 v14, v1
	v_mul_f32_e32 v1, 0xbfb8aa3b, v13
	v_exp_f32_e32 v1, v1
	s_nop 0
	v_add_f32_e32 v1, 1.0, v1
	v_rcp_f32_e32 v15, v1
	s_nop 0
	v_pk_mul_f32 v[10:11], v[14:15], v[12:13]
	s_nop 0
	v_pk_mul_f32 v[2:3], v[2:3], v[10:11]
	s_nop 0
	v_cvt_pk_bf16_f32 v1, v2, v3
	global_store_dwordx2 v[94:95], v[0:1], off offset:80
	s_nop 0
	s_waitcnt vmcnt(7)
	v_lshlrev_b32_e32 v18, 16, v220
	s_waitcnt vmcnt(6)
	v_lshlrev_b32_e32 v14, 16, v218
	v_mul_f32_e32 v5, 0xbfb8aa3b, v14
	v_exp_f32_e32 v5, v5
	v_and_b32_e32 v15, 0xffff0000, v218
	v_and_b32_e32 v19, 0xffff0000, v220
	v_lshlrev_b32_e32 v12, 16, v219
	v_add_f32_e32 v5, 1.0, v5
	v_rcp_f32_e32 v16, v5
	v_mul_f32_e32 v5, 0xbfb8aa3b, v15
	v_exp_f32_e32 v5, v5
	v_and_b32_e32 v13, 0xffff0000, v219
	v_lshlrev_b32_e32 v10, 16, v221
	v_and_b32_e32 v11, 0xffff0000, v221
	v_add_f32_e32 v5, 1.0, v5
	v_rcp_f32_e32 v17, v5
	v_pk_mul_f32 v[18:19], v[4:5], v[18:19] op_sel_hi:[0,1]
	s_waitcnt vmcnt(5)
	v_pk_mul_f32 v[0:1], v[214:215], v[18:19]
	v_pk_mul_f32 v[10:11], v[4:5], v[10:11] op_sel_hi:[0,1]
	v_pk_mul_f32 v[14:15], v[16:17], v[14:15]
	v_pk_mul_f32 v[2:3], v[216:217], v[10:11]
	v_pk_mul_f32 v[0:1], v[0:1], v[14:15]
	s_nop 0
	v_cvt_pk_bf16_f32 v0, v0, v1
	v_mul_f32_e32 v1, 0xbfb8aa3b, v12
	v_exp_f32_e32 v1, v1
	s_nop 0
	v_add_f32_e32 v1, 1.0, v1
	v_rcp_f32_e32 v14, v1
	v_mul_f32_e32 v1, 0xbfb8aa3b, v13
	v_exp_f32_e32 v1, v1
	s_nop 0
	v_add_f32_e32 v1, 1.0, v1
	v_rcp_f32_e32 v15, v1
	s_nop 0
	v_pk_mul_f32 v[10:11], v[14:15], v[12:13]
	s_nop 0
	v_pk_mul_f32 v[2:3], v[2:3], v[10:11]
	s_nop 0
	v_cvt_pk_bf16_f32 v1, v2, v3
	global_store_dwordx2 v[94:95], v[0:1], off offset:96
	s_nop 0
	s_nop 0
	s_waitcnt vmcnt(5)
	v_lshlrev_b32_e32 v14, 16, v228
	s_waitcnt vmcnt(4)
	v_lshlrev_b32_e32 v10, 16, v226
	v_mul_f32_e32 v5, 0xbfb8aa3b, v10
	v_exp_f32_e32 v5, v5
	v_and_b32_e32 v11, 0xffff0000, v226
	v_lshlrev_b32_e32 v2, 16, v227
	v_and_b32_e32 v15, 0xffff0000, v228
	v_add_f32_e32 v5, 1.0, v5
	v_rcp_f32_e32 v12, v5
	v_mul_f32_e32 v5, 0xbfb8aa3b, v11
	v_exp_f32_e32 v5, v5
	v_and_b32_e32 v3, 0xffff0000, v227
	v_add_f32_e32 v5, 1.0, v5
	v_rcp_f32_e32 v13, v5
	v_pk_mul_f32 v[14:15], v[4:5], v[14:15] op_sel_hi:[0,1]
	v_mul_f32_e32 v5, 0xbfb8aa3b, v2
	v_exp_f32_e32 v5, v5
	s_waitcnt vmcnt(3)
	v_pk_mul_f32 v[6:7], v[222:223], v[14:15]
	v_pk_mul_f32 v[10:11], v[12:13], v[10:11]
	v_add_f32_e32 v5, 1.0, v5
	v_pk_mul_f32 v[6:7], v[6:7], v[10:11]
	v_lshlrev_b32_e32 v10, 16, v229
	v_cvt_pk_bf16_f32 v0, v6, v7
	v_rcp_f32_e32 v6, v5
	v_mul_f32_e32 v5, 0xbfb8aa3b, v3
	v_exp_f32_e32 v5, v5
	v_and_b32_e32 v11, 0xffff0000, v229
	v_add_f32_e32 v5, 1.0, v5
	v_rcp_f32_e32 v7, v5
	v_pk_mul_f32 v[4:5], v[4:5], v[10:11] op_sel_hi:[0,1]
	v_pk_mul_f32 v[4:5], v[224:225], v[4:5]
	v_pk_mul_f32 v[2:3], v[6:7], v[2:3]
	s_nop 0
	v_pk_mul_f32 v[2:3], v[4:5], v[2:3]
	s_nop 0
	v_cvt_pk_bf16_f32 v1, v2, v3
	global_store_dwordx2 v[94:95], v[0:1], off offset:112
	s_branch .LBB0_338
